# PROJ 96-WG GEMM epilogue: ssq loads hoisted and reductions batched; attention bias blocks made branch-free (v_fmac + v_cndmask on prefetched LDS values)
# speedup vs baseline: 1.0112x; 1.0027x over previous
; #define LAS __attribute__((address_space(3)))
; __device__ __forceinline__ void attn_unit(LAS unsigned char* lds, bf16_t* proj, const float* biasG, const float* sink, int s, int qb, int kh, int hp, bf16_t* dummy = nullptr) {
;     ...
;             const int st = kbi * 4 + si;
;             if (st < wq || st > wq + 8) continue;
;             f32x4 sa[2][2];
; #pragma unroll
;             for (int kt = 0; kt < 2; ++kt) { sa[kt][0] = (f32x4){0.f, 0.f, 0.f, 0.f}; sa[kt][1] = (f32x4){0.f, 0.f, 0.f, 0.f}; }
; #pragma unroll
;             for (int ks = 0; ks < 4; ++ks)
; #pragma unroll
;                 for (int kt = 0; kt < 2; ++kt) {
;                     const bf16x8 kf = *(const LAS bf16x8*)(Ks + (si * 32 + kt * 16 + l16) * 272 + ks * 64 + kg * 16);
;                     sa[kt][0] = __builtin_amdgcn_mfma_f32_16x16x32_bf16(kf, qf[0][ks], sa[kt][0], 0, 0, 0);
;                     sa[kt][1] = __builtin_amdgcn_mfma_f32_16x16x32_bf16(kf, qf[1][ks], sa[kt][1], 0, 0, 0);
;                 }
;             bf16x8 pf[2];
; #pragma unroll
;             for (int qt = 0; qt < 2; ++qt) {
;                 const int qp = wq * 32 + qt * 16 + l16;
;                 float sv[8]; float mx = -1e30f;
; #pragma unroll
;                 for (int kt = 0; kt < 2; ++kt)
; #pragma unroll
;                     for (int r = 0; r < 4; ++r) {
;                         const int kp = (kbi - 1) * 128 + si * 32 + kt * 16 + kg * 4 + r;
;                         const int rel = kp - qp; const bool valid = (rel >= -128) && (rel <= 128);
;                         const int idx = min(max(rel + 128, 0), 256);
;                         const float v = valid ? (sa[kt][qt][r] * SC + bL[hl * 260 + idx]) : -1e30f;
;                         sv[kt * 4 + r] = v; mx = fmaxf(mx, v);
;                     }
;                 mx = fmaxf(mx, __shfl_xor(mx, 16)); mx = fmaxf(mx, __shfl_xor(mx, 32));
.LBB0_134:
	s_add_i32 s16, s13, -3
	v_cmp_ge_u32_e32 vcc, s16, v192
	v_cmp_le_u32_e64 s[4:5], s16, v195
	s_and_b64 s[4:5], vcc, s[4:5]
	s_and_saveexec_b64 s[78:79], s[4:5]
	s_cbranch_execz .LBB0_168
	v_add_u32_e32 v251, 0x11700, v200
	v_add_u32_e32 v251, v251, v196
	v_add_u32_e32 v252, 0x11700, v201
	v_add_u32_e32 v252, v252, v196
	ds_read_b32 v235, v252 offset:256
	ds_read_b32 v236, v252 offset:260
	ds_read_b32 v237, v252 offset:264
	ds_read_b32 v238, v252 offset:268
	ds_read_b32 v239, v252 offset:320
	ds_read_b32 v240, v252 offset:324
	ds_read_b32 v241, v252 offset:328
	ds_read_b32 v242, v252 offset:332
	ds_read_b32 v243, v251 offset:192
	ds_read_b32 v244, v251 offset:196
	ds_read_b32 v245, v251 offset:200
	ds_read_b32 v246, v251 offset:204
	ds_read_b32 v247, v252 offset:256
	ds_read_b32 v248, v252 offset:260
	ds_read_b32 v249, v252 offset:264
	ds_read_b32 v250, v252 offset:268
	ds_read_b128 v[132:135], v213
	ds_read_b128 v[226:229], v213 offset:64
	ds_read_b128 v[140:143], v213 offset:4352
	v_add_u32_e32 v1, 0xffffff8d, v199
	v_cmp_gt_u32_e32 vcc, s53, v1
	v_add3_u32 v2, v201, v196, s84
	s_waitcnt lgkmcnt(0)
	v_mfma_f32_16x16x32_bf16 v[136:139], v[132:135], v[4:7], 0
	v_mfma_f32_16x16x32_bf16 v[132:135], v[132:135], v[20:23], 0
	v_mfma_f32_16x16x32_bf16 v[136:139], v[226:229], v[8:11], v[136:139]
	v_mfma_f32_16x16x32_bf16 v[132:135], v[226:229], v[24:27], v[132:135]
	ds_read_b128 v[226:229], v213 offset:4416
	v_mfma_f32_16x16x32_bf16 v[144:147], v[140:143], v[4:7], 0
	v_mfma_f32_16x16x32_bf16 v[140:143], v[140:143], v[20:23], 0
	s_waitcnt lgkmcnt(0)
	v_mfma_f32_16x16x32_bf16 v[144:147], v[226:229], v[8:11], v[144:147]
	v_mfma_f32_16x16x32_bf16 v[140:143], v[226:229], v[24:27], v[140:143]
	ds_read_b128 v[226:229], v213 offset:128
	s_waitcnt lgkmcnt(0)
	v_mfma_f32_16x16x32_bf16 v[136:139], v[226:229], v[12:15], v[136:139]
	v_mfma_f32_16x16x32_bf16 v[132:135], v[226:229], v[28:31], v[132:135]
	ds_read_b128 v[226:229], v213 offset:4480
	s_waitcnt lgkmcnt(0)
	v_mfma_f32_16x16x32_bf16 v[230:233], v[226:229], v[12:15], v[144:147]
	v_mfma_f32_16x16x32_bf16 v[226:229], v[226:229], v[28:31], v[140:143]
	s_nop 2
	ds_read_b128 v[140:143], v213 offset:192
	s_waitcnt lgkmcnt(0)
	v_mfma_f32_16x16x32_bf16 v[144:147], v[140:143], v[16:19], v[136:139]
	s_nop 2
	ds_read_b128 v[136:139], v213 offset:4544
	v_mfma_f32_16x16x32_bf16 v[140:143], v[140:143], v[32:35], v[132:135]
	s_waitcnt lgkmcnt(0)
	v_mfma_f32_16x16x32_bf16 v[132:135], v[136:139], v[16:19], v[230:233]
	v_mfma_f32_16x16x32_bf16 v[136:139], v[136:139], v[32:35], v[226:229]
	s_nop 2
	v_mov_b32_e32 v228, 0xf149f2ca
	v_mov_b32_e32 v229, 0xf149f2ca
	s_waitcnt lgkmcnt(0)
	v_fmac_f32_e32 v235, 0x3e0293ee, v144
	v_cndmask_b32_e32 v229, v229, v235, vcc
	v_add_u32_e32 v1, 0xffffff8e, v199
	v_cmp_gt_u32_e64 s[4:5], s53, v1
	v_add3_u32 v225, v201, v196, s85
	v_fmac_f32_e32 v236, 0x3e0293ee, v145
	v_cndmask_b32_e64 v228, v228, v236, s[4:5]
	v_add_u32_e32 v1, 0xffffff8f, v199
	v_cmp_gt_u32_e64 s[6:7], s53, v1
	v_mov_b32_e32 v145, 0xf149f2ca
	v_add3_u32 v226, v201, v196, s42
	v_mov_b32_e32 v230, 0xf149f2ca
	v_fmac_f32_e32 v237, 0x3e0293ee, v146
	v_cndmask_b32_e64 v230, v230, v237, s[6:7]
	v_add_u32_e32 v1, 0xffffff90, v199
	v_cmp_gt_u32_e64 s[8:9], s53, v1
	v_add3_u32 v227, v201, v196, s96
	v_fmac_f32_e32 v238, 0x3e0293ee, v147
	v_cndmask_b32_e64 v145, v145, v238, s[8:9]
	v_add_u32_e32 v1, 0xffffff9d, v199
	v_cmp_gt_u32_e64 s[10:11], s53, v1
	v_mov_b32_e32 v232, 0xf149f2ca
	v_mov_b32_e32 v231, 0xf149f2ca
	v_fmac_f32_e32 v239, 0x3e0293ee, v132
	v_cndmask_b32_e64 v231, v231, v239, s[10:11]
	v_add_u32_e32 v1, 0xffffff9e, v199
	v_cmp_gt_u32_e64 s[10:11], s53, v1
	v_fmac_f32_e32 v240, 0x3e0293ee, v133
	s_nop 0
	v_cndmask_b32_e64 v232, v232, v240, s[10:11]
	v_add_u32_e32 v1, 0xffffff9f, v199
	v_cmp_gt_u32_e64 s[10:11], s53, v1
	v_mov_b32_e32 v132, 0xf149f2ca
	v_mov_b32_e32 v133, 0xf149f2ca
	v_fmac_f32_e32 v241, 0x3e0293ee, v134
	v_cndmask_b32_e64 v133, v133, v241, s[10:11]
	v_add_u32_e32 v1, 0xffffffa0, v199
	v_cmp_gt_u32_e64 s[10:11], s53, v1
	v_fmac_f32_e32 v242, 0x3e0293ee, v135
	s_nop 0
	v_cndmask_b32_e64 v132, v132, v242, s[10:11]
	v_mov_b32_e32 v144, 0xf149f2ca
	v_and_b32_e32 v134, 64, v182
	v_max3_f32 v1, v229, v144, v228
	v_xor_b32_e32 v3, 16, v182
	v_add_u32_e32 v134, 64, v134
	v_max3_f32 v1, v1, v230, v145
	v_cmp_lt_i32_e64 s[10:11], v3, v134
	v_max3_f32 v1, v1, v231, v232
	v_max3_f32 v1, v1, v133, v132
	v_cndmask_b32_e64 v3, v182, v3, s[10:11]
	v_lshlrev_b32_e32 v146, 2, v3
	ds_bpermute_b32 v135, v146, v1
	v_xor_b32_e32 v3, 32, v182
	v_cmp_lt_i32_e64 s[10:11], v3, v134
	s_waitcnt lgkmcnt(0)
	v_max_f32_e32 v134, v135, v135
	v_cndmask_b32_e64 v3, v182, v3, s[10:11]
	v_lshlrev_b32_e32 v3, 2, v3
	v_max_f32_e32 v1, v1, v134
	ds_bpermute_b32 v134, v3, v1
	s_waitcnt lgkmcnt(0)
; #define LAS __attribute__((address_space(3)))
; __device__ __forceinline__ unsigned cvt_pk_bf16(float lo, float hi) { unsigned r; asm volatile("v_cvt_pk_bf16_f32 %0, %1, %2" : "=v"(r) : "v"(lo), "v"(hi)); return r; }
; __device__ __forceinline__ void attn_unit(LAS unsigned char* lds, bf16_t* proj, const float* biasG, const float* sink, int s, int qb, int kh, int hp, bf16_t* dummy = nullptr) {
;     ...
;             for (int qt = 0; qt < 2; ++qt) {
;                 const int qp = wq * 32 + qt * 16 + l16;
;                 float sv[8]; float mx = -1e30f;
; #pragma unroll
;                 for (int kt = 0; kt < 2; ++kt)
; #pragma unroll
;                     for (int r = 0; r < 4; ++r) {
;                         const int kp = (kbi - 1) * 128 + si * 32 + kt * 16 + kg * 4 + r;
;                         const int rel = kp - qp; const bool valid = (rel >= -128) && (rel <= 128);
;                         const int idx = min(max(rel + 128, 0), 256);
;                         const float v = valid ? (sa[kt][qt][r] * SC + bL[hl * 260 + idx]) : -1e30f;
;                         sv[kt * 4 + r] = v; mx = fmaxf(mx, v);
;                     }
;                 mx = fmaxf(mx, __shfl_xor(mx, 16)); mx = fmaxf(mx, __shfl_xor(mx, 32));
;                 const float mnew = fmaxf(m2[qt], mx), alpha = __builtin_amdgcn_exp2f(m2[qt] - mnew); m2[qt] = mnew;
;                 float ps = 0.f; float pv[8];
; #pragma unroll
;                 for (int i = 0; i < 8; ++i) { pv[i] = __builtin_amdgcn_exp2f(sv[i] - mnew); ps += pv[i]; }
;                 lsum[qt] = lsum[qt] * alpha + ps;
; #pragma unroll
;                 for (int dt = 0; dt < 8; ++dt) o[dt][qt] = o[dt][qt] * alpha;
;                 u32x4 pw; pw.x = cvt_pk_bf16(pv[0], pv[1]); pw.y = cvt_pk_bf16(pv[2], pv[3]); pw.z = cvt_pk_bf16(pv[4], pv[5]); pw.w = cvt_pk_bf16(pv[6], pv[7]);
;                 pf[qt] = __builtin_bit_cast(bf16x8, pw);
;             }
; #pragma unroll
;             for (int dt = 0; dt < 8; ++dt) {
;                 const LAS unsigned char* vr = Vt + (dt * 16 + l16) * 288 + (si * 32 + kg * 4) * 2;
;                 const u32x2 lo = *(const LAS u32x2*)(vr), hi = *(const LAS u32x2*)(vr + 32);
	v_max3_f32 v1, v224, v1, v134
	v_sub_f32_e32 v134, v229, v1
	v_exp_f32_e32 v147, v134
	v_sub_f32_e32 v134, v228, v1
	v_exp_f32_e32 v228, v134
	v_sub_f32_e32 v134, v230, v1
	v_exp_f32_e32 v229, v134
	v_sub_f32_e32 v134, v145, v1
	v_exp_f32_e32 v230, v134
	v_sub_f32_e32 v134, v231, v1
	v_exp_f32_e32 v231, v134
	v_sub_f32_e32 v134, v232, v1
	v_sub_f32_e32 v133, v133, v1
	v_sub_f32_e32 v132, v132, v1
	v_exp_f32_e32 v232, v134
	v_exp_f32_e32 v233, v133
	v_exp_f32_e32 v234, v132
	v_add_u32_e32 v145, 0xffffff7d, v199
	v_cmp_gt_u32_e64 s[10:11], s53, v145
	v_mov_b32_e32 v145, 0xf149f2ca
	v_cvt_pk_bf16_f32 v132, v147, v228
	v_cvt_pk_bf16_f32 v133, v229, v230
	v_cvt_pk_bf16_f32 v134, v231, v232
	v_cvt_pk_bf16_f32 v135, v233, v234
	v_fmac_f32_e32 v243, 0x3e0293ee, v140
	v_cndmask_b32_e64 v145, v145, v243, s[10:11]
	v_add_u32_e32 v140, 0xffffff7e, v199
	v_cmp_gt_u32_e64 s[10:11], s53, v140
	v_fmac_f32_e32 v244, 0x3e0293ee, v141
	s_nop 0
	v_cndmask_b32_e64 v144, v144, v244, s[10:11]
	v_add_u32_e32 v140, 0xffffff7f, v199
	v_cmp_gt_u32_e64 s[10:11], s53, v140
	v_mov_b32_e32 v140, 0xf149f2ca
	v_mov_b32_e32 v141, 0xf149f2ca
	v_fmac_f32_e32 v245, 0x3e0293ee, v142
	v_cndmask_b32_e64 v141, v141, v245, s[10:11]
	v_add_u32_e32 v142, 0xffffff80, v199
	v_cmp_gt_u32_e64 s[10:11], s53, v142
	v_fmac_f32_e32 v246, 0x3e0293ee, v143
	s_nop 0
	v_cndmask_b32_e64 v140, v140, v246, s[10:11]
	v_mov_b32_e32 v142, 0xf149f2ca
	v_mov_b32_e32 v143, 0xf149f2ca
	v_fmac_f32_e32 v247, 0x3e0293ee, v136
	v_cndmask_b32_e32 v143, v143, v247, vcc
	v_fmac_f32_e32 v248, 0x3e0293ee, v137
	v_cndmask_b32_e64 v142, v142, v248, s[4:5]
	v_mov_b32_e32 v136, 0xf149f2ca
	v_mov_b32_e32 v137, 0xf149f2ca
	v_fmac_f32_e32 v249, 0x3e0293ee, v138
	v_cndmask_b32_e64 v137, v137, v249, s[6:7]
	v_fmac_f32_e32 v250, 0x3e0293ee, v139
	v_cndmask_b32_e64 v136, v136, v250, s[8:9]
	v_max3_f32 v2, v145, s89, v144
	v_max3_f32 v2, v2, v141, v140
	v_max3_f32 v139, v2, v143, v142
	v_add_f32_e32 v2, 0, v147
	v_add_f32_e32 v2, v228, v2
	v_add_f32_e32 v2, v229, v2
	v_sub_f32_e32 v138, v224, v1
	v_add_f32_e32 v2, v230, v2
	v_add_f32_e32 v2, v231, v2
	v_exp_f32_e32 v138, v138
	v_add_f32_e32 v2, v232, v2
	v_add_f32_e32 v2, v233, v2
	v_add_f32_e32 v2, v234, v2
	v_fmac_f32_e32 v2, v223, v138
	v_pk_mul_f32 v[98:99], v[98:99], v[138:139] op_sel_hi:[1,0]
	v_pk_mul_f32 v[96:97], v[96:97], v[138:139] op_sel_hi:[1,0]
	v_pk_mul_f32 v[106:107], v[106:107], v[138:139] op_sel_hi:[1,0]
	v_pk_mul_f32 v[104:105], v[104:105], v[138:139] op_sel_hi:[1,0]
	v_pk_mul_f32 v[110:111], v[110:111], v[138:139] op_sel_hi:[1,0]
	v_pk_mul_f32 v[108:109], v[108:109], v[138:139] op_sel_hi:[1,0]
	v_pk_mul_f32 v[114:115], v[114:115], v[138:139] op_sel_hi:[1,0]
	v_pk_mul_f32 v[112:113], v[112:113], v[138:139] op_sel_hi:[1,0]
	v_pk_mul_f32 v[118:119], v[118:119], v[138:139] op_sel_hi:[1,0]
	v_pk_mul_f32 v[116:117], v[116:117], v[138:139] op_sel_hi:[1,0]
	v_pk_mul_f32 v[122:123], v[122:123], v[138:139] op_sel_hi:[1,0]
	v_pk_mul_f32 v[120:121], v[120:121], v[138:139] op_sel_hi:[1,0]
	v_pk_mul_f32 v[126:127], v[126:127], v[138:139] op_sel_hi:[1,0]
	v_pk_mul_f32 v[124:125], v[124:125], v[138:139] op_sel_hi:[1,0]
	v_pk_mul_f32 v[130:131], v[130:131], v[138:139] op_sel_hi:[1,0]
	v_pk_mul_f32 v[128:129], v[128:129], v[138:139] op_sel_hi:[1,0]
	v_max3_f32 v138, v139, v137, v136
	ds_bpermute_b32 v139, v146, v138
	v_mov_b32_e32 v223, v2
	v_mov_b32_e32 v224, v1
	s_waitcnt lgkmcnt(0)
	v_max_f32_e32 v139, v139, v139
	v_max_f32_e32 v138, v138, v139
	ds_bpermute_b32 v3, v3, v138
	s_waitcnt lgkmcnt(0)
	v_max3_f32 v3, v222, v138, v3
	v_sub_f32_e32 v139, v145, v3
	v_exp_f32_e32 v139, v139
	v_sub_f32_e32 v144, v144, v3
	v_exp_f32_e32 v144, v144
	v_sub_f32_e32 v141, v141, v3
	v_exp_f32_e32 v141, v141
	v_sub_f32_e32 v140, v140, v3
	v_exp_f32_e32 v146, v140
	v_add_f32_e32 v145, 0, v139
	v_sub_f32_e32 v143, v143, v3
	v_add_f32_e32 v145, v144, v145
	v_exp_f32_e32 v143, v143
	v_sub_f32_e32 v142, v142, v3
	v_add_f32_e32 v145, v141, v145
	v_exp_f32_e32 v142, v142
	v_sub_f32_e32 v137, v137, v3
	v_add_f32_e32 v140, v146, v145
	v_exp_f32_e32 v145, v137
	v_sub_f32_e32 v136, v136, v3
	v_sub_f32_e32 v138, v222, v3
	v_exp_f32_e32 v147, v136
	v_add_f32_e32 v140, v143, v140
	v_exp_f32_e32 v136, v138
	v_add_f32_e32 v140, v142, v140
	v_add_f32_e32 v137, v145, v140
	v_add_f32_e32 v140, v147, v137
	v_fmac_f32_e32 v140, v221, v136
	v_pk_mul_f32 v[70:71], v[70:71], v[136:137] op_sel_hi:[1,0]
	v_pk_mul_f32 v[68:69], v[68:69], v[136:137] op_sel_hi:[1,0]
	v_pk_mul_f32 v[74:75], v[74:75], v[136:137] op_sel_hi:[1,0]
	v_pk_mul_f32 v[72:73], v[72:73], v[136:137] op_sel_hi:[1,0]
	v_pk_mul_f32 v[78:79], v[78:79], v[136:137] op_sel_hi:[1,0]
	v_pk_mul_f32 v[76:77], v[76:77], v[136:137] op_sel_hi:[1,0]
	v_pk_mul_f32 v[82:83], v[82:83], v[136:137] op_sel_hi:[1,0]
	v_pk_mul_f32 v[80:81], v[80:81], v[136:137] op_sel_hi:[1,0]
	v_pk_mul_f32 v[86:87], v[86:87], v[136:137] op_sel_hi:[1,0]
	v_pk_mul_f32 v[84:85], v[84:85], v[136:137] op_sel_hi:[1,0]
	v_pk_mul_f32 v[90:91], v[90:91], v[136:137] op_sel_hi:[1,0]
	v_pk_mul_f32 v[88:89], v[88:89], v[136:137] op_sel_hi:[1,0]
	v_pk_mul_f32 v[94:95], v[94:95], v[136:137] op_sel_hi:[1,0]
	v_pk_mul_f32 v[92:93], v[92:93], v[136:137] op_sel_hi:[1,0]
	v_pk_mul_f32 v[102:103], v[102:103], v[136:137] op_sel_hi:[1,0]
	v_pk_mul_f32 v[100:101], v[100:101], v[136:137] op_sel_hi:[1,0]
	v_cvt_pk_bf16_f32 v136, v139, v144
	v_cvt_pk_bf16_f32 v137, v141, v146
	v_add_u32_e32 v141, v197, v198
	v_cvt_pk_bf16_f32 v138, v143, v142
	v_add_u32_e32 v142, 0x8800, v141
	v_cvt_pk_bf16_f32 v139, v145, v147
	ds_read2_b64 v[236:239], v142 offset1:4
	v_mov_b32_e32 v221, v140
	v_add_u32_e32 v252, 0x9800, v141
	ds_read2_b64 v[240:243], v252 offset0:64 offset1:68
	v_add_u32_e32 v252, 0xa800, v141
	ds_read2_b64 v[244:247], v252 offset0:128 offset1:132
	v_add_u32_e32 v252, 0xb800, v141
	ds_read2_b64 v[248:251], v252 offset0:192 offset1:196
	s_waitcnt lgkmcnt(3)
; #define LAS __attribute__((address_space(3)))
; __device__ __forceinline__ void attn_unit(LAS unsigned char* lds, bf16_t* proj, const float* biasG, const float* sink, int s, int qb, int kh, int hp, bf16_t* dummy = nullptr) {
;     ...
;         for (int si = 0; si < 4; ++si) {
;             const int st = kbi * 4 + si;
;             if (st < wq || st > wq + 8) continue;
;             f32x4 sa[2][2];
; #pragma unroll
;             for (int kt = 0; kt < 2; ++kt) { sa[kt][0] = (f32x4){0.f, 0.f, 0.f, 0.f}; sa[kt][1] = (f32x4){0.f, 0.f, 0.f, 0.f}; }
; #pragma unroll
;             for (int ks = 0; ks < 4; ++ks)
; #pragma unroll
;                 for (int kt = 0; kt < 2; ++kt) {
;                     const bf16x8 kf = *(const LAS bf16x8*)(Ks + (si * 32 + kt * 16 + l16) * 272 + ks * 64 + kg * 16);
;                     sa[kt][0] = __builtin_amdgcn_mfma_f32_16x16x32_bf16(kf, qf[0][ks], sa[kt][0], 0, 0, 0);
;                     sa[kt][1] = __builtin_amdgcn_mfma_f32_16x16x32_bf16(kf, qf[1][ks], sa[kt][1], 0, 0, 0);
;                 }
;             bf16x8 pf[2];
; #pragma unroll
;             for (int qt = 0; qt < 2; ++qt) {
;                 const int qp = wq * 32 + qt * 16 + l16;
;                 float sv[8]; float mx = -1e30f;
; #pragma unroll
;                 for (int kt = 0; kt < 2; ++kt)
; #pragma unroll
;                     for (int r = 0; r < 4; ++r) {
;                         const int kp = (kbi - 1) * 128 + si * 32 + kt * 16 + kg * 4 + r;
;                         const int rel = kp - qp; const bool valid = (rel >= -128) && (rel <= 128);
;                         const int idx = min(max(rel + 128, 0), 256);
;                         const float v = valid ? (sa[kt][qt][r] * SC + bL[hl * 260 + idx]) : -1e30f;
;                         sv[kt * 4 + r] = v; mx = fmaxf(mx, v);
;                     }
;                 mx = fmaxf(mx, __shfl_xor(mx, 16)); mx = fmaxf(mx, __shfl_xor(mx, 32));
;                 const float mnew = fmaxf(m2[qt], mx), alpha = __builtin_amdgcn_exp2f(m2[qt] - mnew); m2[qt] = mnew;
;                 float ps = 0.f; float pv[8];
; #pragma unroll
;                 for (int i = 0; i < 8; ++i) { pv[i] = __builtin_amdgcn_exp2f(sv[i] - mnew); ps += pv[i]; }
;                 lsum[qt] = lsum[qt] * alpha + ps;
; #pragma unroll
;                 for (int dt = 0; dt < 8; ++dt) o[dt][qt] = o[dt][qt] * alpha;
	v_mfma_f32_16x16x32_bf16 v[96:99], v[236:239], v[132:135], v[96:99]
	v_mov_b32_e32 v222, v3
	v_mfma_f32_16x16x32_bf16 v[68:71], v[236:239], v[136:139], v[68:71]
	v_add_u32_e32 v252, 0xd000, v141
	ds_read2_b64 v[236:239], v252 offset1:4
	s_waitcnt lgkmcnt(3)
	v_mfma_f32_16x16x32_bf16 v[104:107], v[240:243], v[132:135], v[104:107]
	v_mfma_f32_16x16x32_bf16 v[72:75], v[240:243], v[136:139], v[72:75]
	v_add_u32_e32 v252, 0xe000, v141
	ds_read2_b64 v[240:243], v252 offset0:64 offset1:68
	v_add_u32_e32 v141, 0xf000, v141
	s_waitcnt lgkmcnt(3)
	v_mfma_f32_16x16x32_bf16 v[108:111], v[244:247], v[132:135], v[108:111]
	v_mfma_f32_16x16x32_bf16 v[76:79], v[244:247], v[136:139], v[76:79]
	ds_read2_b64 v[244:247], v141 offset0:128 offset1:132
	s_waitcnt lgkmcnt(3)
	v_mfma_f32_16x16x32_bf16 v[112:115], v[248:251], v[132:135], v[112:115]
	v_mfma_f32_16x16x32_bf16 v[80:83], v[248:251], v[136:139], v[80:83]
	ds_read2_b64 v[248:251], v214 offset0:192 offset1:196
	s_waitcnt lgkmcnt(3)
	v_mfma_f32_16x16x32_bf16 v[116:119], v[236:239], v[132:135], v[116:119]
	v_mfma_f32_16x16x32_bf16 v[84:87], v[236:239], v[136:139], v[84:87]
	s_waitcnt lgkmcnt(2)
	v_mfma_f32_16x16x32_bf16 v[120:123], v[240:243], v[132:135], v[120:123]
	v_mfma_f32_16x16x32_bf16 v[88:91], v[240:243], v[136:139], v[88:91]
	s_waitcnt lgkmcnt(1)
	v_mfma_f32_16x16x32_bf16 v[124:127], v[244:247], v[132:135], v[124:127]
	v_mfma_f32_16x16x32_bf16 v[92:95], v[244:247], v[136:139], v[92:95]
	s_waitcnt lgkmcnt(0)
	v_mfma_f32_16x16x32_bf16 v[128:131], v[248:251], v[132:135], v[128:131]
	v_mfma_f32_16x16x32_bf16 v[100:103], v[248:251], v[136:139], v[100:103]
.LBB0_168:
	s_or_b64 exec, exec, s[78:79]
	s_add_i32 s4, s13, -2
	v_cmp_ge_u32_e32 vcc, s4, v192
	v_cmp_lt_u32_e64 s[4:5], s16, v195
	s_and_b64 s[4:5], vcc, s[4:5]
	s_and_saveexec_b64 s[78:79], s[4:5]
	s_cbranch_execz .LBB0_202
	v_add_u32_e32 v251, 0x11700, v201
	v_add_u32_e32 v251, v251, v196
	ds_read_b32 v235, v251 offset:384
	ds_read_b32 v236, v251 offset:388
	ds_read_b32 v237, v251 offset:392
	ds_read_b32 v238, v251 offset:396
	ds_read_b32 v239, v251 offset:448
	ds_read_b32 v240, v251 offset:452
	ds_read_b32 v241, v251 offset:456
	ds_read_b32 v242, v251 offset:460
	ds_read_b32 v243, v251 offset:320
	ds_read_b32 v244, v251 offset:324
	ds_read_b32 v245, v251 offset:328
	ds_read_b32 v246, v251 offset:332
	ds_read_b32 v247, v251 offset:384
	ds_read_b32 v248, v251 offset:388
	ds_read_b32 v249, v251 offset:392
	ds_read_b32 v250, v251 offset:396
	ds_read_b128 v[132:135], v210
	ds_read_b128 v[226:229], v210 offset:64
	ds_read_b128 v[140:143], v213 offset:13056
	v_add_u32_e32 v1, 0xffffffad, v199
	v_cmp_gt_u32_e32 vcc, s53, v1
	v_add3_u32 v2, v201, v196, s88
	s_waitcnt lgkmcnt(0)
	v_mfma_f32_16x16x32_bf16 v[136:139], v[132:135], v[4:7], 0
	v_mfma_f32_16x16x32_bf16 v[132:135], v[132:135], v[20:23], 0
	v_mfma_f32_16x16x32_bf16 v[136:139], v[226:229], v[8:11], v[136:139]
	v_mfma_f32_16x16x32_bf16 v[132:135], v[226:229], v[24:27], v[132:135]
	ds_read_b128 v[226:229], v213 offset:13120
	v_mfma_f32_16x16x32_bf16 v[144:147], v[140:143], v[4:7], 0
	v_mfma_f32_16x16x32_bf16 v[140:143], v[140:143], v[20:23], 0
	s_waitcnt lgkmcnt(0)
	v_mfma_f32_16x16x32_bf16 v[144:147], v[226:229], v[8:11], v[144:147]
	v_mfma_f32_16x16x32_bf16 v[140:143], v[226:229], v[24:27], v[140:143]
	ds_read_b128 v[226:229], v210 offset:128
	s_waitcnt lgkmcnt(0)
	v_mfma_f32_16x16x32_bf16 v[136:139], v[226:229], v[12:15], v[136:139]
	v_mfma_f32_16x16x32_bf16 v[132:135], v[226:229], v[28:31], v[132:135]
	ds_read_b128 v[226:229], v213 offset:13184
	s_waitcnt lgkmcnt(0)
	v_mfma_f32_16x16x32_bf16 v[230:233], v[226:229], v[12:15], v[144:147]
	v_mfma_f32_16x16x32_bf16 v[226:229], v[226:229], v[28:31], v[140:143]
	s_nop 2
	ds_read_b128 v[140:143], v210 offset:192
	s_waitcnt lgkmcnt(0)
	v_mfma_f32_16x16x32_bf16 v[144:147], v[140:143], v[16:19], v[136:139]
	s_nop 2
	ds_read_b128 v[136:139], v213 offset:13248
	v_mfma_f32_16x16x32_bf16 v[140:143], v[140:143], v[32:35], v[132:135]
	s_waitcnt lgkmcnt(0)
	v_mfma_f32_16x16x32_bf16 v[132:135], v[136:139], v[16:19], v[230:233]
	v_mfma_f32_16x16x32_bf16 v[136:139], v[136:139], v[32:35], v[226:229]
	s_nop 2
	v_mov_b32_e32 v228, 0xf149f2ca
	v_mov_b32_e32 v229, 0xf149f2ca
	s_waitcnt lgkmcnt(0)
	v_fmac_f32_e32 v235, 0x3e0293ee, v144
	v_cndmask_b32_e32 v229, v229, v235, vcc
	v_add_u32_e32 v1, 0xffffffae, v199
	v_cmp_gt_u32_e64 s[4:5], s53, v1
	v_add3_u32 v225, v201, v196, s55
	v_fmac_f32_e32 v236, 0x3e0293ee, v145
	v_cndmask_b32_e64 v228, v228, v236, s[4:5]
	v_add_u32_e32 v1, 0xffffffaf, v199
	v_cmp_gt_u32_e64 s[6:7], s53, v1
	v_mov_b32_e32 v145, 0xf149f2ca
	v_add3_u32 v226, v201, v196, s59
	v_mov_b32_e32 v230, 0xf149f2ca
	v_fmac_f32_e32 v237, 0x3e0293ee, v146
	v_cndmask_b32_e64 v230, v230, v237, s[6:7]
	v_add_u32_e32 v1, 0xffffffb0, v199
	v_cmp_gt_u32_e64 s[8:9], s53, v1
	v_add3_u32 v227, v201, v196, s43
	v_fmac_f32_e32 v238, 0x3e0293ee, v147
	v_cndmask_b32_e64 v145, v145, v238, s[8:9]
	v_add_u32_e32 v1, 0xffffffbd, v199
	v_cmp_gt_u32_e64 s[10:11], s53, v1
	v_mov_b32_e32 v232, 0xf149f2ca
	v_mov_b32_e32 v231, 0xf149f2ca
	v_fmac_f32_e32 v239, 0x3e0293ee, v132
	v_cndmask_b32_e64 v231, v231, v239, s[10:11]
	v_add_u32_e32 v1, 0xffffffbe, v199
	v_cmp_gt_u32_e64 s[10:11], s53, v1
	v_fmac_f32_e32 v240, 0x3e0293ee, v133
	s_nop 0
	v_cndmask_b32_e64 v232, v232, v240, s[10:11]
	v_add_u32_e32 v1, 0xffffffbf, v199
	v_cmp_gt_u32_e64 s[10:11], s53, v1
	v_mov_b32_e32 v132, 0xf149f2ca
	v_mov_b32_e32 v133, 0xf149f2ca
	v_fmac_f32_e32 v241, 0x3e0293ee, v134
	v_cndmask_b32_e64 v133, v133, v241, s[10:11]
	v_subrev_u32_e32 v1, 64, v199
	v_cmp_gt_u32_e64 s[10:11], s53, v1
	v_fmac_f32_e32 v242, 0x3e0293ee, v135
	s_nop 0
	v_cndmask_b32_e64 v132, v132, v242, s[10:11]
	v_mov_b32_e32 v144, 0xf149f2ca
	v_and_b32_e32 v134, 64, v182
	v_max3_f32 v1, v229, v144, v228
	v_xor_b32_e32 v3, 16, v182
	v_add_u32_e32 v134, 64, v134
	v_max3_f32 v1, v1, v230, v145
	v_cmp_lt_i32_e64 s[10:11], v3, v134
	v_max3_f32 v1, v1, v231, v232
	v_max3_f32 v1, v1, v133, v132
	v_cndmask_b32_e64 v3, v182, v3, s[10:11]
	v_lshlrev_b32_e32 v146, 2, v3
	ds_bpermute_b32 v135, v146, v1
	v_xor_b32_e32 v3, 32, v182
	v_cmp_lt_i32_e64 s[10:11], v3, v134
	s_waitcnt lgkmcnt(0)
; #define LAS __attribute__((address_space(3)))
; __device__ __forceinline__ unsigned cvt_pk_bf16(float lo, float hi) { unsigned r; asm volatile("v_cvt_pk_bf16_f32 %0, %1, %2" : "=v"(r) : "v"(lo), "v"(hi)); return r; }
; __device__ __forceinline__ void attn_unit(LAS unsigned char* lds, bf16_t* proj, const float* biasG, const float* sink, int s, int qb, int kh, int hp, bf16_t* dummy = nullptr) {
;     ...
;             for (int qt = 0; qt < 2; ++qt) {
;                 const int qp = wq * 32 + qt * 16 + l16;
;                 float sv[8]; float mx = -1e30f;
; #pragma unroll
;                 for (int kt = 0; kt < 2; ++kt)
; #pragma unroll
;                     for (int r = 0; r < 4; ++r) {
;                         const int kp = (kbi - 1) * 128 + si * 32 + kt * 16 + kg * 4 + r;
;                         const int rel = kp - qp; const bool valid = (rel >= -128) && (rel <= 128);
;                         const int idx = min(max(rel + 128, 0), 256);
;                         const float v = valid ? (sa[kt][qt][r] * SC + bL[hl * 260 + idx]) : -1e30f;
;                         sv[kt * 4 + r] = v; mx = fmaxf(mx, v);
;                     }
;                 mx = fmaxf(mx, __shfl_xor(mx, 16)); mx = fmaxf(mx, __shfl_xor(mx, 32));
;                 const float mnew = fmaxf(m2[qt], mx), alpha = __builtin_amdgcn_exp2f(m2[qt] - mnew); m2[qt] = mnew;
;                 float ps = 0.f; float pv[8];
; #pragma unroll
;                 for (int i = 0; i < 8; ++i) { pv[i] = __builtin_amdgcn_exp2f(sv[i] - mnew); ps += pv[i]; }
;                 lsum[qt] = lsum[qt] * alpha + ps;
; #pragma unroll
;                 for (int dt = 0; dt < 8; ++dt) o[dt][qt] = o[dt][qt] * alpha;
;                 u32x4 pw; pw.x = cvt_pk_bf16(pv[0], pv[1]); pw.y = cvt_pk_bf16(pv[2], pv[3]); pw.z = cvt_pk_bf16(pv[4], pv[5]); pw.w = cvt_pk_bf16(pv[6], pv[7]);
;                 pf[qt] = __builtin_bit_cast(bf16x8, pw);
;             }
; #pragma unroll
;             for (int dt = 0; dt < 8; ++dt) {
;                 const LAS unsigned char* vr = Vt + (dt * 16 + l16) * 288 + (si * 32 + kg * 4) * 2;
;                 const u32x2 lo = *(const LAS u32x2*)(vr), hi = *(const LAS u32x2*)(vr + 32);
	v_max_f32_e32 v134, v135, v135
	v_cndmask_b32_e64 v3, v182, v3, s[10:11]
	v_lshlrev_b32_e32 v3, 2, v3
	v_max_f32_e32 v1, v1, v134
	ds_bpermute_b32 v134, v3, v1
	s_waitcnt lgkmcnt(0)
	v_max3_f32 v1, v224, v1, v134
	v_sub_f32_e32 v134, v229, v1
	v_exp_f32_e32 v147, v134
	v_sub_f32_e32 v134, v228, v1
	v_exp_f32_e32 v228, v134
	v_sub_f32_e32 v134, v230, v1
	v_exp_f32_e32 v229, v134
	v_sub_f32_e32 v134, v145, v1
	v_exp_f32_e32 v230, v134
	v_sub_f32_e32 v134, v231, v1
	v_exp_f32_e32 v231, v134
	v_sub_f32_e32 v134, v232, v1
	v_sub_f32_e32 v133, v133, v1
	v_sub_f32_e32 v132, v132, v1
	v_exp_f32_e32 v232, v134
	v_exp_f32_e32 v233, v133
	v_exp_f32_e32 v234, v132
	v_add_u32_e32 v145, 0xffffff9d, v199
	v_cmp_gt_u32_e64 s[10:11], s53, v145
	v_mov_b32_e32 v145, 0xf149f2ca
	v_cvt_pk_bf16_f32 v132, v147, v228
	v_cvt_pk_bf16_f32 v133, v229, v230
	v_cvt_pk_bf16_f32 v134, v231, v232
	v_cvt_pk_bf16_f32 v135, v233, v234
	v_fmac_f32_e32 v243, 0x3e0293ee, v140
	v_cndmask_b32_e64 v145, v145, v243, s[10:11]
	v_add_u32_e32 v140, 0xffffff9e, v199
	v_cmp_gt_u32_e64 s[10:11], s53, v140
	v_fmac_f32_e32 v244, 0x3e0293ee, v141
	s_nop 0
	v_cndmask_b32_e64 v144, v144, v244, s[10:11]
	v_add_u32_e32 v140, 0xffffff9f, v199
	v_cmp_gt_u32_e64 s[10:11], s53, v140
	v_mov_b32_e32 v140, 0xf149f2ca
	v_mov_b32_e32 v141, 0xf149f2ca
	v_fmac_f32_e32 v245, 0x3e0293ee, v142
	v_cndmask_b32_e64 v141, v141, v245, s[10:11]
	v_add_u32_e32 v142, 0xffffffa0, v199
	v_cmp_gt_u32_e64 s[10:11], s53, v142
	v_fmac_f32_e32 v246, 0x3e0293ee, v143
	s_nop 0
	v_cndmask_b32_e64 v140, v140, v246, s[10:11]
	v_mov_b32_e32 v142, 0xf149f2ca
	v_mov_b32_e32 v143, 0xf149f2ca
	v_fmac_f32_e32 v247, 0x3e0293ee, v136
	v_cndmask_b32_e32 v143, v143, v247, vcc
	v_fmac_f32_e32 v248, 0x3e0293ee, v137
	v_cndmask_b32_e64 v142, v142, v248, s[4:5]
	v_mov_b32_e32 v136, 0xf149f2ca
	v_mov_b32_e32 v137, 0xf149f2ca
	v_fmac_f32_e32 v249, 0x3e0293ee, v138
	v_cndmask_b32_e64 v137, v137, v249, s[6:7]
	v_fmac_f32_e32 v250, 0x3e0293ee, v139
	v_cndmask_b32_e64 v136, v136, v250, s[8:9]
	v_max3_f32 v2, v145, s89, v144
	v_max3_f32 v2, v2, v141, v140
	v_max3_f32 v139, v2, v143, v142
	v_add_f32_e32 v2, 0, v147
	v_add_f32_e32 v2, v228, v2
	v_add_f32_e32 v2, v229, v2
	v_sub_f32_e32 v138, v224, v1
	v_add_f32_e32 v2, v230, v2
	v_add_f32_e32 v2, v231, v2
	v_exp_f32_e32 v138, v138
	v_add_f32_e32 v2, v232, v2
	v_add_f32_e32 v2, v233, v2
	v_add_f32_e32 v2, v234, v2
	v_fmac_f32_e32 v2, v223, v138
	v_pk_mul_f32 v[98:99], v[98:99], v[138:139] op_sel_hi:[1,0]
	v_pk_mul_f32 v[96:97], v[96:97], v[138:139] op_sel_hi:[1,0]
	v_pk_mul_f32 v[106:107], v[106:107], v[138:139] op_sel_hi:[1,0]
	v_pk_mul_f32 v[104:105], v[104:105], v[138:139] op_sel_hi:[1,0]
	v_pk_mul_f32 v[110:111], v[110:111], v[138:139] op_sel_hi:[1,0]
	v_pk_mul_f32 v[108:109], v[108:109], v[138:139] op_sel_hi:[1,0]
	v_pk_mul_f32 v[114:115], v[114:115], v[138:139] op_sel_hi:[1,0]
	v_pk_mul_f32 v[112:113], v[112:113], v[138:139] op_sel_hi:[1,0]
	v_pk_mul_f32 v[118:119], v[118:119], v[138:139] op_sel_hi:[1,0]
	v_pk_mul_f32 v[116:117], v[116:117], v[138:139] op_sel_hi:[1,0]
	v_pk_mul_f32 v[122:123], v[122:123], v[138:139] op_sel_hi:[1,0]
	v_pk_mul_f32 v[120:121], v[120:121], v[138:139] op_sel_hi:[1,0]
	v_pk_mul_f32 v[126:127], v[126:127], v[138:139] op_sel_hi:[1,0]
	v_pk_mul_f32 v[124:125], v[124:125], v[138:139] op_sel_hi:[1,0]
	v_pk_mul_f32 v[130:131], v[130:131], v[138:139] op_sel_hi:[1,0]
	v_pk_mul_f32 v[128:129], v[128:129], v[138:139] op_sel_hi:[1,0]
	v_max3_f32 v138, v139, v137, v136
	ds_bpermute_b32 v139, v146, v138
	v_mov_b32_e32 v223, v2
	v_mov_b32_e32 v224, v1
	s_waitcnt lgkmcnt(0)
	v_max_f32_e32 v139, v139, v139
	v_max_f32_e32 v138, v138, v139
	ds_bpermute_b32 v3, v3, v138
	s_waitcnt lgkmcnt(0)
	v_max3_f32 v3, v222, v138, v3
	v_sub_f32_e32 v139, v145, v3
	v_exp_f32_e32 v139, v139
	v_sub_f32_e32 v144, v144, v3
	v_exp_f32_e32 v144, v144
	v_sub_f32_e32 v141, v141, v3
	v_exp_f32_e32 v141, v141
	v_sub_f32_e32 v140, v140, v3
	v_exp_f32_e32 v146, v140
	v_add_f32_e32 v145, 0, v139
	v_sub_f32_e32 v143, v143, v3
	v_add_f32_e32 v145, v144, v145
	v_exp_f32_e32 v143, v143
	v_sub_f32_e32 v142, v142, v3
	v_add_f32_e32 v145, v141, v145
	v_exp_f32_e32 v142, v142
	v_sub_f32_e32 v137, v137, v3
	v_add_f32_e32 v140, v146, v145
	v_exp_f32_e32 v145, v137
	v_sub_f32_e32 v136, v136, v3
	v_sub_f32_e32 v138, v222, v3
	v_exp_f32_e32 v147, v136
	v_add_f32_e32 v140, v143, v140
	v_exp_f32_e32 v136, v138
	v_add_f32_e32 v140, v142, v140
	v_add_f32_e32 v137, v145, v140
	v_add_f32_e32 v140, v147, v137
	v_fmac_f32_e32 v140, v221, v136
	v_pk_mul_f32 v[70:71], v[70:71], v[136:137] op_sel_hi:[1,0]
	v_pk_mul_f32 v[68:69], v[68:69], v[136:137] op_sel_hi:[1,0]
	v_pk_mul_f32 v[74:75], v[74:75], v[136:137] op_sel_hi:[1,0]
	v_pk_mul_f32 v[72:73], v[72:73], v[136:137] op_sel_hi:[1,0]
	v_pk_mul_f32 v[78:79], v[78:79], v[136:137] op_sel_hi:[1,0]
	v_pk_mul_f32 v[76:77], v[76:77], v[136:137] op_sel_hi:[1,0]
	v_pk_mul_f32 v[82:83], v[82:83], v[136:137] op_sel_hi:[1,0]
	v_pk_mul_f32 v[80:81], v[80:81], v[136:137] op_sel_hi:[1,0]
	v_pk_mul_f32 v[86:87], v[86:87], v[136:137] op_sel_hi:[1,0]
	v_pk_mul_f32 v[84:85], v[84:85], v[136:137] op_sel_hi:[1,0]
	v_pk_mul_f32 v[90:91], v[90:91], v[136:137] op_sel_hi:[1,0]
	v_pk_mul_f32 v[88:89], v[88:89], v[136:137] op_sel_hi:[1,0]
	v_pk_mul_f32 v[94:95], v[94:95], v[136:137] op_sel_hi:[1,0]
	v_pk_mul_f32 v[92:93], v[92:93], v[136:137] op_sel_hi:[1,0]
	v_pk_mul_f32 v[102:103], v[102:103], v[136:137] op_sel_hi:[1,0]
	v_pk_mul_f32 v[100:101], v[100:101], v[136:137] op_sel_hi:[1,0]
	v_cvt_pk_bf16_f32 v136, v139, v144
	v_cvt_pk_bf16_f32 v137, v141, v146
	v_add_u32_e32 v141, v197, v198
	v_cvt_pk_bf16_f32 v138, v143, v142
	v_add_u32_e32 v142, 0x8800, v141
	v_cvt_pk_bf16_f32 v139, v145, v147
	ds_read2_b64 v[236:239], v142 offset0:8 offset1:12
	v_mov_b32_e32 v221, v140
	v_add_u32_e32 v252, 0x9800, v141
	ds_read2_b64 v[240:243], v252 offset0:72 offset1:76
	ds_read2_b64 v[244:247], v215 offset0:8 offset1:12
	v_add_u32_e32 v252, 0xb800, v141
	ds_read2_b64 v[248:251], v252 offset0:200 offset1:204
	s_waitcnt lgkmcnt(3)
; #define LAS __attribute__((address_space(3)))
; __device__ __forceinline__ void attn_unit(LAS unsigned char* lds, bf16_t* proj, const float* biasG, const float* sink, int s, int qb, int kh, int hp, bf16_t* dummy = nullptr) {
;     ...
;         for (int si = 0; si < 4; ++si) {
;             const int st = kbi * 4 + si;
;             if (st < wq || st > wq + 8) continue;
;             f32x4 sa[2][2];
; #pragma unroll
;             for (int kt = 0; kt < 2; ++kt) { sa[kt][0] = (f32x4){0.f, 0.f, 0.f, 0.f}; sa[kt][1] = (f32x4){0.f, 0.f, 0.f, 0.f}; }
; #pragma unroll
;             for (int ks = 0; ks < 4; ++ks)
; #pragma unroll
;                 for (int kt = 0; kt < 2; ++kt) {
;                     const bf16x8 kf = *(const LAS bf16x8*)(Ks + (si * 32 + kt * 16 + l16) * 272 + ks * 64 + kg * 16);
;                     sa[kt][0] = __builtin_amdgcn_mfma_f32_16x16x32_bf16(kf, qf[0][ks], sa[kt][0], 0, 0, 0);
;                     sa[kt][1] = __builtin_amdgcn_mfma_f32_16x16x32_bf16(kf, qf[1][ks], sa[kt][1], 0, 0, 0);
;                 }
;             bf16x8 pf[2];
; #pragma unroll
;             for (int qt = 0; qt < 2; ++qt) {
;                 const int qp = wq * 32 + qt * 16 + l16;
;                 float sv[8]; float mx = -1e30f;
; #pragma unroll
;                 for (int kt = 0; kt < 2; ++kt)
; #pragma unroll
;                     for (int r = 0; r < 4; ++r) {
;                         const int kp = (kbi - 1) * 128 + si * 32 + kt * 16 + kg * 4 + r;
;                         const int rel = kp - qp; const bool valid = (rel >= -128) && (rel <= 128);
;                         const int idx = min(max(rel + 128, 0), 256);
;                         const float v = valid ? (sa[kt][qt][r] * SC + bL[hl * 260 + idx]) : -1e30f;
;                         sv[kt * 4 + r] = v; mx = fmaxf(mx, v);
;                     }
;                 mx = fmaxf(mx, __shfl_xor(mx, 16)); mx = fmaxf(mx, __shfl_xor(mx, 32));
;                 const float mnew = fmaxf(m2[qt], mx), alpha = __builtin_amdgcn_exp2f(m2[qt] - mnew); m2[qt] = mnew;
;                 float ps = 0.f; float pv[8];
; #pragma unroll
;                 for (int i = 0; i < 8; ++i) { pv[i] = __builtin_amdgcn_exp2f(sv[i] - mnew); ps += pv[i]; }
;                 lsum[qt] = lsum[qt] * alpha + ps;
; #pragma unroll
;                 for (int dt = 0; dt < 8; ++dt) o[dt][qt] = o[dt][qt] * alpha;
	v_mfma_f32_16x16x32_bf16 v[96:99], v[236:239], v[132:135], v[96:99]
	v_mov_b32_e32 v222, v3
	v_mfma_f32_16x16x32_bf16 v[68:71], v[236:239], v[136:139], v[68:71]
	v_add_u32_e32 v252, 0xd000, v141
	ds_read2_b64 v[236:239], v252 offset0:8 offset1:12
	s_waitcnt lgkmcnt(3)
	v_mfma_f32_16x16x32_bf16 v[104:107], v[240:243], v[132:135], v[104:107]
	v_mfma_f32_16x16x32_bf16 v[72:75], v[240:243], v[136:139], v[72:75]
	v_add_u32_e32 v252, 0xe000, v141
	ds_read2_b64 v[240:243], v252 offset0:72 offset1:76
	v_add_u32_e32 v141, 0xf000, v141
	s_waitcnt lgkmcnt(3)
	v_mfma_f32_16x16x32_bf16 v[108:111], v[244:247], v[132:135], v[108:111]
	v_mfma_f32_16x16x32_bf16 v[76:79], v[244:247], v[136:139], v[76:79]
	ds_read2_b64 v[244:247], v141 offset0:136 offset1:140
	s_waitcnt lgkmcnt(3)
	v_mfma_f32_16x16x32_bf16 v[112:115], v[248:251], v[132:135], v[112:115]
	v_mfma_f32_16x16x32_bf16 v[80:83], v[248:251], v[136:139], v[80:83]
	ds_read2_b64 v[248:251], v216 offset0:192 offset1:196
	s_waitcnt lgkmcnt(3)
	v_mfma_f32_16x16x32_bf16 v[116:119], v[236:239], v[132:135], v[116:119]
	v_mfma_f32_16x16x32_bf16 v[84:87], v[236:239], v[136:139], v[84:87]
	s_waitcnt lgkmcnt(2)
	v_mfma_f32_16x16x32_bf16 v[120:123], v[240:243], v[132:135], v[120:123]
	v_mfma_f32_16x16x32_bf16 v[88:91], v[240:243], v[136:139], v[88:91]
	s_waitcnt lgkmcnt(1)
	v_mfma_f32_16x16x32_bf16 v[124:127], v[244:247], v[132:135], v[124:127]
	v_mfma_f32_16x16x32_bf16 v[92:95], v[244:247], v[136:139], v[92:95]
	s_waitcnt lgkmcnt(0)
	v_mfma_f32_16x16x32_bf16 v[128:131], v[248:251], v[132:135], v[128:131]
	v_mfma_f32_16x16x32_bf16 v[100:103], v[248:251], v[136:139], v[100:103]
.LBB0_202:
	s_or_b64 exec, exec, s[78:79]
	s_add_i32 s4, s13, -1
	v_cmp_ge_u32_e32 vcc, s4, v192
	v_cmp_le_u32_e64 s[4:5], s4, v195
	s_and_b64 s[4:5], vcc, s[4:5]
	s_and_saveexec_b64 s[78:79], s[4:5]
	s_cbranch_execz .LBB0_236
	v_add_u32_e32 v251, 0x11700, v201
	v_add_u32_e32 v251, v251, v196
	ds_read_b32 v235, v251 offset:512
	ds_read_b32 v236, v251 offset:516
	ds_read_b32 v237, v251 offset:520
	ds_read_b32 v238, v251 offset:524
	ds_read_b32 v239, v251 offset:576
	ds_read_b32 v240, v251 offset:580
	ds_read_b32 v241, v251 offset:584
	ds_read_b32 v242, v251 offset:588
	ds_read_b32 v243, v251 offset:448
	ds_read_b32 v244, v251 offset:452
	ds_read_b32 v245, v251 offset:456
	ds_read_b32 v246, v251 offset:460
	ds_read_b32 v247, v251 offset:512
	ds_read_b32 v248, v251 offset:516
	ds_read_b32 v249, v251 offset:520
	ds_read_b32 v250, v251 offset:524
	ds_read_b128 v[132:135], v211
	ds_read_b128 v[226:229], v211 offset:64
	ds_read_b128 v[140:143], v213 offset:21760
	v_subrev_u32_e32 v1, 51, v199
	v_cmp_gt_u32_e32 vcc, s53, v1
	v_add3_u32 v2, v201, v196, s14
	s_waitcnt lgkmcnt(0)
	v_mfma_f32_16x16x32_bf16 v[136:139], v[132:135], v[4:7], 0
	v_mfma_f32_16x16x32_bf16 v[132:135], v[132:135], v[20:23], 0
	v_mfma_f32_16x16x32_bf16 v[136:139], v[226:229], v[8:11], v[136:139]
	v_mfma_f32_16x16x32_bf16 v[132:135], v[226:229], v[24:27], v[132:135]
	ds_read_b128 v[226:229], v213 offset:21824
	v_mfma_f32_16x16x32_bf16 v[144:147], v[140:143], v[4:7], 0
	v_mfma_f32_16x16x32_bf16 v[140:143], v[140:143], v[20:23], 0
	s_waitcnt lgkmcnt(0)
	v_mfma_f32_16x16x32_bf16 v[144:147], v[226:229], v[8:11], v[144:147]
	v_mfma_f32_16x16x32_bf16 v[140:143], v[226:229], v[24:27], v[140:143]
	ds_read_b128 v[226:229], v211 offset:128
	s_waitcnt lgkmcnt(0)
	v_mfma_f32_16x16x32_bf16 v[136:139], v[226:229], v[12:15], v[136:139]
	v_mfma_f32_16x16x32_bf16 v[132:135], v[226:229], v[28:31], v[132:135]
	ds_read_b128 v[226:229], v213 offset:21888
	s_waitcnt lgkmcnt(0)
	v_mfma_f32_16x16x32_bf16 v[230:233], v[226:229], v[12:15], v[144:147]
	v_mfma_f32_16x16x32_bf16 v[226:229], v[226:229], v[28:31], v[140:143]
	s_nop 2
	ds_read_b128 v[140:143], v211 offset:192
	s_waitcnt lgkmcnt(0)
	v_mfma_f32_16x16x32_bf16 v[144:147], v[140:143], v[16:19], v[136:139]
	s_nop 2
	ds_read_b128 v[136:139], v213 offset:21952
	v_mfma_f32_16x16x32_bf16 v[140:143], v[140:143], v[32:35], v[132:135]
	s_waitcnt lgkmcnt(0)
	v_mfma_f32_16x16x32_bf16 v[132:135], v[136:139], v[16:19], v[230:233]
	v_mfma_f32_16x16x32_bf16 v[136:139], v[136:139], v[32:35], v[226:229]
	s_nop 2
	v_mov_b32_e32 v228, 0xf149f2ca
	v_mov_b32_e32 v229, 0xf149f2ca
	s_waitcnt lgkmcnt(0)
	v_fmac_f32_e32 v235, 0x3e0293ee, v144
	v_cndmask_b32_e32 v229, v229, v235, vcc
	v_subrev_u32_e32 v1, 50, v199
	v_cmp_gt_u32_e64 s[4:5], s53, v1
	v_add3_u32 v225, v201, v196, s54
	v_fmac_f32_e32 v236, 0x3e0293ee, v145
	v_cndmask_b32_e64 v228, v228, v236, s[4:5]
	v_subrev_u32_e32 v1, 49, v199
	v_cmp_gt_u32_e64 s[6:7], s53, v1
	v_mov_b32_e32 v145, 0xf149f2ca
	v_add3_u32 v226, v201, v196, s58
	v_mov_b32_e32 v230, 0xf149f2ca
	v_fmac_f32_e32 v237, 0x3e0293ee, v146
	v_cndmask_b32_e64 v230, v230, v237, s[6:7]
	v_subrev_u32_e32 v1, 48, v199
	v_cmp_gt_u32_e64 s[8:9], s53, v1
	v_add3_u32 v227, v201, v196, s97
	v_fmac_f32_e32 v238, 0x3e0293ee, v147
	v_cndmask_b32_e64 v145, v145, v238, s[8:9]
	v_subrev_u32_e32 v1, 35, v199
	v_cmp_gt_u32_e64 s[10:11], s53, v1
	v_mov_b32_e32 v232, 0xf149f2ca
	v_mov_b32_e32 v231, 0xf149f2ca
	v_fmac_f32_e32 v239, 0x3e0293ee, v132
	v_cndmask_b32_e64 v231, v231, v239, s[10:11]
	v_subrev_u32_e32 v1, 34, v199
	v_cmp_gt_u32_e64 s[10:11], s53, v1
	v_fmac_f32_e32 v240, 0x3e0293ee, v133
	s_nop 0
	v_cndmask_b32_e64 v232, v232, v240, s[10:11]
	v_subrev_u32_e32 v1, 33, v199
	v_cmp_gt_u32_e64 s[10:11], s53, v1
	v_mov_b32_e32 v132, 0xf149f2ca
	v_mov_b32_e32 v133, 0xf149f2ca
	v_fmac_f32_e32 v241, 0x3e0293ee, v134
	v_cndmask_b32_e64 v133, v133, v241, s[10:11]
	v_subrev_u32_e32 v1, 32, v199
	v_cmp_gt_u32_e64 s[10:11], s53, v1
	v_fmac_f32_e32 v242, 0x3e0293ee, v135
	s_nop 0
	v_cndmask_b32_e64 v132, v132, v242, s[10:11]
	v_mov_b32_e32 v144, 0xf149f2ca
	v_and_b32_e32 v134, 64, v182
	v_max3_f32 v1, v229, v144, v228
	v_xor_b32_e32 v3, 16, v182
	v_add_u32_e32 v134, 64, v134
	v_max3_f32 v1, v1, v230, v145
	v_cmp_lt_i32_e64 s[10:11], v3, v134
	v_max3_f32 v1, v1, v231, v232
	v_max3_f32 v1, v1, v133, v132
	v_cndmask_b32_e64 v3, v182, v3, s[10:11]
	v_lshlrev_b32_e32 v146, 2, v3
	ds_bpermute_b32 v135, v146, v1
	v_xor_b32_e32 v3, 32, v182
	v_cmp_lt_i32_e64 s[10:11], v3, v134
	s_waitcnt lgkmcnt(0)
; #define LAS __attribute__((address_space(3)))
; __device__ __forceinline__ unsigned cvt_pk_bf16(float lo, float hi) { unsigned r; asm volatile("v_cvt_pk_bf16_f32 %0, %1, %2" : "=v"(r) : "v"(lo), "v"(hi)); return r; }
; __device__ __forceinline__ void attn_unit(LAS unsigned char* lds, bf16_t* proj, const float* biasG, const float* sink, int s, int qb, int kh, int hp, bf16_t* dummy = nullptr) {
;     ...
;             for (int qt = 0; qt < 2; ++qt) {
;                 const int qp = wq * 32 + qt * 16 + l16;
;                 float sv[8]; float mx = -1e30f;
; #pragma unroll
;                 for (int kt = 0; kt < 2; ++kt)
; #pragma unroll
;                     for (int r = 0; r < 4; ++r) {
;                         const int kp = (kbi - 1) * 128 + si * 32 + kt * 16 + kg * 4 + r;
;                         const int rel = kp - qp; const bool valid = (rel >= -128) && (rel <= 128);
;                         const int idx = min(max(rel + 128, 0), 256);
;                         const float v = valid ? (sa[kt][qt][r] * SC + bL[hl * 260 + idx]) : -1e30f;
;                         sv[kt * 4 + r] = v; mx = fmaxf(mx, v);
;                     }
;                 mx = fmaxf(mx, __shfl_xor(mx, 16)); mx = fmaxf(mx, __shfl_xor(mx, 32));
;                 const float mnew = fmaxf(m2[qt], mx), alpha = __builtin_amdgcn_exp2f(m2[qt] - mnew); m2[qt] = mnew;
;                 float ps = 0.f; float pv[8];
; #pragma unroll
;                 for (int i = 0; i < 8; ++i) { pv[i] = __builtin_amdgcn_exp2f(sv[i] - mnew); ps += pv[i]; }
;                 lsum[qt] = lsum[qt] * alpha + ps;
; #pragma unroll
;                 for (int dt = 0; dt < 8; ++dt) o[dt][qt] = o[dt][qt] * alpha;
;                 u32x4 pw; pw.x = cvt_pk_bf16(pv[0], pv[1]); pw.y = cvt_pk_bf16(pv[2], pv[3]); pw.z = cvt_pk_bf16(pv[4], pv[5]); pw.w = cvt_pk_bf16(pv[6], pv[7]);
;                 pf[qt] = __builtin_bit_cast(bf16x8, pw);
;             }
; #pragma unroll
;             for (int dt = 0; dt < 8; ++dt) {
;                 const LAS unsigned char* vr = Vt + (dt * 16 + l16) * 288 + (si * 32 + kg * 4) * 2;
;                 const u32x2 lo = *(const LAS u32x2*)(vr), hi = *(const LAS u32x2*)(vr + 32);
	v_max_f32_e32 v134, v135, v135
	v_cndmask_b32_e64 v3, v182, v3, s[10:11]
	v_lshlrev_b32_e32 v3, 2, v3
	v_max_f32_e32 v1, v1, v134
	ds_bpermute_b32 v134, v3, v1
	s_waitcnt lgkmcnt(0)
	v_max3_f32 v1, v224, v1, v134
	v_sub_f32_e32 v134, v229, v1
	v_exp_f32_e32 v147, v134
	v_sub_f32_e32 v134, v228, v1
	v_exp_f32_e32 v228, v134
	v_sub_f32_e32 v134, v230, v1
	v_exp_f32_e32 v229, v134
	v_sub_f32_e32 v134, v145, v1
	v_exp_f32_e32 v230, v134
	v_sub_f32_e32 v134, v231, v1
	v_exp_f32_e32 v231, v134
	v_sub_f32_e32 v134, v232, v1
	v_sub_f32_e32 v133, v133, v1
	v_sub_f32_e32 v132, v132, v1
	v_exp_f32_e32 v232, v134
	v_exp_f32_e32 v233, v133
	v_exp_f32_e32 v234, v132
	v_add_u32_e32 v145, 0xffffffbd, v199
	v_cmp_gt_u32_e64 s[10:11], s53, v145
	v_mov_b32_e32 v145, 0xf149f2ca
	v_cvt_pk_bf16_f32 v132, v147, v228
	v_cvt_pk_bf16_f32 v133, v229, v230
	v_cvt_pk_bf16_f32 v134, v231, v232
	v_cvt_pk_bf16_f32 v135, v233, v234
	v_fmac_f32_e32 v243, 0x3e0293ee, v140
	v_cndmask_b32_e64 v145, v145, v243, s[10:11]
	v_add_u32_e32 v140, 0xffffffbe, v199
	v_cmp_gt_u32_e64 s[10:11], s53, v140
	v_fmac_f32_e32 v244, 0x3e0293ee, v141
	s_nop 0
	v_cndmask_b32_e64 v144, v144, v244, s[10:11]
	v_add_u32_e32 v140, 0xffffffbf, v199
	v_cmp_gt_u32_e64 s[10:11], s53, v140
	v_mov_b32_e32 v140, 0xf149f2ca
	v_mov_b32_e32 v141, 0xf149f2ca
	v_fmac_f32_e32 v245, 0x3e0293ee, v142
	v_cndmask_b32_e64 v141, v141, v245, s[10:11]
	v_subrev_u32_e32 v142, 64, v199
	v_cmp_gt_u32_e64 s[10:11], s53, v142
	v_fmac_f32_e32 v246, 0x3e0293ee, v143
	s_nop 0
	v_cndmask_b32_e64 v140, v140, v246, s[10:11]
	v_mov_b32_e32 v142, 0xf149f2ca
	v_mov_b32_e32 v143, 0xf149f2ca
	v_fmac_f32_e32 v247, 0x3e0293ee, v136
	v_cndmask_b32_e32 v143, v143, v247, vcc
	v_fmac_f32_e32 v248, 0x3e0293ee, v137
	v_cndmask_b32_e64 v142, v142, v248, s[4:5]
	v_mov_b32_e32 v136, 0xf149f2ca
	v_mov_b32_e32 v137, 0xf149f2ca
	v_fmac_f32_e32 v249, 0x3e0293ee, v138
	v_cndmask_b32_e64 v137, v137, v249, s[6:7]
	v_fmac_f32_e32 v250, 0x3e0293ee, v139
	v_cndmask_b32_e64 v136, v136, v250, s[8:9]
	v_max3_f32 v2, v145, s89, v144
	v_max3_f32 v2, v2, v141, v140
	v_max3_f32 v139, v2, v143, v142
	v_add_f32_e32 v2, 0, v147
	v_add_f32_e32 v2, v228, v2
	v_add_f32_e32 v2, v229, v2
	v_sub_f32_e32 v138, v224, v1
	v_add_f32_e32 v2, v230, v2
	v_add_f32_e32 v2, v231, v2
	v_exp_f32_e32 v138, v138
	v_add_f32_e32 v2, v232, v2
	v_add_f32_e32 v2, v233, v2
	v_add_f32_e32 v2, v234, v2
	v_fmac_f32_e32 v2, v223, v138
	v_pk_mul_f32 v[98:99], v[98:99], v[138:139] op_sel_hi:[1,0]
	v_pk_mul_f32 v[96:97], v[96:97], v[138:139] op_sel_hi:[1,0]
	v_pk_mul_f32 v[106:107], v[106:107], v[138:139] op_sel_hi:[1,0]
	v_pk_mul_f32 v[104:105], v[104:105], v[138:139] op_sel_hi:[1,0]
	v_pk_mul_f32 v[110:111], v[110:111], v[138:139] op_sel_hi:[1,0]
	v_pk_mul_f32 v[108:109], v[108:109], v[138:139] op_sel_hi:[1,0]
	v_pk_mul_f32 v[114:115], v[114:115], v[138:139] op_sel_hi:[1,0]
	v_pk_mul_f32 v[112:113], v[112:113], v[138:139] op_sel_hi:[1,0]
	v_pk_mul_f32 v[118:119], v[118:119], v[138:139] op_sel_hi:[1,0]
	v_pk_mul_f32 v[116:117], v[116:117], v[138:139] op_sel_hi:[1,0]
	v_pk_mul_f32 v[122:123], v[122:123], v[138:139] op_sel_hi:[1,0]
	v_pk_mul_f32 v[120:121], v[120:121], v[138:139] op_sel_hi:[1,0]
	v_pk_mul_f32 v[126:127], v[126:127], v[138:139] op_sel_hi:[1,0]
	v_pk_mul_f32 v[124:125], v[124:125], v[138:139] op_sel_hi:[1,0]
	v_pk_mul_f32 v[130:131], v[130:131], v[138:139] op_sel_hi:[1,0]
	v_pk_mul_f32 v[128:129], v[128:129], v[138:139] op_sel_hi:[1,0]
	v_max3_f32 v138, v139, v137, v136
	ds_bpermute_b32 v139, v146, v138
	v_mov_b32_e32 v223, v2
	v_mov_b32_e32 v224, v1
	s_waitcnt lgkmcnt(0)
	v_max_f32_e32 v139, v139, v139
	v_max_f32_e32 v138, v138, v139
	ds_bpermute_b32 v3, v3, v138
	s_waitcnt lgkmcnt(0)
	v_max3_f32 v3, v222, v138, v3
	v_sub_f32_e32 v139, v145, v3
	v_exp_f32_e32 v139, v139
	v_sub_f32_e32 v144, v144, v3
	v_exp_f32_e32 v144, v144
	v_sub_f32_e32 v141, v141, v3
	v_exp_f32_e32 v141, v141
	v_sub_f32_e32 v140, v140, v3
	v_exp_f32_e32 v146, v140
	v_add_f32_e32 v145, 0, v139
	v_sub_f32_e32 v143, v143, v3
	v_add_f32_e32 v145, v144, v145
	v_exp_f32_e32 v143, v143
	v_sub_f32_e32 v142, v142, v3
	v_add_f32_e32 v145, v141, v145
	v_exp_f32_e32 v142, v142
	v_sub_f32_e32 v137, v137, v3
	v_add_f32_e32 v140, v146, v145
	v_exp_f32_e32 v145, v137
	v_sub_f32_e32 v136, v136, v3
	v_sub_f32_e32 v138, v222, v3
	v_exp_f32_e32 v147, v136
	v_add_f32_e32 v140, v143, v140
	v_exp_f32_e32 v136, v138
	v_add_f32_e32 v140, v142, v140
	v_add_f32_e32 v137, v145, v140
	v_add_f32_e32 v140, v147, v137
	v_fmac_f32_e32 v140, v221, v136
	v_pk_mul_f32 v[70:71], v[70:71], v[136:137] op_sel_hi:[1,0]
	v_pk_mul_f32 v[68:69], v[68:69], v[136:137] op_sel_hi:[1,0]
	v_pk_mul_f32 v[74:75], v[74:75], v[136:137] op_sel_hi:[1,0]
	v_pk_mul_f32 v[72:73], v[72:73], v[136:137] op_sel_hi:[1,0]
	v_pk_mul_f32 v[78:79], v[78:79], v[136:137] op_sel_hi:[1,0]
	v_pk_mul_f32 v[76:77], v[76:77], v[136:137] op_sel_hi:[1,0]
	v_pk_mul_f32 v[82:83], v[82:83], v[136:137] op_sel_hi:[1,0]
	v_pk_mul_f32 v[80:81], v[80:81], v[136:137] op_sel_hi:[1,0]
	v_pk_mul_f32 v[86:87], v[86:87], v[136:137] op_sel_hi:[1,0]
	v_pk_mul_f32 v[84:85], v[84:85], v[136:137] op_sel_hi:[1,0]
	v_pk_mul_f32 v[90:91], v[90:91], v[136:137] op_sel_hi:[1,0]
	v_pk_mul_f32 v[88:89], v[88:89], v[136:137] op_sel_hi:[1,0]
	v_pk_mul_f32 v[94:95], v[94:95], v[136:137] op_sel_hi:[1,0]
	v_pk_mul_f32 v[92:93], v[92:93], v[136:137] op_sel_hi:[1,0]
	v_pk_mul_f32 v[102:103], v[102:103], v[136:137] op_sel_hi:[1,0]
	v_pk_mul_f32 v[100:101], v[100:101], v[136:137] op_sel_hi:[1,0]
	v_cvt_pk_bf16_f32 v136, v139, v144
	v_cvt_pk_bf16_f32 v137, v141, v146
	v_add_u32_e32 v141, v197, v198
	v_cvt_pk_bf16_f32 v138, v143, v142
	v_add_u32_e32 v142, 0x8800, v141
	v_cvt_pk_bf16_f32 v139, v145, v147
	ds_read2_b64 v[236:239], v142 offset0:16 offset1:20
	v_mov_b32_e32 v221, v140
	v_add_u32_e32 v252, 0x9800, v141
	ds_read2_b64 v[240:243], v252 offset0:80 offset1:84
	v_add_u32_e32 v252, 0xa800, v141
	ds_read2_b64 v[244:247], v252 offset0:144 offset1:148
	v_add_u32_e32 v252, 0xb800, v141
	ds_read2_b64 v[248:251], v252 offset0:208 offset1:212
	s_waitcnt lgkmcnt(3)
; #define LAS __attribute__((address_space(3)))
; __device__ __forceinline__ void attn_unit(LAS unsigned char* lds, bf16_t* proj, const float* biasG, const float* sink, int s, int qb, int kh, int hp, bf16_t* dummy = nullptr) {
;     ...
;             for (int dt = 0; dt < 8; ++dt) {
;                 const LAS unsigned char* vr = Vt + (dt * 16 + l16) * 288 + (si * 32 + kg * 4) * 2;
;                 const u32x2 lo = *(const LAS u32x2*)(vr), hi = *(const LAS u32x2*)(vr + 32);
;                 u32x4 vw; vw.x = lo.x; vw.y = lo.y; vw.z = hi.x; vw.w = hi.y;
;                 const bf16x8 vf = __builtin_bit_cast(bf16x8, vw);
;                 o[dt][0] = __builtin_amdgcn_mfma_f32_16x16x32_bf16(vf, pf[0], o[dt][0], 0, 0, 0);
;                 o[dt][1] = __builtin_amdgcn_mfma_f32_16x16x32_bf16(vf, pf[1], o[dt][1], 0, 0, 0);
;             }
	v_mfma_f32_16x16x32_bf16 v[96:99], v[236:239], v[132:135], v[96:99]
	v_mov_b32_e32 v222, v3
	v_mfma_f32_16x16x32_bf16 v[68:71], v[236:239], v[136:139], v[68:71]
	ds_read2_b64 v[236:239], v217 offset0:16 offset1:20
	s_waitcnt lgkmcnt(3)
	v_mfma_f32_16x16x32_bf16 v[104:107], v[240:243], v[132:135], v[104:107]
	v_mfma_f32_16x16x32_bf16 v[72:75], v[240:243], v[136:139], v[72:75]
	v_add_u32_e32 v252, 0xe000, v141
	ds_read2_b64 v[240:243], v252 offset0:80 offset1:84
	v_add_u32_e32 v141, 0xf000, v141
	s_waitcnt lgkmcnt(3)
	v_mfma_f32_16x16x32_bf16 v[108:111], v[244:247], v[132:135], v[108:111]
	v_mfma_f32_16x16x32_bf16 v[76:79], v[244:247], v[136:139], v[76:79]
	ds_read2_b64 v[244:247], v141 offset0:144 offset1:148
	s_waitcnt lgkmcnt(3)
	v_mfma_f32_16x16x32_bf16 v[112:115], v[248:251], v[132:135], v[112:115]
	v_mfma_f32_16x16x32_bf16 v[80:83], v[248:251], v[136:139], v[80:83]
	ds_read2_b64 v[248:251], v218 offset0:192 offset1:196
	s_waitcnt lgkmcnt(3)
	v_mfma_f32_16x16x32_bf16 v[116:119], v[236:239], v[132:135], v[116:119]
	v_mfma_f32_16x16x32_bf16 v[84:87], v[236:239], v[136:139], v[84:87]
	s_waitcnt lgkmcnt(2)
	v_mfma_f32_16x16x32_bf16 v[120:123], v[240:243], v[132:135], v[120:123]
	v_mfma_f32_16x16x32_bf16 v[88:91], v[240:243], v[136:139], v[88:91]
	s_waitcnt lgkmcnt(1)
	v_mfma_f32_16x16x32_bf16 v[124:127], v[244:247], v[132:135], v[124:127]
	v_mfma_f32_16x16x32_bf16 v[92:95], v[244:247], v[136:139], v[92:95]
	s_waitcnt lgkmcnt(0)
	v_mfma_f32_16x16x32_bf16 v[128:131], v[248:251], v[132:135], v[128:131]
	v_mfma_f32_16x16x32_bf16 v[100:103], v[248:251], v[136:139], v[100:103]
; #define LAS __attribute__((address_space(3)))
; __device__ __forceinline__ void attn_unit(LAS unsigned char* lds, bf16_t* proj, const float* biasG, const float* sink, int s, int qb, int kh, int hp, bf16_t* dummy = nullptr) {
;     ...
;             const int st = kbi * 4 + si;
;             if (st < wq || st > wq + 8) continue;
;             f32x4 sa[2][2];
; #pragma unroll
;             for (int kt = 0; kt < 2; ++kt) { sa[kt][0] = (f32x4){0.f, 0.f, 0.f, 0.f}; sa[kt][1] = (f32x4){0.f, 0.f, 0.f, 0.f}; }
; #pragma unroll
;             for (int ks = 0; ks < 4; ++ks)
; #pragma unroll
;                 for (int kt = 0; kt < 2; ++kt) {
;                     const bf16x8 kf = *(const LAS bf16x8*)(Ks + (si * 32 + kt * 16 + l16) * 272 + ks * 64 + kg * 16);
;                     sa[kt][0] = __builtin_amdgcn_mfma_f32_16x16x32_bf16(kf, qf[0][ks], sa[kt][0], 0, 0, 0);
;                     sa[kt][1] = __builtin_amdgcn_mfma_f32_16x16x32_bf16(kf, qf[1][ks], sa[kt][1], 0, 0, 0);
;                 }
;             bf16x8 pf[2];
; #pragma unroll
;             for (int qt = 0; qt < 2; ++qt) {
;                 const int qp = wq * 32 + qt * 16 + l16;
;                 float sv[8]; float mx = -1e30f;
; #pragma unroll
;                 for (int kt = 0; kt < 2; ++kt)
; #pragma unroll
;                     for (int r = 0; r < 4; ++r) {
;                         const int kp = (kbi - 1) * 128 + si * 32 + kt * 16 + kg * 4 + r;
;                         const int rel = kp - qp; const bool valid = (rel >= -128) && (rel <= 128);
;                         const int idx = min(max(rel + 128, 0), 256);
;                         const float v = valid ? (sa[kt][qt][r] * SC + bL[hl * 260 + idx]) : -1e30f;
;                         sv[kt * 4 + r] = v; mx = fmaxf(mx, v);
;                     }
;                 mx = fmaxf(mx, __shfl_xor(mx, 16)); mx = fmaxf(mx, __shfl_xor(mx, 32));
;                 const float mnew = fmaxf(m2[qt], mx), alpha = __builtin_amdgcn_exp2f(m2[qt] - mnew); m2[qt] = mnew;
;                 float ps = 0.f; float pv[8];
; #pragma unroll
;                 for (int i = 0; i < 8; ++i) { pv[i] = __builtin_amdgcn_exp2f(sv[i] - mnew); ps += pv[i]; }
;                 lsum[qt] = lsum[qt] * alpha + ps;
; #pragma unroll
;                 for (int dt = 0; dt < 8; ++dt) o[dt][qt] = o[dt][qt] * alpha;
.LBB0_236:
	s_or_b64 exec, exec, s[78:79]
	v_cmp_le_u32_e32 vcc, s13, v195
	s_and_saveexec_b64 s[78:79], vcc
	s_cbranch_execz .LBB0_131
	v_add_u32_e32 v251, 0x11700, v201
	v_add_u32_e32 v251, v251, v196
	ds_read_b32 v235, v251 offset:640
	ds_read_b32 v236, v251 offset:644
	ds_read_b32 v237, v251 offset:648
	ds_read_b32 v238, v251 offset:652
	ds_read_b32 v239, v251 offset:704
	ds_read_b32 v240, v251 offset:708
	ds_read_b32 v241, v251 offset:712
	ds_read_b32 v242, v251 offset:716
	ds_read_b32 v243, v251 offset:576
	ds_read_b32 v244, v251 offset:580
	ds_read_b32 v245, v251 offset:584
	ds_read_b32 v246, v251 offset:588
	ds_read_b32 v247, v251 offset:640
	ds_read_b32 v248, v251 offset:644
	ds_read_b32 v249, v251 offset:648
	ds_read_b32 v250, v251 offset:652
	ds_read_b128 v[132:135], v212
	ds_read_b128 v[226:229], v212 offset:64
	ds_read_b128 v[140:143], v213 offset:30464
	v_subrev_u32_e32 v1, 19, v199
	v_cmp_gt_u32_e32 vcc, s53, v1
	v_add3_u32 v2, v201, v196, s49
	s_waitcnt lgkmcnt(0)
	v_mfma_f32_16x16x32_bf16 v[136:139], v[132:135], v[4:7], 0
	v_mfma_f32_16x16x32_bf16 v[132:135], v[132:135], v[20:23], 0
	v_mfma_f32_16x16x32_bf16 v[136:139], v[226:229], v[8:11], v[136:139]
	v_mfma_f32_16x16x32_bf16 v[132:135], v[226:229], v[24:27], v[132:135]
	ds_read_b128 v[226:229], v213 offset:30528
	v_mfma_f32_16x16x32_bf16 v[144:147], v[140:143], v[4:7], 0
	v_mfma_f32_16x16x32_bf16 v[140:143], v[140:143], v[20:23], 0
	s_waitcnt lgkmcnt(0)
	v_mfma_f32_16x16x32_bf16 v[144:147], v[226:229], v[8:11], v[144:147]
	v_mfma_f32_16x16x32_bf16 v[140:143], v[226:229], v[24:27], v[140:143]
	ds_read_b128 v[226:229], v212 offset:128
	s_waitcnt lgkmcnt(0)
	v_mfma_f32_16x16x32_bf16 v[136:139], v[226:229], v[12:15], v[136:139]
	v_mfma_f32_16x16x32_bf16 v[132:135], v[226:229], v[28:31], v[132:135]
	ds_read_b128 v[226:229], v213 offset:30592
	s_waitcnt lgkmcnt(0)
	v_mfma_f32_16x16x32_bf16 v[230:233], v[226:229], v[12:15], v[144:147]
	v_mfma_f32_16x16x32_bf16 v[226:229], v[226:229], v[28:31], v[140:143]
	s_nop 2
	ds_read_b128 v[140:143], v212 offset:192
	s_waitcnt lgkmcnt(0)
	v_mfma_f32_16x16x32_bf16 v[144:147], v[140:143], v[16:19], v[136:139]
	s_nop 2
	ds_read_b128 v[136:139], v213 offset:30656
	v_mfma_f32_16x16x32_bf16 v[140:143], v[140:143], v[32:35], v[132:135]
	s_waitcnt lgkmcnt(0)
	v_mfma_f32_16x16x32_bf16 v[132:135], v[136:139], v[16:19], v[230:233]
	v_mfma_f32_16x16x32_bf16 v[136:139], v[136:139], v[32:35], v[226:229]
	s_nop 2
	v_mov_b32_e32 v228, 0xf149f2ca
	v_mov_b32_e32 v229, 0xf149f2ca
	s_waitcnt lgkmcnt(0)
	v_fmac_f32_e32 v235, 0x3e0293ee, v144
	v_cndmask_b32_e32 v229, v229, v235, vcc
	v_subrev_u32_e32 v1, 18, v199
	v_cmp_gt_u32_e64 s[4:5], s53, v1
	v_add3_u32 v225, v201, v196, s0
	v_fmac_f32_e32 v236, 0x3e0293ee, v145
	v_cndmask_b32_e64 v228, v228, v236, s[4:5]
	v_subrev_u32_e32 v1, 17, v199
	v_cmp_gt_u32_e64 s[6:7], s53, v1
	v_mov_b32_e32 v145, 0xf149f2ca
	v_add3_u32 v226, v201, v196, s1
	v_mov_b32_e32 v230, 0xf149f2ca
	v_fmac_f32_e32 v237, 0x3e0293ee, v146
	v_cndmask_b32_e64 v230, v230, v237, s[6:7]
	v_add_u32_e32 v1, -16, v199
	v_cmp_gt_u32_e64 s[8:9], s53, v1
	v_add3_u32 v227, v201, v196, s15
	v_fmac_f32_e32 v238, 0x3e0293ee, v147
	v_cndmask_b32_e64 v145, v145, v238, s[8:9]
	v_add_u32_e32 v1, -3, v199
	v_cmp_gt_u32_e64 s[10:11], s53, v1
	v_mov_b32_e32 v232, 0xf149f2ca
	v_mov_b32_e32 v231, 0xf149f2ca
	v_fmac_f32_e32 v239, 0x3e0293ee, v132
	v_cndmask_b32_e64 v231, v231, v239, s[10:11]
	v_add_u32_e32 v1, -2, v199
	v_cmp_gt_u32_e64 s[10:11], s53, v1
	v_fmac_f32_e32 v240, 0x3e0293ee, v133
	s_nop 0
	v_cndmask_b32_e64 v232, v232, v240, s[10:11]
	v_add_u32_e32 v1, -1, v199
	v_cmp_gt_u32_e64 s[10:11], s53, v1
	v_mov_b32_e32 v132, 0xf149f2ca
	v_mov_b32_e32 v133, 0xf149f2ca
	v_fmac_f32_e32 v241, 0x3e0293ee, v134
	v_cndmask_b32_e64 v133, v133, v241, s[10:11]
	v_cmp_gt_u32_e64 s[10:11], s53, v199
	v_fmac_f32_e32 v242, 0x3e0293ee, v135
	s_nop 0
	v_cndmask_b32_e64 v132, v132, v242, s[10:11]
	v_mov_b32_e32 v144, 0xf149f2ca
	v_and_b32_e32 v134, 64, v182
	v_max3_f32 v1, v229, v144, v228
	v_xor_b32_e32 v3, 16, v182
	v_add_u32_e32 v134, 64, v134
	v_max3_f32 v1, v1, v230, v145
	v_cmp_lt_i32_e64 s[10:11], v3, v134
	v_max3_f32 v1, v1, v231, v232
	v_max3_f32 v1, v1, v133, v132
	v_cndmask_b32_e64 v3, v182, v3, s[10:11]
	v_lshlrev_b32_e32 v146, 2, v3
	ds_bpermute_b32 v135, v146, v1
	v_xor_b32_e32 v3, 32, v182
	v_cmp_lt_i32_e64 s[10:11], v3, v134
	s_waitcnt lgkmcnt(0)
	v_max_f32_e32 v134, v135, v135
	v_cndmask_b32_e64 v3, v182, v3, s[10:11]
	v_lshlrev_b32_e32 v3, 2, v3
	v_max_f32_e32 v1, v1, v134
	ds_bpermute_b32 v134, v3, v1
	s_waitcnt lgkmcnt(0)
	v_max3_f32 v1, v224, v1, v134
	v_sub_f32_e32 v134, v229, v1
	v_exp_f32_e32 v147, v134
	v_sub_f32_e32 v134, v228, v1
	v_exp_f32_e32 v228, v134
	v_sub_f32_e32 v134, v230, v1
	v_exp_f32_e32 v229, v134
	v_sub_f32_e32 v134, v145, v1
	v_exp_f32_e32 v230, v134
	v_sub_f32_e32 v134, v231, v1
	v_exp_f32_e32 v231, v134
	v_sub_f32_e32 v134, v232, v1
	v_sub_f32_e32 v133, v133, v1
	v_sub_f32_e32 v132, v132, v1
	v_exp_f32_e32 v232, v134
	v_exp_f32_e32 v233, v133
	v_exp_f32_e32 v234, v132
	v_subrev_u32_e32 v145, 35, v199
	v_cmp_gt_u32_e64 s[10:11], s53, v145
	v_mov_b32_e32 v145, 0xf149f2ca
	v_cvt_pk_bf16_f32 v132, v147, v228
	v_cvt_pk_bf16_f32 v133, v229, v230
	v_cvt_pk_bf16_f32 v134, v231, v232
	v_cvt_pk_bf16_f32 v135, v233, v234
	v_fmac_f32_e32 v243, 0x3e0293ee, v140
	v_cndmask_b32_e64 v145, v145, v243, s[10:11]
	v_subrev_u32_e32 v140, 34, v199
	v_cmp_gt_u32_e64 s[10:11], s53, v140
	v_fmac_f32_e32 v244, 0x3e0293ee, v141
	s_nop 0
	v_cndmask_b32_e64 v144, v144, v244, s[10:11]
	v_subrev_u32_e32 v140, 33, v199
	v_cmp_gt_u32_e64 s[10:11], s53, v140
	v_mov_b32_e32 v140, 0xf149f2ca
	v_mov_b32_e32 v141, 0xf149f2ca
	v_fmac_f32_e32 v245, 0x3e0293ee, v142
	v_cndmask_b32_e64 v141, v141, v245, s[10:11]
	v_subrev_u32_e32 v142, 32, v199
	v_cmp_gt_u32_e64 s[10:11], s53, v142
	v_fmac_f32_e32 v246, 0x3e0293ee, v143
	s_nop 0
	v_cndmask_b32_e64 v140, v140, v246, s[10:11]
	v_mov_b32_e32 v142, 0xf149f2ca
	v_mov_b32_e32 v143, 0xf149f2ca
	v_fmac_f32_e32 v247, 0x3e0293ee, v136
	v_cndmask_b32_e32 v143, v143, v247, vcc
	v_fmac_f32_e32 v248, 0x3e0293ee, v137
	v_cndmask_b32_e64 v142, v142, v248, s[4:5]
	v_mov_b32_e32 v136, 0xf149f2ca
	v_mov_b32_e32 v137, 0xf149f2ca
	v_fmac_f32_e32 v249, 0x3e0293ee, v138
	v_cndmask_b32_e64 v137, v137, v249, s[6:7]
	s_and_saveexec_b64 s[4:5], s[8:9]
	s_cbranch_execz .LBB0_130
	v_mov_b32_e32 v136, v250
	v_fmac_f32_e32 v136, 0x3e0293ee, v139
	s_branch .LBB0_130

; #define PG8_STAGE(bufoff, gbase, voff) do { _Pragma("unroll") for (int _i = 0; _i < 2; ++_i) \
;         __builtin_amdgcn_global_load_lds((const unsigned*)((const char*)(gbase) + (voff)[_i]), (LAS unsigned*)(lds + (bufoff) + ldsw + _i * 8192), 16, 0, 0); } while (0)
; #define PG8_LDA(dst, b, h) do { _Pragma("unroll") for (int m = 0; m < 4; ++m) _Pragma("unroll") for (int k = 0; k < 2; ++k) dst[m][k] = *(const LAS bf16x8*)(lds + PG8_SA(b, h) + aoff + m * 2048 + k * 1024); } while (0)
; #define PG8_LDB(dst, b, h) do { _Pragma("unroll") for (int n = 0; n < 2; ++n) _Pragma("unroll") for (int k = 0; k < 2; ++k) dst[n][k] = *(const LAS bf16x8*)(lds + PG8_SB(b, h) + boff + n * 2048 + k * 1024); } while (0)
; #define PG8_MMA(ai, bj, At, Bt) do { __builtin_amdgcn_s_setprio(3); _Pragma("unroll") for (int m = 0; m < 4; ++m) _Pragma("unroll") for (int n = 0; n < 2; ++n) _Pragma("unroll") for (int k = 0; k < 2; ++k) \
;         acc[ai][bj][m][n] = __builtin_amdgcn_mfma_f32_16x16x32_bf16(Bt[n][k], At[m][k], acc[ai][bj][m][n], 0, 0, 0); __builtin_amdgcn_s_setprio(0); } while (0)
; #define PG8_WAIT_V(n) asm volatile("s_waitcnt vmcnt(" #n ")" ::: "memory")
; #define PG8_WAIT_L(n) asm volatile("s_waitcnt lgkmcnt(" #n ")" ::: "memory")
; #define PG8_BAR __builtin_amdgcn_s_barrier()
; #define PG8_SCHED __builtin_amdgcn_sched_barrier(0)
;     ...
;             PG8_LDB(B0, 0, 0); PG8_LDB(B1, 0, 1); PG8_SCHED; PG8_LDA(At, 0, 0); PG8_STAGE(PG8_SA(1, 1), a1 + hstepA, voffA);
;             PG8_WAIT_V(8); PG8_WAIT_L(0); PG8_BAR; PG8_MMA(0, 0, At, B0); PG8_MMA(0, 1, At, B1); PG8_BAR; PG8_SCHED;
;             PG8_LDA(At, 0, 1); PG8_STAGE(PG8_SB(0, 0), b2, voffB); PG8_STAGE(PG8_SB(0, 1), b2 + hstepB, voffB); PG8_STAGE(PG8_SA(0, 0), a2, voffA);
;             PG8_WAIT_V(8); PG8_WAIT_L(0); PG8_BAR; PG8_MMA(1, 0, At, B0); PG8_MMA(1, 1, At, B1); PG8_BAR; PG8_SCHED;
.LBB0_451:
	s_add_u32 s77, s78, 0xfffc0080
	s_addc_u32 s80, s79, -1
	s_add_i32 s87, 0, 0x10000
	s_cmp_eq_u32 s61, 12
	s_cselect_b32 s83, s11, s80
	s_cselect_b32 s82, s34, s77
	v_add_u32_e32 v167, s87, v164
	s_cselect_b32 s81, s9, s60
	s_cselect_b32 s80, s35, s42
	s_add_i32 s77, 0, 0x14000
	ds_read_b128 v[144:147], v167
	ds_read_b128 v[168:171], v167 offset:1024
	ds_read_b128 v[172:175], v167 offset:2048
	ds_read_b128 v[192:195], v167 offset:3072
	v_add_u32_e32 v167, s77, v164
	ds_read_b128 v[196:199], v167
	ds_read_b128 v[200:203], v167 offset:1024
	ds_read_b128 v[204:207], v167 offset:2048
	ds_read_b128 v[208:211], v167 offset:3072
	v_lshl_add_u64 v[176:177], s[78:79], 0, v[142:143]
	s_add_i32 m0, s69, 0xc000
	ds_read_b128 v[212:215], v166
	ds_read_b128 v[216:219], v166 offset:1024
	ds_read_b128 v[220:223], v166 offset:2048
	ds_read_b128 v[224:227], v166 offset:3072
	ds_read_b128 v[228:231], v166 offset:4096
	ds_read_b128 v[232:235], v166 offset:5120
	ds_read_b128 v[236:239], v166 offset:6144
	ds_read_b128 v[240:243], v166 offset:7168
	global_load_lds_dwordx4 v[176:177], off
	v_lshl_add_u64 v[176:177], s[78:79], 0, v[140:141]
	s_add_i32 m0, s69, 0xe000
	s_nop 0
	global_load_lds_dwordx4 v[176:177], off
	s_waitcnt vmcnt(8)
	s_waitcnt lgkmcnt(0)
	s_barrier
	s_setprio 3
	s_waitcnt lgkmcnt(0)
	v_mfma_f32_16x16x32_bf16 v[126:129], v[144:147], v[212:215], v[126:129]
	v_mfma_f32_16x16x32_bf16 v[122:125], v[172:175], v[212:215], v[122:125]
	v_mfma_f32_16x16x32_bf16 v[110:113], v[144:147], v[220:223], v[110:113]
	v_mfma_f32_16x16x32_bf16 v[106:109], v[172:175], v[220:223], v[106:109]
	v_mfma_f32_16x16x32_bf16 v[94:97], v[144:147], v[228:231], v[94:97]
	v_mfma_f32_16x16x32_bf16 v[90:93], v[172:175], v[228:231], v[90:93]
	v_mfma_f32_16x16x32_bf16 v[78:81], v[144:147], v[236:239], v[78:81]
	v_mfma_f32_16x16x32_bf16 v[74:77], v[172:175], v[236:239], v[74:77]
	v_mfma_f32_16x16x32_bf16 v[126:129], v[168:171], v[216:219], v[126:129]
	v_mfma_f32_16x16x32_bf16 v[122:125], v[192:195], v[216:219], v[122:125]
	v_mfma_f32_16x16x32_bf16 v[110:113], v[168:171], v[224:227], v[110:113]
	v_mfma_f32_16x16x32_bf16 v[106:109], v[192:195], v[224:227], v[106:109]
	v_mfma_f32_16x16x32_bf16 v[94:97], v[168:171], v[232:235], v[94:97]
	v_mfma_f32_16x16x32_bf16 v[90:93], v[192:195], v[232:235], v[90:93]
	v_mfma_f32_16x16x32_bf16 v[78:81], v[168:171], v[240:243], v[78:81]
	v_mfma_f32_16x16x32_bf16 v[74:77], v[192:195], v[240:243], v[74:77]
	s_setprio 0
	s_setprio 3
	v_mfma_f32_16x16x32_bf16 v[118:121], v[196:199], v[212:215], v[118:121]
	v_mfma_f32_16x16x32_bf16 v[114:117], v[204:207], v[212:215], v[114:117]
	v_mfma_f32_16x16x32_bf16 v[102:105], v[196:199], v[220:223], v[102:105]
	v_mfma_f32_16x16x32_bf16 v[98:101], v[204:207], v[220:223], v[98:101]
	v_mfma_f32_16x16x32_bf16 v[86:89], v[196:199], v[228:231], v[86:89]
	v_mfma_f32_16x16x32_bf16 v[82:85], v[204:207], v[228:231], v[82:85]
	v_mfma_f32_16x16x32_bf16 v[70:73], v[196:199], v[236:239], v[70:73]
	v_mfma_f32_16x16x32_bf16 v[66:69], v[204:207], v[236:239], v[66:69]
	v_mfma_f32_16x16x32_bf16 v[118:121], v[200:203], v[216:219], v[118:121]
	v_mfma_f32_16x16x32_bf16 v[114:117], v[208:211], v[216:219], v[114:117]
	v_mfma_f32_16x16x32_bf16 v[102:105], v[200:203], v[224:227], v[102:105]
	v_mfma_f32_16x16x32_bf16 v[98:101], v[208:211], v[224:227], v[98:101]
	v_mfma_f32_16x16x32_bf16 v[86:89], v[200:203], v[232:235], v[86:89]
	v_mfma_f32_16x16x32_bf16 v[82:85], v[208:211], v[232:235], v[82:85]
	v_mfma_f32_16x16x32_bf16 v[70:73], v[200:203], v[240:243], v[70:73]
	v_mfma_f32_16x16x32_bf16 v[66:69], v[208:211], v[240:243], v[66:69]
	s_setprio 0
	s_barrier
	s_add_i32 s87, s87, s31
	v_lshl_add_u64 v[176:177], s[80:81], 0, v[134:135]
	s_mov_b32 m0, s87
	ds_read_b128 v[212:215], v166 offset:16384
	ds_read_b128 v[216:219], v166 offset:17408
	ds_read_b128 v[220:223], v166 offset:18432
	ds_read_b128 v[224:227], v166 offset:19456
	ds_read_b128 v[228:231], v166 offset:20480
	ds_read_b128 v[232:235], v166 offset:21504
	ds_read_b128 v[236:239], v166 offset:22528
	ds_read_b128 v[240:243], v166 offset:23552
	global_load_lds_dwordx4 v[176:177], off
	s_add_i32 m0, s87, 0x2000
	s_add_u32 s94, s80, 0x10000
	v_lshl_add_u64 v[244:245], s[80:81], 0, v[130:131]
	s_addc_u32 s95, s81, 0
	s_add_i32 s77, s77, s31
	global_load_lds_dwordx4 v[244:245], off
	v_lshl_add_u64 v[246:247], s[94:95], 0, v[134:135]
	s_mov_b32 m0, s77
	v_lshl_add_u64 v[248:249], s[82:83], 0, v[132:133]
	global_load_lds_dwordx4 v[246:247], off
	v_lshl_add_u64 v[246:247], s[94:95], 0, v[130:131]
	s_add_i32 m0, s77, 0x2000
	s_nop 0
	global_load_lds_dwordx4 v[246:247], off
	v_lshl_add_u64 v[246:247], s[82:83], 0, v[136:137]
	s_mov_b32 m0, s69
	s_nop 0
	global_load_lds_dwordx4 v[246:247], off
	s_mov_b32 m0, s70
	s_nop 0
	global_load_lds_dwordx4 v[248:249], off
	s_waitcnt vmcnt(8)
	s_waitcnt lgkmcnt(0)
	s_barrier
; #define PG8_STAGE(bufoff, gbase, voff) do { _Pragma("unroll") for (int _i = 0; _i < 2; ++_i) \
;         __builtin_amdgcn_global_load_lds((const unsigned*)((const char*)(gbase) + (voff)[_i]), (LAS unsigned*)(lds + (bufoff) + ldsw + _i * 8192), 16, 0, 0); } while (0)
; #define PG8_LDA(dst, b, h) do { _Pragma("unroll") for (int m = 0; m < 4; ++m) _Pragma("unroll") for (int k = 0; k < 2; ++k) dst[m][k] = *(const LAS bf16x8*)(lds + PG8_SA(b, h) + aoff + m * 2048 + k * 1024); } while (0)
; #define PG8_LDB(dst, b, h) do { _Pragma("unroll") for (int n = 0; n < 2; ++n) _Pragma("unroll") for (int k = 0; k < 2; ++k) dst[n][k] = *(const LAS bf16x8*)(lds + PG8_SB(b, h) + boff + n * 2048 + k * 1024); } while (0)
; #define PG8_MMA(ai, bj, At, Bt) do { __builtin_amdgcn_s_setprio(3); _Pragma("unroll") for (int m = 0; m < 4; ++m) _Pragma("unroll") for (int n = 0; n < 2; ++n) _Pragma("unroll") for (int k = 0; k < 2; ++k) \
;         acc[ai][bj][m][n] = __builtin_amdgcn_mfma_f32_16x16x32_bf16(Bt[n][k], At[m][k], acc[ai][bj][m][n], 0, 0, 0); __builtin_amdgcn_s_setprio(0); } while (0)
; #define PG8_WAIT_V(n) asm volatile("s_waitcnt vmcnt(" #n ")" ::: "memory")
; #define PG8_WAIT_L(n) asm volatile("s_waitcnt lgkmcnt(" #n ")" ::: "memory")
; #define PG8_BAR __builtin_amdgcn_s_barrier()
; #define PG8_SCHED __builtin_amdgcn_sched_barrier(0)
;     ...
;             PG8_LDB(B0, 0, 0); PG8_LDB(B1, 0, 1); PG8_SCHED; PG8_LDA(At, 0, 0); PG8_STAGE(PG8_SA(1, 1), a1 + hstepA, voffA);
;             PG8_WAIT_V(8); PG8_WAIT_L(0); PG8_BAR; PG8_MMA(0, 0, At, B0); PG8_MMA(0, 1, At, B1); PG8_BAR; PG8_SCHED;
;             PG8_LDA(At, 0, 1); PG8_STAGE(PG8_SB(0, 0), b2, voffB); PG8_STAGE(PG8_SB(0, 1), b2 + hstepB, voffB); PG8_STAGE(PG8_SA(0, 0), a2, voffA);
;             PG8_WAIT_V(8); PG8_WAIT_L(0); PG8_BAR; PG8_MMA(1, 0, At, B0); PG8_MMA(1, 1, At, B1); PG8_BAR; PG8_SCHED;
;             PG8_LDB(B0, 1, 0); PG8_LDB(B1, 1, 1); PG8_SCHED; PG8_LDA(At, 1, 0); PG8_STAGE(PG8_SA(0, 1), a2 + hstepA, voffA);
;             PG8_WAIT_V(8); PG8_WAIT_L(0); PG8_BAR; PG8_MMA(0, 0, At, B0); PG8_MMA(0, 1, At, B1); PG8_BAR; PG8_SCHED;
;             PG8_LDA(At, 1, 1); PG8_STAGE(PG8_SB(1, 0), b3, voffB); PG8_STAGE(PG8_SB(1, 1), b3 + hstepB, voffB); PG8_STAGE(PG8_SA(1, 0), a3, voffA);
;             PG8_WAIT_V(8); PG8_WAIT_L(0); PG8_BAR; PG8_MMA(1, 0, At, B0); PG8_MMA(1, 1, At, B1); PG8_BAR; PG8_SCHED;
	s_setprio 3
	s_waitcnt lgkmcnt(0)
	v_mfma_f32_16x16x32_bf16 v[62:65], v[144:147], v[212:215], v[62:65]
	v_mfma_f32_16x16x32_bf16 v[58:61], v[172:175], v[212:215], v[58:61]
	v_mfma_f32_16x16x32_bf16 v[46:49], v[144:147], v[220:223], v[46:49]
	v_mfma_f32_16x16x32_bf16 v[42:45], v[172:175], v[220:223], v[42:45]
	v_mfma_f32_16x16x32_bf16 v[30:33], v[144:147], v[228:231], v[30:33]
	v_mfma_f32_16x16x32_bf16 v[26:29], v[172:175], v[228:231], v[26:29]
	v_mfma_f32_16x16x32_bf16 v[14:17], v[144:147], v[236:239], v[14:17]
	v_mfma_f32_16x16x32_bf16 v[10:13], v[172:175], v[236:239], v[10:13]
	v_mfma_f32_16x16x32_bf16 v[62:65], v[168:171], v[216:219], v[62:65]
	v_mfma_f32_16x16x32_bf16 v[58:61], v[192:195], v[216:219], v[58:61]
	v_mfma_f32_16x16x32_bf16 v[46:49], v[168:171], v[224:227], v[46:49]
	v_mfma_f32_16x16x32_bf16 v[42:45], v[192:195], v[224:227], v[42:45]
	v_mfma_f32_16x16x32_bf16 v[30:33], v[168:171], v[232:235], v[30:33]
	v_mfma_f32_16x16x32_bf16 v[26:29], v[192:195], v[232:235], v[26:29]
	v_mfma_f32_16x16x32_bf16 v[14:17], v[168:171], v[240:243], v[14:17]
	v_mfma_f32_16x16x32_bf16 v[10:13], v[192:195], v[240:243], v[10:13]
	s_setprio 0
	s_setprio 3
	v_mfma_f32_16x16x32_bf16 v[54:57], v[196:199], v[212:215], v[54:57]
	v_mfma_f32_16x16x32_bf16 v[50:53], v[204:207], v[212:215], v[50:53]
	v_mfma_f32_16x16x32_bf16 v[38:41], v[196:199], v[220:223], v[38:41]
	v_mfma_f32_16x16x32_bf16 v[34:37], v[204:207], v[220:223], v[34:37]
	v_mfma_f32_16x16x32_bf16 v[22:25], v[196:199], v[228:231], v[22:25]
	v_mfma_f32_16x16x32_bf16 v[18:21], v[204:207], v[228:231], v[18:21]
	v_mfma_f32_16x16x32_bf16 v[6:9], v[196:199], v[236:239], v[6:9]
	v_mfma_f32_16x16x32_bf16 v[2:5], v[204:207], v[236:239], v[2:5]
	v_mfma_f32_16x16x32_bf16 v[54:57], v[200:203], v[216:219], v[54:57]
	v_mfma_f32_16x16x32_bf16 v[50:53], v[208:211], v[216:219], v[50:53]
	v_mfma_f32_16x16x32_bf16 v[38:41], v[200:203], v[224:227], v[38:41]
	v_mfma_f32_16x16x32_bf16 v[34:37], v[208:211], v[224:227], v[34:37]
	v_mfma_f32_16x16x32_bf16 v[22:25], v[200:203], v[232:235], v[22:25]
	v_mfma_f32_16x16x32_bf16 v[18:21], v[208:211], v[232:235], v[18:21]
	v_mfma_f32_16x16x32_bf16 v[6:9], v[200:203], v[240:243], v[6:9]
	v_mfma_f32_16x16x32_bf16 v[2:5], v[208:211], v[240:243], v[2:5]
	s_setprio 0
	s_barrier
	s_add_i32 s77, 0, 0x18000
	v_add_u32_e32 v167, s77, v164
	s_add_i32 s87, 0, 0x1c000
	ds_read_b128 v[144:147], v167
	ds_read_b128 v[168:171], v167 offset:1024
	ds_read_b128 v[172:175], v167 offset:2048
	ds_read_b128 v[192:195], v167 offset:3072
	v_add_u32_e32 v167, s87, v164
	ds_read_b128 v[196:199], v167
	ds_read_b128 v[200:203], v167 offset:1024
	ds_read_b128 v[204:207], v167 offset:2048
	ds_read_b128 v[208:211], v167 offset:3072
	s_add_u32 s82, s82, 0x40000
	s_addc_u32 s83, s83, 0
	s_mov_b32 m0, s71
	v_lshl_add_u64 v[250:251], s[82:83], 0, v[136:137]
	ds_read_b128 v[212:215], v166 offset:32768
	ds_read_b128 v[216:219], v166 offset:33792
	ds_read_b128 v[220:223], v166 offset:34816
	ds_read_b128 v[224:227], v166 offset:35840
	ds_read_b128 v[228:231], v166 offset:36864
	ds_read_b128 v[232:235], v166 offset:37888
	ds_read_b128 v[236:239], v166 offset:38912
	ds_read_b128 v[240:243], v166 offset:39936
	global_load_lds_dwordx4 v[250:251], off
	v_lshl_add_u64 v[250:251], s[82:83], 0, v[132:133]
	s_mov_b32 m0, s86
	s_nop 0
	global_load_lds_dwordx4 v[250:251], off
	s_waitcnt vmcnt(8)
	s_waitcnt lgkmcnt(0)
	s_barrier
	s_setprio 3
	s_waitcnt lgkmcnt(0)
	v_mfma_f32_16x16x32_bf16 v[126:129], v[144:147], v[212:215], v[126:129]
	v_mfma_f32_16x16x32_bf16 v[122:125], v[172:175], v[212:215], v[122:125]
	v_mfma_f32_16x16x32_bf16 v[110:113], v[144:147], v[220:223], v[110:113]
	v_mfma_f32_16x16x32_bf16 v[106:109], v[172:175], v[220:223], v[106:109]
	v_mfma_f32_16x16x32_bf16 v[94:97], v[144:147], v[228:231], v[94:97]
	v_mfma_f32_16x16x32_bf16 v[90:93], v[172:175], v[228:231], v[90:93]
	v_mfma_f32_16x16x32_bf16 v[78:81], v[144:147], v[236:239], v[78:81]
	v_mfma_f32_16x16x32_bf16 v[74:77], v[172:175], v[236:239], v[74:77]
	v_mfma_f32_16x16x32_bf16 v[126:129], v[168:171], v[216:219], v[126:129]
	v_mfma_f32_16x16x32_bf16 v[122:125], v[192:195], v[216:219], v[122:125]
	v_mfma_f32_16x16x32_bf16 v[110:113], v[168:171], v[224:227], v[110:113]
	v_mfma_f32_16x16x32_bf16 v[106:109], v[192:195], v[224:227], v[106:109]
	v_mfma_f32_16x16x32_bf16 v[94:97], v[168:171], v[232:235], v[94:97]
	v_mfma_f32_16x16x32_bf16 v[90:93], v[192:195], v[232:235], v[90:93]
	v_mfma_f32_16x16x32_bf16 v[78:81], v[168:171], v[240:243], v[78:81]
	v_mfma_f32_16x16x32_bf16 v[74:77], v[192:195], v[240:243], v[74:77]
	s_setprio 0
	s_setprio 3
	v_mfma_f32_16x16x32_bf16 v[118:121], v[196:199], v[212:215], v[118:121]
	v_mfma_f32_16x16x32_bf16 v[114:117], v[204:207], v[212:215], v[114:117]
	v_mfma_f32_16x16x32_bf16 v[102:105], v[196:199], v[220:223], v[102:105]
	v_mfma_f32_16x16x32_bf16 v[98:101], v[204:207], v[220:223], v[98:101]
	v_mfma_f32_16x16x32_bf16 v[86:89], v[196:199], v[228:231], v[86:89]
	v_mfma_f32_16x16x32_bf16 v[82:85], v[204:207], v[228:231], v[82:85]
	v_mfma_f32_16x16x32_bf16 v[70:73], v[196:199], v[236:239], v[70:73]
	v_mfma_f32_16x16x32_bf16 v[66:69], v[204:207], v[236:239], v[66:69]
	v_mfma_f32_16x16x32_bf16 v[118:121], v[200:203], v[216:219], v[118:121]
	v_mfma_f32_16x16x32_bf16 v[114:117], v[208:211], v[216:219], v[114:117]
	v_mfma_f32_16x16x32_bf16 v[102:105], v[200:203], v[224:227], v[102:105]
	v_mfma_f32_16x16x32_bf16 v[98:101], v[208:211], v[224:227], v[98:101]
	v_mfma_f32_16x16x32_bf16 v[86:89], v[200:203], v[232:235], v[86:89]
	v_mfma_f32_16x16x32_bf16 v[82:85], v[208:211], v[232:235], v[82:85]
	v_mfma_f32_16x16x32_bf16 v[70:73], v[200:203], v[240:243], v[70:73]
	v_mfma_f32_16x16x32_bf16 v[66:69], v[208:211], v[240:243], v[66:69]
	s_setprio 0
	s_barrier
; #define PG8_STAGE(bufoff, gbase, voff) do { _Pragma("unroll") for (int _i = 0; _i < 2; ++_i) \
;         __builtin_amdgcn_global_load_lds((const unsigned*)((const char*)(gbase) + (voff)[_i]), (LAS unsigned*)(lds + (bufoff) + ldsw + _i * 8192), 16, 0, 0); } while (0)
; #define PG8_LDA(dst, b, h) do { _Pragma("unroll") for (int m = 0; m < 4; ++m) _Pragma("unroll") for (int k = 0; k < 2; ++k) dst[m][k] = *(const LAS bf16x8*)(lds + PG8_SA(b, h) + aoff + m * 2048 + k * 1024); } while (0)
; #define PG8_MMA(ai, bj, At, Bt) do { __builtin_amdgcn_s_setprio(3); _Pragma("unroll") for (int m = 0; m < 4; ++m) _Pragma("unroll") for (int n = 0; n < 2; ++n) _Pragma("unroll") for (int k = 0; k < 2; ++k) \
;         acc[ai][bj][m][n] = __builtin_amdgcn_mfma_f32_16x16x32_bf16(Bt[n][k], At[m][k], acc[ai][bj][m][n], 0, 0, 0); __builtin_amdgcn_s_setprio(0); } while (0)
; #define PG8_WAIT_V(n) asm volatile("s_waitcnt vmcnt(" #n ")" ::: "memory")
; #define PG8_WAIT_L(n) asm volatile("s_waitcnt lgkmcnt(" #n ")" ::: "memory")
; #define PG8_BAR __builtin_amdgcn_s_barrier()
; #define PG8_SCHED __builtin_amdgcn_sched_barrier(0)
; __device__ __forceinline__ float row_rs4(const float* ssq, int row, int fq) {
;     const f32x4 a = *(const f32x4*)(ssq + (size_t)row * 16 + fq * 4);
;     ...
;             PG8_LDA(At, 1, 1); PG8_STAGE(PG8_SB(1, 0), b3, voffB); PG8_STAGE(PG8_SB(1, 1), b3 + hstepB, voffB); PG8_STAGE(PG8_SA(1, 0), a3, voffA);
;             PG8_WAIT_V(8); PG8_WAIT_L(0); PG8_BAR; PG8_MMA(1, 0, At, B0); PG8_MMA(1, 1, At, B1); PG8_BAR; PG8_SCHED;
	s_add_i32 s77, s77, s31
	v_lshl_add_u64 v[176:177], v[176:177], 0, s[46:47]
	s_mov_b32 m0, s77
	ds_read_b128 v[212:215], v166 offset:49152
	ds_read_b128 v[216:219], v166 offset:50176
	ds_read_b128 v[220:223], v166 offset:51200
	ds_read_b128 v[224:227], v166 offset:52224
	ds_read_b128 v[228:231], v166 offset:53248
	ds_read_b128 v[232:235], v166 offset:54272
	ds_read_b128 v[236:239], v166 offset:55296
	ds_read_b128 v[240:243], v166 offset:56320
	global_load_lds_dwordx4 v[176:177], off
	s_add_i32 m0, s77, 0x2000
	s_add_u32 s80, s80, 0x10080
	v_lshl_add_u64 v[176:177], v[244:245], 0, s[46:47]
	s_addc_u32 s81, s81, 0
	s_add_i32 s77, s87, s31
	global_load_lds_dwordx4 v[176:177], off
	v_lshl_add_u64 v[176:177], s[80:81], 0, v[134:135]
	s_mov_b32 m0, s77
	s_nop 0
	global_load_lds_dwordx4 v[176:177], off
	v_lshl_add_u64 v[176:177], s[80:81], 0, v[130:131]
	s_add_i32 m0, s77, 0x2000
	s_nop 0
	global_load_lds_dwordx4 v[176:177], off
	v_lshl_add_u64 v[176:177], v[246:247], 0, s[46:47]
	s_mov_b32 m0, s40
	s_nop 0
	global_load_lds_dwordx4 v[176:177], off
	v_lshl_add_u64 v[176:177], v[248:249], 0, s[46:47]
	s_mov_b32 m0, s4
	s_nop 0
	global_load_lds_dwordx4 v[176:177], off
	s_waitcnt vmcnt(8)
	s_waitcnt lgkmcnt(0)
	s_barrier
	s_setprio 3
	s_waitcnt lgkmcnt(0)
	v_mfma_f32_16x16x32_bf16 v[62:65], v[144:147], v[212:215], v[62:65]
	v_mfma_f32_16x16x32_bf16 v[58:61], v[172:175], v[212:215], v[58:61]
	v_mfma_f32_16x16x32_bf16 v[46:49], v[144:147], v[220:223], v[46:49]
	v_mfma_f32_16x16x32_bf16 v[42:45], v[172:175], v[220:223], v[42:45]
	v_mfma_f32_16x16x32_bf16 v[30:33], v[144:147], v[228:231], v[30:33]
	v_mfma_f32_16x16x32_bf16 v[26:29], v[172:175], v[228:231], v[26:29]
	v_mfma_f32_16x16x32_bf16 v[14:17], v[144:147], v[236:239], v[14:17]
	v_mfma_f32_16x16x32_bf16 v[10:13], v[172:175], v[236:239], v[10:13]
	v_mfma_f32_16x16x32_bf16 v[62:65], v[168:171], v[216:219], v[62:65]
	v_mfma_f32_16x16x32_bf16 v[58:61], v[192:195], v[216:219], v[58:61]
	v_mfma_f32_16x16x32_bf16 v[46:49], v[168:171], v[224:227], v[46:49]
	v_mfma_f32_16x16x32_bf16 v[42:45], v[192:195], v[224:227], v[42:45]
	v_mfma_f32_16x16x32_bf16 v[30:33], v[168:171], v[232:235], v[30:33]
	v_mfma_f32_16x16x32_bf16 v[26:29], v[192:195], v[232:235], v[26:29]
	v_mfma_f32_16x16x32_bf16 v[14:17], v[168:171], v[240:243], v[14:17]
	v_mfma_f32_16x16x32_bf16 v[10:13], v[192:195], v[240:243], v[10:13]
	s_setprio 0
	s_setprio 3
	v_mfma_f32_16x16x32_bf16 v[54:57], v[196:199], v[212:215], v[54:57]
	v_mfma_f32_16x16x32_bf16 v[50:53], v[204:207], v[212:215], v[50:53]
	v_mfma_f32_16x16x32_bf16 v[38:41], v[196:199], v[220:223], v[38:41]
	v_mfma_f32_16x16x32_bf16 v[34:37], v[204:207], v[220:223], v[34:37]
	v_mfma_f32_16x16x32_bf16 v[22:25], v[196:199], v[228:231], v[22:25]
	v_mfma_f32_16x16x32_bf16 v[18:21], v[204:207], v[228:231], v[18:21]
	v_mfma_f32_16x16x32_bf16 v[6:9], v[196:199], v[236:239], v[6:9]
	v_mfma_f32_16x16x32_bf16 v[2:5], v[204:207], v[236:239], v[2:5]
	v_mfma_f32_16x16x32_bf16 v[54:57], v[200:203], v[216:219], v[54:57]
	v_mfma_f32_16x16x32_bf16 v[50:53], v[208:211], v[216:219], v[50:53]
	v_mfma_f32_16x16x32_bf16 v[38:41], v[200:203], v[224:227], v[38:41]
	v_mfma_f32_16x16x32_bf16 v[34:37], v[208:211], v[224:227], v[34:37]
	v_mfma_f32_16x16x32_bf16 v[22:25], v[200:203], v[232:235], v[22:25]
	v_mfma_f32_16x16x32_bf16 v[18:21], v[208:211], v[232:235], v[18:21]
	v_mfma_f32_16x16x32_bf16 v[6:9], v[200:203], v[240:243], v[6:9]
	v_mfma_f32_16x16x32_bf16 v[2:5], v[208:211], v[240:243], v[2:5]
	s_setprio 0
	s_barrier
	s_add_i32 s61, s61, 2
	s_add_u32 s42, s42, 0x100
	s_addc_u32 s60, s60, 0
	s_add_u32 s78, s78, 0x100
	s_addc_u32 s79, s79, 0
	s_cmp_gt_u32 s61, 13
	s_cbranch_scc0 .LBB0_451
	v_lshl_add_u32 v232, s76, 8, v1
	v_ashrrev_i32_e32 v233, 31, v232
	v_lshlrev_b64 v[234:235], 6, v[232:233]
	v_lshl_add_u64 v[234:235], v[138:139], 0, v[234:235]
	global_load_dwordx4 v[192:195], v[234:235], off
	global_load_dwordx4 v[196:199], v[234:235], off offset:1024
	global_load_dwordx4 v[200:203], v[234:235], off offset:2048
	global_load_dwordx4 v[204:207], v[234:235], off offset:3072
	v_add_u32_e32 v232, 0x80, v232
	v_ashrrev_i32_e32 v233, 31, v232
	v_lshlrev_b64 v[234:235], 6, v[232:233]
	v_lshl_add_u64 v[234:235], v[138:139], 0, v[234:235]
	global_load_dwordx4 v[208:211], v[234:235], off
	global_load_dwordx4 v[212:215], v[234:235], off offset:1024
	global_load_dwordx4 v[216:219], v[234:235], off offset:2048
	global_load_dwordx4 v[220:223], v[234:235], off offset:3072
	v_xor_b32_e32 v176, 16, v182
	v_xor_b32_e32 v177, 32, v182
	v_lshlrev_b32_e32 v176, 2, v176
	v_lshlrev_b32_e32 v177, 2, v177
	s_and_b64 vcc, exec, s[6:7]
	s_cbranch_vccz .LBB0_454
	s_barrier
; __device__ __forceinline__ unsigned cvt_pk_bf16(float lo, float hi) { unsigned r; asm volatile("v_cvt_pk_bf16_f32 %0, %1, %2" : "=v"(r) : "v"(lo), "v"(hi)); return r; }
; __device__ __forceinline__ float row_rs4(const float* ssq, int row, int fq) {
;     const f32x4 a = *(const f32x4*)(ssq + (size_t)row * 16 + fq * 4);
;     float s = (a[0] + a[1]) + (a[2] + a[3]);
;     s += __shfl_xor(s, 16); s += __shfl_xor(s, 32);
;     return __builtin_amdgcn_rsqf(s * (1.0f / 1024.0f) + 1e-6f);
; }
;     __device__ __forceinline__ void operator()(const f32x4 (&acc)[2][2][4][2], const Unit& u, int wr, int wc, int fr, int fq) const {
;     ...
;                 const int row = row0 + ai * HALF + m * 16; const float rs = row_rs4(ssq, row, fq);
; #pragma unroll
;                 for (int bj = 0; bj < 2; ++bj) {
;                     const f32x4 v0 = acc[ai][bj][m][0] * rs, v1 = acc[ai][bj][m][1] * rs;
;                     u32x4 w; w.x = cvt_pk_bf16(v0[0], v0[1]); w.y = cvt_pk_bf16(v0[2], v0[3]); w.z = cvt_pk_bf16(v1[0], v1[1]); w.w = cvt_pk_bf16(v1[2], v1[3]);
;                     *(u32x4*)(proj + (size_t)row * pitch + col0 + bj * 32) = w;
.LBB0_454:
	s_waitcnt vmcnt(0)
	v_add_f32_e32 v192, v192, v193
	v_add_f32_e32 v194, v194, v195
	v_add_f32_e32 v196, v196, v197
	v_add_f32_e32 v198, v198, v199
	v_add_f32_e32 v200, v200, v201
	v_add_f32_e32 v202, v202, v203
	v_add_f32_e32 v204, v204, v205
	v_add_f32_e32 v206, v206, v207
	v_add_f32_e32 v208, v208, v209
	v_add_f32_e32 v210, v210, v211
	v_add_f32_e32 v212, v212, v213
	v_add_f32_e32 v214, v214, v215
	v_add_f32_e32 v216, v216, v217
	v_add_f32_e32 v218, v218, v219
	v_add_f32_e32 v220, v220, v221
	v_add_f32_e32 v222, v222, v223
	v_add_f32_e32 v192, v192, v194
	v_add_f32_e32 v196, v196, v198
	v_add_f32_e32 v200, v200, v202
	v_add_f32_e32 v204, v204, v206
	v_add_f32_e32 v208, v208, v210
	v_add_f32_e32 v212, v212, v214
	v_add_f32_e32 v216, v216, v218
	v_add_f32_e32 v220, v220, v222
	ds_bpermute_b32 v224, v176, v192
	ds_bpermute_b32 v225, v176, v196
	ds_bpermute_b32 v226, v176, v200
	ds_bpermute_b32 v227, v176, v204
	ds_bpermute_b32 v228, v176, v208
	ds_bpermute_b32 v229, v176, v212
	ds_bpermute_b32 v230, v176, v216
	ds_bpermute_b32 v231, v176, v220
	s_waitcnt lgkmcnt(7)
	v_add_f32_e32 v192, v192, v224
	s_waitcnt lgkmcnt(6)
	v_add_f32_e32 v196, v196, v225
	s_waitcnt lgkmcnt(5)
	v_add_f32_e32 v200, v200, v226
	s_waitcnt lgkmcnt(4)
	v_add_f32_e32 v204, v204, v227
	s_waitcnt lgkmcnt(3)
	v_add_f32_e32 v208, v208, v228
	s_waitcnt lgkmcnt(2)
	v_add_f32_e32 v212, v212, v229
	s_waitcnt lgkmcnt(1)
	v_add_f32_e32 v216, v216, v230
	s_waitcnt lgkmcnt(0)
	v_add_f32_e32 v220, v220, v231
	ds_bpermute_b32 v224, v177, v192
	ds_bpermute_b32 v225, v177, v196
	ds_bpermute_b32 v226, v177, v200
	ds_bpermute_b32 v227, v177, v204
	ds_bpermute_b32 v228, v177, v208
	ds_bpermute_b32 v229, v177, v212
	ds_bpermute_b32 v230, v177, v216
	ds_bpermute_b32 v231, v177, v220
	s_waitcnt lgkmcnt(7)
	v_add_f32_e32 v192, v192, v224
	s_waitcnt lgkmcnt(6)
	v_add_f32_e32 v196, v196, v225
	s_waitcnt lgkmcnt(5)
	v_add_f32_e32 v200, v200, v226
	s_waitcnt lgkmcnt(4)
	v_add_f32_e32 v204, v204, v227
	s_waitcnt lgkmcnt(3)
	v_add_f32_e32 v208, v208, v228
	s_waitcnt lgkmcnt(2)
	v_add_f32_e32 v212, v212, v229
	s_waitcnt lgkmcnt(1)
	v_add_f32_e32 v216, v216, v230
	s_waitcnt lgkmcnt(0)
	v_add_f32_e32 v220, v220, v231
	v_fmamk_f32 v192, v192, 0x3a800000, v179
	v_fmamk_f32 v196, v196, 0x3a800000, v179
	v_fmamk_f32 v200, v200, 0x3a800000, v179
	v_fmamk_f32 v204, v204, 0x3a800000, v179
	v_fmamk_f32 v208, v208, 0x3a800000, v179
	v_fmamk_f32 v212, v212, 0x3a800000, v179
	v_fmamk_f32 v216, v216, 0x3a800000, v179
	v_fmamk_f32 v220, v220, 0x3a800000, v179
	v_rsq_f32_e32 v192, v192
	v_rsq_f32_e32 v196, v196
	v_rsq_f32_e32 v200, v200
	v_rsq_f32_e32 v204, v204
	v_rsq_f32_e32 v208, v208
	v_rsq_f32_e32 v212, v212
	v_rsq_f32_e32 v216, v216
	v_rsq_f32_e32 v220, v220
	s_nop 0
	v_and_b32_e32 v147, 64, v182
	v_xor_b32_e32 v145, 16, v182
	v_add_u32_e32 v147, 64, v147
	v_cmp_lt_i32_e32 vcc, v145, v147
	v_lshl_add_u32 v144, s76, 8, v1
	v_lshl_or_b32 v146, s19, 8, v165
	v_cndmask_b32_e32 v145, v182, v145, vcc
	v_lshlrev_b32_e32 v167, 2, v145
	v_xor_b32_e32 v145, 32, v182
	v_cmp_lt_i32_e32 vcc, v145, v147
	v_ashrrev_i32_e32 v147, 31, v146
	v_readlane_b32 s94, v254, 21
	v_cndmask_b32_e32 v145, v182, v145, vcc
	v_lshlrev_b32_e32 v168, 2, v145
	v_ashrrev_i32_e32 v145, 31, v144
	v_lshlrev_b64 v[170:171], 6, v[144:145]
	v_lshl_add_u64 v[170:171], v[138:139], 0, v[170:171]
	s_mov_b64 s[76:77], -1
	s_andn2_b64 vcc, exec, s[2:3]
	s_mov_b32 s42, 0x11808
	v_readlane_b32 s87, v254, 19
	v_readlane_b32 s95, v254, 22
	s_nop 0
	v_mov_b32_e32 v170, v192
	s_nop 0
	v_pk_mul_f32 v[128:129], v[128:129], v[170:171] op_sel_hi:[1,0]
	v_pk_mul_f32 v[126:127], v[126:127], v[170:171] op_sel_hi:[1,0]
	v_pk_mul_f32 v[122:123], v[122:123], v[170:171] op_sel_hi:[1,0]
	v_pk_mul_f32 v[124:125], v[124:125], v[170:171] op_sel_hi:[1,0]
	v_cvt_pk_bf16_f32 v126, v126, v127
	v_cvt_pk_bf16_f32 v127, v128, v129
	v_cvt_pk_bf16_f32 v128, v122, v123
	v_mov_b64_e32 v[122:123], s[74:75]
	v_cvt_pk_bf16_f32 v129, v124, v125
	v_mad_i64_i32 v[172:173], s[34:35], v144, s92, v[122:123]
	v_lshlrev_b64 v[124:125], 1, v[146:147]
	v_lshl_add_u64 v[146:147], v[172:173], 0, v[124:125]
	v_pk_mul_f32 v[118:119], v[118:119], v[170:171] op_sel_hi:[1,0]
	global_store_dwordx4 v[146:147], v[126:129], off
	v_pk_mul_f32 v[120:121], v[120:121], v[170:171] op_sel_hi:[1,0]
	s_nop 0
	v_pk_mul_f32 v[126:127], v[116:117], v[170:171] op_sel_hi:[1,0]
	v_pk_mul_f32 v[116:117], v[114:115], v[170:171] op_sel_hi:[1,0]
	v_cvt_pk_bf16_f32 v114, v118, v119
	v_or_b32_e32 v118, 16, v144
	v_cvt_pk_bf16_f32 v115, v120, v121
	v_ashrrev_i32_e32 v119, 31, v118
	v_cvt_pk_bf16_f32 v116, v116, v117
	v_cvt_pk_bf16_f32 v117, v126, v127
	global_store_dwordx4 v[146:147], v[114:117], off offset:64
	s_nop 1
	v_lshlrev_b64 v[114:115], 6, v[118:119]
	v_lshl_add_u64 v[114:115], v[138:139], 0, v[114:115]
	s_nop 0
	v_mov_b32_e32 v114, v196
	s_nop 0
	v_pk_mul_f32 v[110:111], v[110:111], v[114:115] op_sel_hi:[1,0]
	v_pk_mul_f32 v[116:117], v[108:109], v[114:115] op_sel_hi:[1,0]
	v_pk_mul_f32 v[108:109], v[106:107], v[114:115] op_sel_hi:[1,0]
	v_cvt_pk_bf16_f32 v106, v110, v111
	v_mad_i64_i32 v[110:111], s[34:35], v118, s92, v[122:123]
	v_pk_mul_f32 v[112:113], v[112:113], v[114:115] op_sel_hi:[1,0]
	v_lshl_add_u64 v[110:111], v[110:111], 0, v[124:125]
	v_cvt_pk_bf16_f32 v107, v112, v113
	v_pk_mul_f32 v[102:103], v[102:103], v[114:115] op_sel_hi:[1,0]
	v_cvt_pk_bf16_f32 v108, v108, v109
	v_cvt_pk_bf16_f32 v109, v116, v117
	global_store_dwordx4 v[110:111], v[106:109], off
	v_pk_mul_f32 v[104:105], v[104:105], v[114:115] op_sel_hi:[1,0]
	s_nop 0
	v_pk_mul_f32 v[106:107], v[100:101], v[114:115] op_sel_hi:[1,0]
; __device__ __forceinline__ unsigned cvt_pk_bf16(float lo, float hi) { unsigned r; asm volatile("v_cvt_pk_bf16_f32 %0, %1, %2" : "=v"(r) : "v"(lo), "v"(hi)); return r; }
;     __device__ __forceinline__ void operator()(const f32x4 (&acc)[2][2][4][2], const Unit& u, int wr, int wc, int fr, int fq) const {
;     ...
;             for (int m = 0; m < 4; ++m) {
;                 const int row = row0 + ai * HALF + m * 16; const float rs = row_rs4(ssq, row, fq);
; #pragma unroll
;                 for (int bj = 0; bj < 2; ++bj) {
;                     const f32x4 v0 = acc[ai][bj][m][0] * rs, v1 = acc[ai][bj][m][1] * rs;
;                     u32x4 w; w.x = cvt_pk_bf16(v0[0], v0[1]); w.y = cvt_pk_bf16(v0[2], v0[3]); w.z = cvt_pk_bf16(v1[0], v1[1]); w.w = cvt_pk_bf16(v1[2], v1[3]);
;                     *(u32x4*)(proj + (size_t)row * pitch + col0 + bj * 32) = w;
;                 }
	v_pk_mul_f32 v[100:101], v[98:99], v[114:115] op_sel_hi:[1,0]
	v_cvt_pk_bf16_f32 v98, v102, v103
	v_or_b32_e32 v102, 32, v144
	v_cvt_pk_bf16_f32 v99, v104, v105
	v_ashrrev_i32_e32 v103, 31, v102
	v_cvt_pk_bf16_f32 v100, v100, v101
	v_cvt_pk_bf16_f32 v101, v106, v107
	global_store_dwordx4 v[110:111], v[98:101], off offset:64
	s_nop 1
	v_lshlrev_b64 v[98:99], 6, v[102:103]
	v_lshl_add_u64 v[98:99], v[138:139], 0, v[98:99]
	s_nop 0
	v_mov_b32_e32 v98, v200
	s_nop 0
	v_pk_mul_f32 v[94:95], v[94:95], v[98:99] op_sel_hi:[1,0]
	v_pk_mul_f32 v[100:101], v[92:93], v[98:99] op_sel_hi:[1,0]
	v_pk_mul_f32 v[92:93], v[90:91], v[98:99] op_sel_hi:[1,0]
	v_cvt_pk_bf16_f32 v90, v94, v95
	v_mad_i64_i32 v[94:95], s[34:35], v102, s92, v[122:123]
	v_pk_mul_f32 v[96:97], v[96:97], v[98:99] op_sel_hi:[1,0]
	v_lshl_add_u64 v[94:95], v[94:95], 0, v[124:125]
	v_cvt_pk_bf16_f32 v91, v96, v97
	v_pk_mul_f32 v[86:87], v[86:87], v[98:99] op_sel_hi:[1,0]
	v_cvt_pk_bf16_f32 v92, v92, v93
	v_cvt_pk_bf16_f32 v93, v100, v101
	global_store_dwordx4 v[94:95], v[90:93], off
	v_pk_mul_f32 v[88:89], v[88:89], v[98:99] op_sel_hi:[1,0]
	s_nop 0
	v_pk_mul_f32 v[90:91], v[84:85], v[98:99] op_sel_hi:[1,0]
	v_pk_mul_f32 v[84:85], v[82:83], v[98:99] op_sel_hi:[1,0]
	v_cvt_pk_bf16_f32 v82, v86, v87
	v_or_b32_e32 v86, 48, v144
	v_cvt_pk_bf16_f32 v83, v88, v89
	v_ashrrev_i32_e32 v87, 31, v86
	v_cvt_pk_bf16_f32 v84, v84, v85
	v_cvt_pk_bf16_f32 v85, v90, v91
	global_store_dwordx4 v[94:95], v[82:85], off offset:64
	s_nop 1
	v_lshlrev_b64 v[82:83], 6, v[86:87]
	v_lshl_add_u64 v[82:83], v[138:139], 0, v[82:83]
	s_nop 0
	v_mov_b32_e32 v82, v204
	s_nop 0
	v_pk_mul_f32 v[78:79], v[78:79], v[82:83] op_sel_hi:[1,0]
	v_pk_mul_f32 v[84:85], v[76:77], v[82:83] op_sel_hi:[1,0]
	v_pk_mul_f32 v[76:77], v[74:75], v[82:83] op_sel_hi:[1,0]
	v_cvt_pk_bf16_f32 v74, v78, v79
	v_mad_i64_i32 v[78:79], s[34:35], v86, s92, v[122:123]
	v_pk_mul_f32 v[80:81], v[80:81], v[82:83] op_sel_hi:[1,0]
	v_lshl_add_u64 v[78:79], v[78:79], 0, v[124:125]
	v_cvt_pk_bf16_f32 v75, v80, v81
	v_pk_mul_f32 v[70:71], v[70:71], v[82:83] op_sel_hi:[1,0]
	v_cvt_pk_bf16_f32 v76, v76, v77
	v_cvt_pk_bf16_f32 v77, v84, v85
	global_store_dwordx4 v[78:79], v[74:77], off
	v_pk_mul_f32 v[72:73], v[72:73], v[82:83] op_sel_hi:[1,0]
	s_nop 0
	v_pk_mul_f32 v[74:75], v[68:69], v[82:83] op_sel_hi:[1,0]
	v_pk_mul_f32 v[68:69], v[66:67], v[82:83] op_sel_hi:[1,0]
	v_cvt_pk_bf16_f32 v66, v70, v71
	v_add_u32_e32 v70, 0x80, v144
	v_cvt_pk_bf16_f32 v67, v72, v73
	v_ashrrev_i32_e32 v71, 31, v70
	v_cvt_pk_bf16_f32 v68, v68, v69
	v_cvt_pk_bf16_f32 v69, v74, v75
	global_store_dwordx4 v[78:79], v[66:69], off offset:64
	s_nop 1
	v_lshlrev_b64 v[66:67], 6, v[70:71]
	v_lshl_add_u64 v[66:67], v[138:139], 0, v[66:67]
	s_nop 0
	v_mov_b32_e32 v66, v208
	s_nop 0
	v_pk_mul_f32 v[62:63], v[62:63], v[66:67] op_sel_hi:[1,0]
	v_pk_mul_f32 v[68:69], v[60:61], v[66:67] op_sel_hi:[1,0]
	v_pk_mul_f32 v[60:61], v[58:59], v[66:67] op_sel_hi:[1,0]
	v_cvt_pk_bf16_f32 v58, v62, v63
	v_mad_i64_i32 v[62:63], s[34:35], v70, s92, v[122:123]
	v_pk_mul_f32 v[64:65], v[64:65], v[66:67] op_sel_hi:[1,0]
	v_lshl_add_u64 v[62:63], v[62:63], 0, v[124:125]
	v_cvt_pk_bf16_f32 v59, v64, v65
	v_pk_mul_f32 v[54:55], v[54:55], v[66:67] op_sel_hi:[1,0]
	v_cvt_pk_bf16_f32 v60, v60, v61
	v_cvt_pk_bf16_f32 v61, v68, v69
	global_store_dwordx4 v[62:63], v[58:61], off
	v_pk_mul_f32 v[56:57], v[56:57], v[66:67] op_sel_hi:[1,0]
	s_nop 0
	v_pk_mul_f32 v[58:59], v[52:53], v[66:67] op_sel_hi:[1,0]
	v_pk_mul_f32 v[52:53], v[50:51], v[66:67] op_sel_hi:[1,0]
	v_cvt_pk_bf16_f32 v50, v54, v55
	v_add_u32_e32 v54, 0x90, v144
	v_cvt_pk_bf16_f32 v51, v56, v57
	v_ashrrev_i32_e32 v55, 31, v54
; __device__ __forceinline__ unsigned cvt_pk_bf16(float lo, float hi) { unsigned r; asm volatile("v_cvt_pk_bf16_f32 %0, %1, %2" : "=v"(r) : "v"(lo), "v"(hi)); return r; }
;     __device__ __forceinline__ void operator()(const f32x4 (&acc)[2][2][4][2], const Unit& u, int wr, int wc, int fr, int fq) const {
;     ...
;             for (int m = 0; m < 4; ++m) {
;                 const int row = row0 + ai * HALF + m * 16; const float rs = row_rs4(ssq, row, fq);
; #pragma unroll
;                 for (int bj = 0; bj < 2; ++bj) {
;                     const f32x4 v0 = acc[ai][bj][m][0] * rs, v1 = acc[ai][bj][m][1] * rs;
;                     u32x4 w; w.x = cvt_pk_bf16(v0[0], v0[1]); w.y = cvt_pk_bf16(v0[2], v0[3]); w.z = cvt_pk_bf16(v1[0], v1[1]); w.w = cvt_pk_bf16(v1[2], v1[3]);
;                     *(u32x4*)(proj + (size_t)row * pitch + col0 + bj * 32) = w;
;                 }
	v_cvt_pk_bf16_f32 v52, v52, v53
	v_cvt_pk_bf16_f32 v53, v58, v59
	global_store_dwordx4 v[62:63], v[50:53], off offset:64
	s_nop 1
	v_lshlrev_b64 v[50:51], 6, v[54:55]
	v_lshl_add_u64 v[50:51], v[138:139], 0, v[50:51]
	s_nop 0
	v_mov_b32_e32 v50, v212
	s_nop 0
	v_pk_mul_f32 v[46:47], v[46:47], v[50:51] op_sel_hi:[1,0]
	v_pk_mul_f32 v[52:53], v[44:45], v[50:51] op_sel_hi:[1,0]
	v_pk_mul_f32 v[44:45], v[42:43], v[50:51] op_sel_hi:[1,0]
	v_cvt_pk_bf16_f32 v42, v46, v47
	v_mad_i64_i32 v[46:47], s[34:35], v54, s92, v[122:123]
	v_pk_mul_f32 v[48:49], v[48:49], v[50:51] op_sel_hi:[1,0]
	v_lshl_add_u64 v[46:47], v[46:47], 0, v[124:125]
	v_cvt_pk_bf16_f32 v43, v48, v49
	v_pk_mul_f32 v[38:39], v[38:39], v[50:51] op_sel_hi:[1,0]
	v_cvt_pk_bf16_f32 v44, v44, v45
	v_cvt_pk_bf16_f32 v45, v52, v53
	global_store_dwordx4 v[46:47], v[42:45], off
	v_pk_mul_f32 v[40:41], v[40:41], v[50:51] op_sel_hi:[1,0]
	s_nop 0
	v_pk_mul_f32 v[42:43], v[36:37], v[50:51] op_sel_hi:[1,0]
	v_pk_mul_f32 v[36:37], v[34:35], v[50:51] op_sel_hi:[1,0]
	v_cvt_pk_bf16_f32 v34, v38, v39
	v_add_u32_e32 v38, 0xa0, v144
	v_cvt_pk_bf16_f32 v35, v40, v41
	v_ashrrev_i32_e32 v39, 31, v38
	v_cvt_pk_bf16_f32 v36, v36, v37
	v_cvt_pk_bf16_f32 v37, v42, v43
	global_store_dwordx4 v[46:47], v[34:37], off offset:64
	s_nop 1
	v_lshlrev_b64 v[34:35], 6, v[38:39]
	v_lshl_add_u64 v[34:35], v[138:139], 0, v[34:35]
	s_nop 0
	v_mov_b32_e32 v34, v216
	s_nop 0
	v_pk_mul_f32 v[30:31], v[30:31], v[34:35] op_sel_hi:[1,0]
	v_pk_mul_f32 v[36:37], v[28:29], v[34:35] op_sel_hi:[1,0]
	v_pk_mul_f32 v[28:29], v[26:27], v[34:35] op_sel_hi:[1,0]
	v_cvt_pk_bf16_f32 v26, v30, v31
	v_mad_i64_i32 v[30:31], s[34:35], v38, s92, v[122:123]
	v_pk_mul_f32 v[32:33], v[32:33], v[34:35] op_sel_hi:[1,0]
	v_lshl_add_u64 v[30:31], v[30:31], 0, v[124:125]
	v_cvt_pk_bf16_f32 v27, v32, v33
	v_pk_mul_f32 v[22:23], v[22:23], v[34:35] op_sel_hi:[1,0]
	v_cvt_pk_bf16_f32 v28, v28, v29
	v_cvt_pk_bf16_f32 v29, v36, v37
	global_store_dwordx4 v[30:31], v[26:29], off
	v_pk_mul_f32 v[24:25], v[24:25], v[34:35] op_sel_hi:[1,0]
	s_nop 0
	v_pk_mul_f32 v[26:27], v[20:21], v[34:35] op_sel_hi:[1,0]
	v_pk_mul_f32 v[20:21], v[18:19], v[34:35] op_sel_hi:[1,0]
	v_cvt_pk_bf16_f32 v18, v22, v23
	v_add_u32_e32 v22, 0xb0, v144
	v_cvt_pk_bf16_f32 v19, v24, v25
	v_ashrrev_i32_e32 v23, 31, v22
	v_cvt_pk_bf16_f32 v20, v20, v21
	v_cvt_pk_bf16_f32 v21, v26, v27
	global_store_dwordx4 v[30:31], v[18:21], off offset:64
	s_nop 1
	v_lshlrev_b64 v[18:19], 6, v[22:23]
	v_lshl_add_u64 v[18:19], v[138:139], 0, v[18:19]
	s_nop 0
	v_mov_b32_e32 v18, v220
	s_nop 0
	v_pk_mul_f32 v[14:15], v[14:15], v[18:19] op_sel_hi:[1,0]
	v_pk_mul_f32 v[20:21], v[12:13], v[18:19] op_sel_hi:[1,0]
	v_pk_mul_f32 v[12:13], v[10:11], v[18:19] op_sel_hi:[1,0]
	v_cvt_pk_bf16_f32 v10, v14, v15
	v_mad_i64_i32 v[14:15], s[34:35], v22, s92, v[122:123]
	v_pk_mul_f32 v[16:17], v[16:17], v[18:19] op_sel_hi:[1,0]
	v_lshl_add_u64 v[14:15], v[14:15], 0, v[124:125]
	v_cvt_pk_bf16_f32 v11, v16, v17
	v_cvt_pk_bf16_f32 v12, v12, v13
	v_cvt_pk_bf16_f32 v13, v20, v21
	global_store_dwordx4 v[14:15], v[10:13], off
	v_pk_mul_f32 v[8:9], v[8:9], v[18:19] op_sel_hi:[1,0]
	v_pk_mul_f32 v[6:7], v[6:7], v[18:19] op_sel_hi:[1,0]
	v_pk_mul_f32 v[10:11], v[4:5], v[18:19] op_sel_hi:[1,0]
	v_pk_mul_f32 v[4:5], v[2:3], v[18:19] op_sel_hi:[1,0]
	v_cvt_pk_bf16_f32 v2, v6, v7
	v_cvt_pk_bf16_f32 v3, v8, v9
	s_nop 0
	v_cvt_pk_bf16_f32 v4, v4, v5
	v_cvt_pk_bf16_f32 v5, v10, v11
	global_store_dwordx4 v[14:15], v[2:5], off offset:64
	s_cbranch_vccnz .LBB0_447
	v_readlane_b32 s2, v254, 27
	v_readlane_b32 s3, v254, 28
	s_andn2_b64 vcc, exec, s[2:3]
	s_cbranch_vccnz .LBB0_446
	s_barrier
	s_branch .LBB0_446

; #define LAS __attribute__((address_space(3)))
; __device__ __forceinline__ void attn_unit(LAS unsigned char* lds, bf16_t* proj, const float* biasG, const float* sink, int s, int qb, int kh, int hp, bf16_t* dummy = nullptr) {
;     ...
;             if (st < wq || st > wq + 8) continue;
;             f32x4 sa[2][2];
; #pragma unroll
;             for (int kt = 0; kt < 2; ++kt) { sa[kt][0] = (f32x4){0.f, 0.f, 0.f, 0.f}; sa[kt][1] = (f32x4){0.f, 0.f, 0.f, 0.f}; }
; #pragma unroll
;             for (int ks = 0; ks < 4; ++ks)
; #pragma unroll
;                 for (int kt = 0; kt < 2; ++kt) {
;                     const bf16x8 kf = *(const LAS bf16x8*)(Ks + (si * 32 + kt * 16 + l16) * 272 + ks * 64 + kg * 16);
;                     sa[kt][0] = __builtin_amdgcn_mfma_f32_16x16x32_bf16(kf, qf[0][ks], sa[kt][0], 0, 0, 0);
;                     sa[kt][1] = __builtin_amdgcn_mfma_f32_16x16x32_bf16(kf, qf[1][ks], sa[kt][1], 0, 0, 0);
;                 }
;             bf16x8 pf[2];
; #pragma unroll
;             for (int qt = 0; qt < 2; ++qt) {
;                 const int qp = wq * 32 + qt * 16 + l16;
;                 float sv[8]; float mx = -1e30f;
; #pragma unroll
;                 for (int kt = 0; kt < 2; ++kt)
; #pragma unroll
;                     for (int r = 0; r < 4; ++r) {
;                         const int kp = (kbi - 1) * 128 + si * 32 + kt * 16 + kg * 4 + r;
;                         const int rel = kp - qp; const bool valid = (rel >= -128) && (rel <= 128);
;                         const int idx = min(max(rel + 128, 0), 256);
;                         const float v = valid ? (sa[kt][qt][r] * SC + bL[hl * 260 + idx]) : -1e30f;
;                         sv[kt * 4 + r] = v; mx = fmaxf(mx, v);
;                     }
;                 mx = fmaxf(mx, __shfl_xor(mx, 16)); mx = fmaxf(mx, __shfl_xor(mx, 32));
;                 const float mnew = fmaxf(m2[qt], mx), alpha = __builtin_amdgcn_exp2f(m2[qt] - mnew); m2[qt] = mnew;
.LBB0_665:
	s_add_i32 s19, s30, -3
	v_cmp_ge_u32_e32 vcc, s19, v192
	v_cmp_le_u32_e64 s[4:5], s19, v195
	s_and_b64 s[4:5], vcc, s[4:5]
	s_and_saveexec_b64 s[74:75], s[4:5]
	s_cbranch_execz .LBB0_699
	v_add_u32_e32 v251, 0x11700, v200
	v_add_u32_e32 v251, v251, v196
	v_add_u32_e32 v252, 0x11700, v201
	v_add_u32_e32 v252, v252, v196
	ds_read_b32 v235, v252 offset:256
	ds_read_b32 v236, v252 offset:260
	ds_read_b32 v237, v252 offset:264
	ds_read_b32 v238, v252 offset:268
	ds_read_b32 v239, v252 offset:320
	ds_read_b32 v240, v252 offset:324
	ds_read_b32 v241, v252 offset:328
	ds_read_b32 v242, v252 offset:332
	ds_read_b32 v243, v251 offset:192
	ds_read_b32 v244, v251 offset:196
	ds_read_b32 v245, v251 offset:200
	ds_read_b32 v246, v251 offset:204
	ds_read_b32 v247, v252 offset:256
	ds_read_b32 v248, v252 offset:260
	ds_read_b32 v249, v252 offset:264
	ds_read_b32 v250, v252 offset:268
	ds_read_b128 v[132:135], v213
	ds_read_b128 v[226:229], v213 offset:64
	ds_read_b128 v[140:143], v213 offset:4352
	v_add_u32_e32 v1, 0xffffff8d, v199
	v_cmp_gt_u32_e32 vcc, s53, v1
	v_add3_u32 v2, v201, v196, s31
	s_waitcnt lgkmcnt(0)
	v_mfma_f32_16x16x32_bf16 v[136:139], v[132:135], v[4:7], 0
	v_mfma_f32_16x16x32_bf16 v[132:135], v[132:135], v[20:23], 0
	v_mfma_f32_16x16x32_bf16 v[136:139], v[226:229], v[8:11], v[136:139]
	v_mfma_f32_16x16x32_bf16 v[132:135], v[226:229], v[24:27], v[132:135]
	ds_read_b128 v[226:229], v213 offset:4416
	v_mfma_f32_16x16x32_bf16 v[144:147], v[140:143], v[4:7], 0
	v_mfma_f32_16x16x32_bf16 v[140:143], v[140:143], v[20:23], 0
	s_waitcnt lgkmcnt(0)
	v_mfma_f32_16x16x32_bf16 v[144:147], v[226:229], v[8:11], v[144:147]
	v_mfma_f32_16x16x32_bf16 v[140:143], v[226:229], v[24:27], v[140:143]
	ds_read_b128 v[226:229], v213 offset:128
	s_waitcnt lgkmcnt(0)
	v_mfma_f32_16x16x32_bf16 v[136:139], v[226:229], v[12:15], v[136:139]
	v_mfma_f32_16x16x32_bf16 v[132:135], v[226:229], v[28:31], v[132:135]
	ds_read_b128 v[226:229], v213 offset:4480
	s_waitcnt lgkmcnt(0)
	v_mfma_f32_16x16x32_bf16 v[230:233], v[226:229], v[12:15], v[144:147]
	v_mfma_f32_16x16x32_bf16 v[226:229], v[226:229], v[28:31], v[140:143]
	s_nop 2
	ds_read_b128 v[140:143], v213 offset:192
	s_waitcnt lgkmcnt(0)
	v_mfma_f32_16x16x32_bf16 v[144:147], v[140:143], v[16:19], v[136:139]
	s_nop 2
	ds_read_b128 v[136:139], v213 offset:4544
	v_mfma_f32_16x16x32_bf16 v[140:143], v[140:143], v[32:35], v[132:135]
	s_waitcnt lgkmcnt(0)
	v_mfma_f32_16x16x32_bf16 v[132:135], v[136:139], v[16:19], v[230:233]
	v_mfma_f32_16x16x32_bf16 v[136:139], v[136:139], v[32:35], v[226:229]
	s_nop 2
	v_mov_b32_e32 v228, 0xf149f2ca
	v_mov_b32_e32 v229, 0xf149f2ca
	s_waitcnt lgkmcnt(0)
	v_fmac_f32_e32 v235, 0x3e0293ee, v144
	v_cndmask_b32_e32 v229, v229, v235, vcc
	v_add_u32_e32 v1, 0xffffff8e, v199
	v_cmp_gt_u32_e64 s[4:5], s53, v1
	v_add3_u32 v225, v201, v196, s40
	v_fmac_f32_e32 v236, 0x3e0293ee, v145
	v_cndmask_b32_e64 v228, v228, v236, s[4:5]
	v_add_u32_e32 v1, 0xffffff8f, v199
	v_cmp_gt_u32_e64 s[6:7], s53, v1
	v_mov_b32_e32 v145, 0xf149f2ca
	v_add3_u32 v226, v201, v196, s42
	v_mov_b32_e32 v230, 0xf149f2ca
	v_fmac_f32_e32 v237, 0x3e0293ee, v146
	v_cndmask_b32_e64 v230, v230, v237, s[6:7]
	v_add_u32_e32 v1, 0xffffff90, v199
	v_cmp_gt_u32_e64 s[8:9], s53, v1
	v_add3_u32 v227, v201, v196, s96
	v_fmac_f32_e32 v238, 0x3e0293ee, v147
	v_cndmask_b32_e64 v145, v145, v238, s[8:9]
	v_add_u32_e32 v1, 0xffffff9d, v199
	v_cmp_gt_u32_e64 s[10:11], s53, v1
	v_mov_b32_e32 v232, 0xf149f2ca
	v_mov_b32_e32 v231, 0xf149f2ca
	v_fmac_f32_e32 v239, 0x3e0293ee, v132
	v_cndmask_b32_e64 v231, v231, v239, s[10:11]
	v_add_u32_e32 v1, 0xffffff9e, v199
	v_cmp_gt_u32_e64 s[10:11], s53, v1
	v_fmac_f32_e32 v240, 0x3e0293ee, v133
	s_nop 0
	v_cndmask_b32_e64 v232, v232, v240, s[10:11]
	v_add_u32_e32 v1, 0xffffff9f, v199
	v_cmp_gt_u32_e64 s[10:11], s53, v1
	v_mov_b32_e32 v132, 0xf149f2ca
	v_mov_b32_e32 v133, 0xf149f2ca
	v_fmac_f32_e32 v241, 0x3e0293ee, v134
	v_cndmask_b32_e64 v133, v133, v241, s[10:11]
	v_add_u32_e32 v1, 0xffffffa0, v199
	v_cmp_gt_u32_e64 s[10:11], s53, v1
	v_fmac_f32_e32 v242, 0x3e0293ee, v135
	s_nop 0
	v_cndmask_b32_e64 v132, v132, v242, s[10:11]
	v_mov_b32_e32 v144, 0xf149f2ca
	v_and_b32_e32 v134, 64, v182
	v_max3_f32 v1, v229, v144, v228
	v_xor_b32_e32 v3, 16, v182
	v_add_u32_e32 v134, 64, v134
	v_max3_f32 v1, v1, v230, v145
	v_cmp_lt_i32_e64 s[10:11], v3, v134
	v_max3_f32 v1, v1, v231, v232
	v_max3_f32 v1, v1, v133, v132
	v_cndmask_b32_e64 v3, v182, v3, s[10:11]
	v_lshlrev_b32_e32 v146, 2, v3
	ds_bpermute_b32 v135, v146, v1
	v_xor_b32_e32 v3, 32, v182
	v_cmp_lt_i32_e64 s[10:11], v3, v134
	s_waitcnt lgkmcnt(0)
	v_max_f32_e32 v134, v135, v135
	v_cndmask_b32_e64 v3, v182, v3, s[10:11]
	v_lshlrev_b32_e32 v3, 2, v3
	v_max_f32_e32 v1, v1, v134
	ds_bpermute_b32 v134, v3, v1
	s_waitcnt lgkmcnt(0)
; __device__ __forceinline__ unsigned cvt_pk_bf16(float lo, float hi) { unsigned r; asm volatile("v_cvt_pk_bf16_f32 %0, %1, %2" : "=v"(r) : "v"(lo), "v"(hi)); return r; }
; __device__ __forceinline__ void attn_unit(LAS unsigned char* lds, bf16_t* proj, const float* biasG, const float* sink, int s, int qb, int kh, int hp, bf16_t* dummy = nullptr) {
;     ...
;                         const float v = valid ? (sa[kt][qt][r] * SC + bL[hl * 260 + idx]) : -1e30f;
;                         sv[kt * 4 + r] = v; mx = fmaxf(mx, v);
;                     }
;                 mx = fmaxf(mx, __shfl_xor(mx, 16)); mx = fmaxf(mx, __shfl_xor(mx, 32));
;                 const float mnew = fmaxf(m2[qt], mx), alpha = __builtin_amdgcn_exp2f(m2[qt] - mnew); m2[qt] = mnew;
;                 float ps = 0.f; float pv[8];
; #pragma unroll
;                 for (int i = 0; i < 8; ++i) { pv[i] = __builtin_amdgcn_exp2f(sv[i] - mnew); ps += pv[i]; }
;                 lsum[qt] = lsum[qt] * alpha + ps;
; #pragma unroll
;                 for (int dt = 0; dt < 8; ++dt) o[dt][qt] = o[dt][qt] * alpha;
;                 u32x4 pw; pw.x = cvt_pk_bf16(pv[0], pv[1]); pw.y = cvt_pk_bf16(pv[2], pv[3]); pw.z = cvt_pk_bf16(pv[4], pv[5]); pw.w = cvt_pk_bf16(pv[6], pv[7]);
;                 pf[qt] = __builtin_bit_cast(bf16x8, pw);
	v_max3_f32 v1, v224, v1, v134
	v_sub_f32_e32 v134, v229, v1
	v_exp_f32_e32 v147, v134
	v_sub_f32_e32 v134, v228, v1
	v_exp_f32_e32 v228, v134
	v_sub_f32_e32 v134, v230, v1
	v_exp_f32_e32 v229, v134
	v_sub_f32_e32 v134, v145, v1
	v_exp_f32_e32 v230, v134
	v_sub_f32_e32 v134, v231, v1
	v_exp_f32_e32 v231, v134
	v_sub_f32_e32 v134, v232, v1
	v_sub_f32_e32 v133, v133, v1
	v_sub_f32_e32 v132, v132, v1
	v_exp_f32_e32 v232, v134
	v_exp_f32_e32 v233, v133
	v_exp_f32_e32 v234, v132
	v_add_u32_e32 v145, 0xffffff7d, v199
	v_cmp_gt_u32_e64 s[10:11], s53, v145
	v_mov_b32_e32 v145, 0xf149f2ca
	v_cvt_pk_bf16_f32 v132, v147, v228
	v_cvt_pk_bf16_f32 v133, v229, v230
	v_cvt_pk_bf16_f32 v134, v231, v232
	v_cvt_pk_bf16_f32 v135, v233, v234
	v_fmac_f32_e32 v243, 0x3e0293ee, v140
	v_cndmask_b32_e64 v145, v145, v243, s[10:11]
	v_add_u32_e32 v140, 0xffffff7e, v199
	v_cmp_gt_u32_e64 s[10:11], s53, v140
	v_fmac_f32_e32 v244, 0x3e0293ee, v141
	s_nop 0
	v_cndmask_b32_e64 v144, v144, v244, s[10:11]
	v_add_u32_e32 v140, 0xffffff7f, v199
	v_cmp_gt_u32_e64 s[10:11], s53, v140
	v_mov_b32_e32 v140, 0xf149f2ca
	v_mov_b32_e32 v141, 0xf149f2ca
	v_fmac_f32_e32 v245, 0x3e0293ee, v142
	v_cndmask_b32_e64 v141, v141, v245, s[10:11]
	v_add_u32_e32 v142, 0xffffff80, v199
	v_cmp_gt_u32_e64 s[10:11], s53, v142
	v_fmac_f32_e32 v246, 0x3e0293ee, v143
	s_nop 0
	v_cndmask_b32_e64 v140, v140, v246, s[10:11]
	v_mov_b32_e32 v142, 0xf149f2ca
	v_mov_b32_e32 v143, 0xf149f2ca
	v_fmac_f32_e32 v247, 0x3e0293ee, v136
	v_cndmask_b32_e32 v143, v143, v247, vcc
	v_fmac_f32_e32 v248, 0x3e0293ee, v137
	v_cndmask_b32_e64 v142, v142, v248, s[4:5]
	v_mov_b32_e32 v136, 0xf149f2ca
	v_mov_b32_e32 v137, 0xf149f2ca
	v_fmac_f32_e32 v249, 0x3e0293ee, v138
	v_cndmask_b32_e64 v137, v137, v249, s[6:7]
	v_fmac_f32_e32 v250, 0x3e0293ee, v139
	v_cndmask_b32_e64 v136, v136, v250, s[8:9]
	v_max3_f32 v2, v145, s89, v144
	v_max3_f32 v2, v2, v141, v140
	v_max3_f32 v139, v2, v143, v142
	v_add_f32_e32 v2, 0, v147
	v_add_f32_e32 v2, v228, v2
	v_add_f32_e32 v2, v229, v2
	v_sub_f32_e32 v138, v224, v1
	v_add_f32_e32 v2, v230, v2
	v_add_f32_e32 v2, v231, v2
	v_exp_f32_e32 v138, v138
	v_add_f32_e32 v2, v232, v2
	v_add_f32_e32 v2, v233, v2
	v_add_f32_e32 v2, v234, v2
	v_fmac_f32_e32 v2, v223, v138
	v_pk_mul_f32 v[98:99], v[98:99], v[138:139] op_sel_hi:[1,0]
	v_pk_mul_f32 v[96:97], v[96:97], v[138:139] op_sel_hi:[1,0]
	v_pk_mul_f32 v[106:107], v[106:107], v[138:139] op_sel_hi:[1,0]
	v_pk_mul_f32 v[104:105], v[104:105], v[138:139] op_sel_hi:[1,0]
	v_pk_mul_f32 v[110:111], v[110:111], v[138:139] op_sel_hi:[1,0]
	v_pk_mul_f32 v[108:109], v[108:109], v[138:139] op_sel_hi:[1,0]
	v_pk_mul_f32 v[114:115], v[114:115], v[138:139] op_sel_hi:[1,0]
	v_pk_mul_f32 v[112:113], v[112:113], v[138:139] op_sel_hi:[1,0]
	v_pk_mul_f32 v[118:119], v[118:119], v[138:139] op_sel_hi:[1,0]
	v_pk_mul_f32 v[116:117], v[116:117], v[138:139] op_sel_hi:[1,0]
	v_pk_mul_f32 v[122:123], v[122:123], v[138:139] op_sel_hi:[1,0]
	v_pk_mul_f32 v[120:121], v[120:121], v[138:139] op_sel_hi:[1,0]
	v_pk_mul_f32 v[126:127], v[126:127], v[138:139] op_sel_hi:[1,0]
	v_pk_mul_f32 v[124:125], v[124:125], v[138:139] op_sel_hi:[1,0]
	v_pk_mul_f32 v[130:131], v[130:131], v[138:139] op_sel_hi:[1,0]
	v_pk_mul_f32 v[128:129], v[128:129], v[138:139] op_sel_hi:[1,0]
	v_max3_f32 v138, v139, v137, v136
	ds_bpermute_b32 v139, v146, v138
	v_mov_b32_e32 v223, v2
	v_mov_b32_e32 v224, v1
	s_waitcnt lgkmcnt(0)
	v_max_f32_e32 v139, v139, v139
	v_max_f32_e32 v138, v138, v139
	ds_bpermute_b32 v3, v3, v138
	s_waitcnt lgkmcnt(0)
	v_max3_f32 v3, v222, v138, v3
	v_sub_f32_e32 v139, v145, v3
	v_exp_f32_e32 v139, v139
	v_sub_f32_e32 v144, v144, v3
	v_exp_f32_e32 v144, v144
	v_sub_f32_e32 v141, v141, v3
	v_exp_f32_e32 v141, v141
	v_sub_f32_e32 v140, v140, v3
	v_exp_f32_e32 v146, v140
	v_add_f32_e32 v145, 0, v139
	v_sub_f32_e32 v143, v143, v3
	v_add_f32_e32 v145, v144, v145
	v_exp_f32_e32 v143, v143
	v_sub_f32_e32 v142, v142, v3
	v_add_f32_e32 v145, v141, v145
	v_exp_f32_e32 v142, v142
	v_sub_f32_e32 v137, v137, v3
	v_add_f32_e32 v140, v146, v145
	v_exp_f32_e32 v145, v137
	v_sub_f32_e32 v136, v136, v3
	v_sub_f32_e32 v138, v222, v3
	v_exp_f32_e32 v147, v136
	v_add_f32_e32 v140, v143, v140
	v_exp_f32_e32 v136, v138
	v_add_f32_e32 v140, v142, v140
	v_add_f32_e32 v137, v145, v140
	v_add_f32_e32 v140, v147, v137
	v_fmac_f32_e32 v140, v221, v136
	v_pk_mul_f32 v[70:71], v[70:71], v[136:137] op_sel_hi:[1,0]
	v_pk_mul_f32 v[68:69], v[68:69], v[136:137] op_sel_hi:[1,0]
	v_pk_mul_f32 v[74:75], v[74:75], v[136:137] op_sel_hi:[1,0]
	v_pk_mul_f32 v[72:73], v[72:73], v[136:137] op_sel_hi:[1,0]
	v_pk_mul_f32 v[78:79], v[78:79], v[136:137] op_sel_hi:[1,0]
	v_pk_mul_f32 v[76:77], v[76:77], v[136:137] op_sel_hi:[1,0]
	v_pk_mul_f32 v[82:83], v[82:83], v[136:137] op_sel_hi:[1,0]
	v_pk_mul_f32 v[80:81], v[80:81], v[136:137] op_sel_hi:[1,0]
	v_pk_mul_f32 v[86:87], v[86:87], v[136:137] op_sel_hi:[1,0]
	v_pk_mul_f32 v[84:85], v[84:85], v[136:137] op_sel_hi:[1,0]
	v_pk_mul_f32 v[90:91], v[90:91], v[136:137] op_sel_hi:[1,0]
	v_pk_mul_f32 v[88:89], v[88:89], v[136:137] op_sel_hi:[1,0]
	v_pk_mul_f32 v[94:95], v[94:95], v[136:137] op_sel_hi:[1,0]
	v_pk_mul_f32 v[92:93], v[92:93], v[136:137] op_sel_hi:[1,0]
	v_pk_mul_f32 v[102:103], v[102:103], v[136:137] op_sel_hi:[1,0]
	v_pk_mul_f32 v[100:101], v[100:101], v[136:137] op_sel_hi:[1,0]
	v_cvt_pk_bf16_f32 v136, v139, v144
	v_cvt_pk_bf16_f32 v137, v141, v146
	v_add_u32_e32 v141, v197, v198
	v_cvt_pk_bf16_f32 v138, v143, v142
	v_add_u32_e32 v142, 0x8800, v141
	v_cvt_pk_bf16_f32 v139, v145, v147
	ds_read2_b64 v[236:239], v142 offset1:4
	v_mov_b32_e32 v221, v140
	v_add_u32_e32 v252, 0x9800, v141
	ds_read2_b64 v[240:243], v252 offset0:64 offset1:68
	v_add_u32_e32 v252, 0xa800, v141
	ds_read2_b64 v[244:247], v252 offset0:128 offset1:132
	v_add_u32_e32 v252, 0xb800, v141
	ds_read2_b64 v[248:251], v252 offset0:192 offset1:196
	s_waitcnt lgkmcnt(3)
; #define LAS __attribute__((address_space(3)))
; __device__ __forceinline__ void attn_unit(LAS unsigned char* lds, bf16_t* proj, const float* biasG, const float* sink, int s, int qb, int kh, int hp, bf16_t* dummy = nullptr) {
;     ...
;             if (st < wq || st > wq + 8) continue;
;             f32x4 sa[2][2];
; #pragma unroll
;             for (int kt = 0; kt < 2; ++kt) { sa[kt][0] = (f32x4){0.f, 0.f, 0.f, 0.f}; sa[kt][1] = (f32x4){0.f, 0.f, 0.f, 0.f}; }
; #pragma unroll
;             for (int ks = 0; ks < 4; ++ks)
; #pragma unroll
;                 for (int kt = 0; kt < 2; ++kt) {
;                     const bf16x8 kf = *(const LAS bf16x8*)(Ks + (si * 32 + kt * 16 + l16) * 272 + ks * 64 + kg * 16);
;                     sa[kt][0] = __builtin_amdgcn_mfma_f32_16x16x32_bf16(kf, qf[0][ks], sa[kt][0], 0, 0, 0);
;                     sa[kt][1] = __builtin_amdgcn_mfma_f32_16x16x32_bf16(kf, qf[1][ks], sa[kt][1], 0, 0, 0);
;                 }
;             bf16x8 pf[2];
; #pragma unroll
;             for (int qt = 0; qt < 2; ++qt) {
;                 const int qp = wq * 32 + qt * 16 + l16;
;                 float sv[8]; float mx = -1e30f;
; #pragma unroll
;                 for (int kt = 0; kt < 2; ++kt)
; #pragma unroll
;                     for (int r = 0; r < 4; ++r) {
;                         const int kp = (kbi - 1) * 128 + si * 32 + kt * 16 + kg * 4 + r;
;                         const int rel = kp - qp; const bool valid = (rel >= -128) && (rel <= 128);
;                         const int idx = min(max(rel + 128, 0), 256);
;                         const float v = valid ? (sa[kt][qt][r] * SC + bL[hl * 260 + idx]) : -1e30f;
;     ...
; #pragma unroll
;             for (int dt = 0; dt < 8; ++dt) {
;                 const LAS unsigned char* vr = Vt + (dt * 16 + l16) * 288 + (si * 32 + kg * 4) * 2;
;                 const u32x2 lo = *(const LAS u32x2*)(vr), hi = *(const LAS u32x2*)(vr + 32);
;                 u32x4 vw; vw.x = lo.x; vw.y = lo.y; vw.z = hi.x; vw.w = hi.y;
;                 const bf16x8 vf = __builtin_bit_cast(bf16x8, vw);
;                 o[dt][0] = __builtin_amdgcn_mfma_f32_16x16x32_bf16(vf, pf[0], o[dt][0], 0, 0, 0);
;                 o[dt][1] = __builtin_amdgcn_mfma_f32_16x16x32_bf16(vf, pf[1], o[dt][1], 0, 0, 0);
;             }
	v_mfma_f32_16x16x32_bf16 v[96:99], v[236:239], v[132:135], v[96:99]
	v_mov_b32_e32 v222, v3
	v_mfma_f32_16x16x32_bf16 v[68:71], v[236:239], v[136:139], v[68:71]
	v_add_u32_e32 v252, 0xd000, v141
	ds_read2_b64 v[236:239], v252 offset1:4
	s_waitcnt lgkmcnt(3)
	v_mfma_f32_16x16x32_bf16 v[104:107], v[240:243], v[132:135], v[104:107]
	v_mfma_f32_16x16x32_bf16 v[72:75], v[240:243], v[136:139], v[72:75]
	v_add_u32_e32 v252, 0xe000, v141
	ds_read2_b64 v[240:243], v252 offset0:64 offset1:68
	v_add_u32_e32 v141, 0xf000, v141
	s_waitcnt lgkmcnt(3)
	v_mfma_f32_16x16x32_bf16 v[108:111], v[244:247], v[132:135], v[108:111]
	v_mfma_f32_16x16x32_bf16 v[76:79], v[244:247], v[136:139], v[76:79]
	ds_read2_b64 v[244:247], v141 offset0:128 offset1:132
	s_waitcnt lgkmcnt(3)
	v_mfma_f32_16x16x32_bf16 v[112:115], v[248:251], v[132:135], v[112:115]
	v_mfma_f32_16x16x32_bf16 v[80:83], v[248:251], v[136:139], v[80:83]
	ds_read2_b64 v[248:251], v214 offset0:192 offset1:196
	s_waitcnt lgkmcnt(3)
	v_mfma_f32_16x16x32_bf16 v[116:119], v[236:239], v[132:135], v[116:119]
	v_mfma_f32_16x16x32_bf16 v[84:87], v[236:239], v[136:139], v[84:87]
	s_waitcnt lgkmcnt(2)
	v_mfma_f32_16x16x32_bf16 v[120:123], v[240:243], v[132:135], v[120:123]
	v_mfma_f32_16x16x32_bf16 v[88:91], v[240:243], v[136:139], v[88:91]
	s_waitcnt lgkmcnt(1)
	v_mfma_f32_16x16x32_bf16 v[124:127], v[244:247], v[132:135], v[124:127]
	v_mfma_f32_16x16x32_bf16 v[92:95], v[244:247], v[136:139], v[92:95]
	s_waitcnt lgkmcnt(0)
	v_mfma_f32_16x16x32_bf16 v[128:131], v[248:251], v[132:135], v[128:131]
	v_mfma_f32_16x16x32_bf16 v[100:103], v[248:251], v[136:139], v[100:103]
.LBB0_699:
	s_or_b64 exec, exec, s[74:75]
	s_add_i32 s4, s30, -2
	v_cmp_ge_u32_e32 vcc, s4, v192
	v_cmp_lt_u32_e64 s[4:5], s19, v195
	s_and_b64 s[4:5], vcc, s[4:5]
	s_and_saveexec_b64 s[74:75], s[4:5]
	s_cbranch_execz .LBB0_733
	v_add_u32_e32 v251, 0x11700, v201
	v_add_u32_e32 v251, v251, v196
	ds_read_b32 v235, v251 offset:384
	ds_read_b32 v236, v251 offset:388
	ds_read_b32 v237, v251 offset:392
	ds_read_b32 v238, v251 offset:396
	ds_read_b32 v239, v251 offset:448
	ds_read_b32 v240, v251 offset:452
	ds_read_b32 v241, v251 offset:456
	ds_read_b32 v242, v251 offset:460
	ds_read_b32 v243, v251 offset:320
	ds_read_b32 v244, v251 offset:324
	ds_read_b32 v245, v251 offset:328
	ds_read_b32 v246, v251 offset:332
	ds_read_b32 v247, v251 offset:384
	ds_read_b32 v248, v251 offset:388
	ds_read_b32 v249, v251 offset:392
	ds_read_b32 v250, v251 offset:396
	ds_read_b128 v[132:135], v210
	ds_read_b128 v[226:229], v210 offset:64
	ds_read_b128 v[140:143], v213 offset:13056
	v_add_u32_e32 v1, 0xffffffad, v199
	v_cmp_gt_u32_e32 vcc, s53, v1
	v_add3_u32 v2, v201, v196, s88
	s_waitcnt lgkmcnt(0)
	v_mfma_f32_16x16x32_bf16 v[136:139], v[132:135], v[4:7], 0
	v_mfma_f32_16x16x32_bf16 v[132:135], v[132:135], v[20:23], 0
	v_mfma_f32_16x16x32_bf16 v[136:139], v[226:229], v[8:11], v[136:139]
	v_mfma_f32_16x16x32_bf16 v[132:135], v[226:229], v[24:27], v[132:135]
	ds_read_b128 v[226:229], v213 offset:13120
	v_mfma_f32_16x16x32_bf16 v[144:147], v[140:143], v[4:7], 0
	v_mfma_f32_16x16x32_bf16 v[140:143], v[140:143], v[20:23], 0
	s_waitcnt lgkmcnt(0)
	v_mfma_f32_16x16x32_bf16 v[144:147], v[226:229], v[8:11], v[144:147]
	v_mfma_f32_16x16x32_bf16 v[140:143], v[226:229], v[24:27], v[140:143]
	ds_read_b128 v[226:229], v210 offset:128
	s_waitcnt lgkmcnt(0)
	v_mfma_f32_16x16x32_bf16 v[136:139], v[226:229], v[12:15], v[136:139]
	v_mfma_f32_16x16x32_bf16 v[132:135], v[226:229], v[28:31], v[132:135]
	ds_read_b128 v[226:229], v213 offset:13184
	s_waitcnt lgkmcnt(0)
	v_mfma_f32_16x16x32_bf16 v[230:233], v[226:229], v[12:15], v[144:147]
	v_mfma_f32_16x16x32_bf16 v[226:229], v[226:229], v[28:31], v[140:143]
	s_nop 2
	ds_read_b128 v[140:143], v210 offset:192
	s_waitcnt lgkmcnt(0)
	v_mfma_f32_16x16x32_bf16 v[144:147], v[140:143], v[16:19], v[136:139]
	s_nop 2
	ds_read_b128 v[136:139], v213 offset:13248
	v_mfma_f32_16x16x32_bf16 v[140:143], v[140:143], v[32:35], v[132:135]
	s_waitcnt lgkmcnt(0)
	v_mfma_f32_16x16x32_bf16 v[132:135], v[136:139], v[16:19], v[230:233]
	v_mfma_f32_16x16x32_bf16 v[136:139], v[136:139], v[32:35], v[226:229]
	s_nop 2
	v_mov_b32_e32 v228, 0xf149f2ca
	v_mov_b32_e32 v229, 0xf149f2ca
	s_waitcnt lgkmcnt(0)
	v_fmac_f32_e32 v235, 0x3e0293ee, v144
	v_cndmask_b32_e32 v229, v229, v235, vcc
	v_add_u32_e32 v1, 0xffffffae, v199
	v_cmp_gt_u32_e64 s[4:5], s53, v1
	v_add3_u32 v225, v201, v196, s55
	v_fmac_f32_e32 v236, 0x3e0293ee, v145
	v_cndmask_b32_e64 v228, v228, v236, s[4:5]
	v_add_u32_e32 v1, 0xffffffaf, v199
	v_cmp_gt_u32_e64 s[6:7], s53, v1
	v_mov_b32_e32 v145, 0xf149f2ca
	v_add3_u32 v226, v201, v196, s59
	v_mov_b32_e32 v230, 0xf149f2ca
	v_fmac_f32_e32 v237, 0x3e0293ee, v146
	v_cndmask_b32_e64 v230, v230, v237, s[6:7]
	v_add_u32_e32 v1, 0xffffffb0, v199
	v_cmp_gt_u32_e64 s[8:9], s53, v1
	v_add3_u32 v227, v201, v196, s43
	v_fmac_f32_e32 v238, 0x3e0293ee, v147
	v_cndmask_b32_e64 v145, v145, v238, s[8:9]
	v_add_u32_e32 v1, 0xffffffbd, v199
	v_cmp_gt_u32_e64 s[10:11], s53, v1
	v_mov_b32_e32 v232, 0xf149f2ca
	v_mov_b32_e32 v231, 0xf149f2ca
	v_fmac_f32_e32 v239, 0x3e0293ee, v132
	v_cndmask_b32_e64 v231, v231, v239, s[10:11]
	v_add_u32_e32 v1, 0xffffffbe, v199
	v_cmp_gt_u32_e64 s[10:11], s53, v1
	v_fmac_f32_e32 v240, 0x3e0293ee, v133
	s_nop 0
	v_cndmask_b32_e64 v232, v232, v240, s[10:11]
	v_add_u32_e32 v1, 0xffffffbf, v199
	v_cmp_gt_u32_e64 s[10:11], s53, v1
	v_mov_b32_e32 v132, 0xf149f2ca
	v_mov_b32_e32 v133, 0xf149f2ca
	v_fmac_f32_e32 v241, 0x3e0293ee, v134
	v_cndmask_b32_e64 v133, v133, v241, s[10:11]
	v_subrev_u32_e32 v1, 64, v199
	v_cmp_gt_u32_e64 s[10:11], s53, v1
	v_fmac_f32_e32 v242, 0x3e0293ee, v135
	s_nop 0
	v_cndmask_b32_e64 v132, v132, v242, s[10:11]
	v_mov_b32_e32 v144, 0xf149f2ca
	v_and_b32_e32 v134, 64, v182
	v_max3_f32 v1, v229, v144, v228
	v_xor_b32_e32 v3, 16, v182
	v_add_u32_e32 v134, 64, v134
	v_max3_f32 v1, v1, v230, v145
	v_cmp_lt_i32_e64 s[10:11], v3, v134
	v_max3_f32 v1, v1, v231, v232
	v_max3_f32 v1, v1, v133, v132
	v_cndmask_b32_e64 v3, v182, v3, s[10:11]
	v_lshlrev_b32_e32 v146, 2, v3
	ds_bpermute_b32 v135, v146, v1
	v_xor_b32_e32 v3, 32, v182
	v_cmp_lt_i32_e64 s[10:11], v3, v134
	s_waitcnt lgkmcnt(0)
; __device__ __forceinline__ unsigned cvt_pk_bf16(float lo, float hi) { unsigned r; asm volatile("v_cvt_pk_bf16_f32 %0, %1, %2" : "=v"(r) : "v"(lo), "v"(hi)); return r; }
; __device__ __forceinline__ void attn_unit(LAS unsigned char* lds, bf16_t* proj, const float* biasG, const float* sink, int s, int qb, int kh, int hp, bf16_t* dummy = nullptr) {
;     ...
;                         const float v = valid ? (sa[kt][qt][r] * SC + bL[hl * 260 + idx]) : -1e30f;
;                         sv[kt * 4 + r] = v; mx = fmaxf(mx, v);
;                     }
;                 mx = fmaxf(mx, __shfl_xor(mx, 16)); mx = fmaxf(mx, __shfl_xor(mx, 32));
;                 const float mnew = fmaxf(m2[qt], mx), alpha = __builtin_amdgcn_exp2f(m2[qt] - mnew); m2[qt] = mnew;
;                 float ps = 0.f; float pv[8];
; #pragma unroll
;                 for (int i = 0; i < 8; ++i) { pv[i] = __builtin_amdgcn_exp2f(sv[i] - mnew); ps += pv[i]; }
;                 lsum[qt] = lsum[qt] * alpha + ps;
; #pragma unroll
;                 for (int dt = 0; dt < 8; ++dt) o[dt][qt] = o[dt][qt] * alpha;
;                 u32x4 pw; pw.x = cvt_pk_bf16(pv[0], pv[1]); pw.y = cvt_pk_bf16(pv[2], pv[3]); pw.z = cvt_pk_bf16(pv[4], pv[5]); pw.w = cvt_pk_bf16(pv[6], pv[7]);
;                 pf[qt] = __builtin_bit_cast(bf16x8, pw);
	v_max_f32_e32 v134, v135, v135
	v_cndmask_b32_e64 v3, v182, v3, s[10:11]
	v_lshlrev_b32_e32 v3, 2, v3
	v_max_f32_e32 v1, v1, v134
	ds_bpermute_b32 v134, v3, v1
	s_waitcnt lgkmcnt(0)
	v_max3_f32 v1, v224, v1, v134
	v_sub_f32_e32 v134, v229, v1
	v_exp_f32_e32 v147, v134
	v_sub_f32_e32 v134, v228, v1
	v_exp_f32_e32 v228, v134
	v_sub_f32_e32 v134, v230, v1
	v_exp_f32_e32 v229, v134
	v_sub_f32_e32 v134, v145, v1
	v_exp_f32_e32 v230, v134
	v_sub_f32_e32 v134, v231, v1
	v_exp_f32_e32 v231, v134
	v_sub_f32_e32 v134, v232, v1
	v_sub_f32_e32 v133, v133, v1
	v_sub_f32_e32 v132, v132, v1
	v_exp_f32_e32 v232, v134
	v_exp_f32_e32 v233, v133
	v_exp_f32_e32 v234, v132
	v_add_u32_e32 v145, 0xffffff9d, v199
	v_cmp_gt_u32_e64 s[10:11], s53, v145
	v_mov_b32_e32 v145, 0xf149f2ca
	v_cvt_pk_bf16_f32 v132, v147, v228
	v_cvt_pk_bf16_f32 v133, v229, v230
	v_cvt_pk_bf16_f32 v134, v231, v232
	v_cvt_pk_bf16_f32 v135, v233, v234
	v_fmac_f32_e32 v243, 0x3e0293ee, v140
	v_cndmask_b32_e64 v145, v145, v243, s[10:11]
	v_add_u32_e32 v140, 0xffffff9e, v199
	v_cmp_gt_u32_e64 s[10:11], s53, v140
	v_fmac_f32_e32 v244, 0x3e0293ee, v141
	s_nop 0
	v_cndmask_b32_e64 v144, v144, v244, s[10:11]
	v_add_u32_e32 v140, 0xffffff9f, v199
	v_cmp_gt_u32_e64 s[10:11], s53, v140
	v_mov_b32_e32 v140, 0xf149f2ca
	v_mov_b32_e32 v141, 0xf149f2ca
	v_fmac_f32_e32 v245, 0x3e0293ee, v142
	v_cndmask_b32_e64 v141, v141, v245, s[10:11]
	v_add_u32_e32 v142, 0xffffffa0, v199
	v_cmp_gt_u32_e64 s[10:11], s53, v142
	v_fmac_f32_e32 v246, 0x3e0293ee, v143
	s_nop 0
	v_cndmask_b32_e64 v140, v140, v246, s[10:11]
	v_mov_b32_e32 v142, 0xf149f2ca
	v_mov_b32_e32 v143, 0xf149f2ca
	v_fmac_f32_e32 v247, 0x3e0293ee, v136
	v_cndmask_b32_e32 v143, v143, v247, vcc
	v_fmac_f32_e32 v248, 0x3e0293ee, v137
	v_cndmask_b32_e64 v142, v142, v248, s[4:5]
	v_mov_b32_e32 v136, 0xf149f2ca
	v_mov_b32_e32 v137, 0xf149f2ca
	v_fmac_f32_e32 v249, 0x3e0293ee, v138
	v_cndmask_b32_e64 v137, v137, v249, s[6:7]
	v_fmac_f32_e32 v250, 0x3e0293ee, v139
	v_cndmask_b32_e64 v136, v136, v250, s[8:9]
	v_max3_f32 v2, v145, s89, v144
	v_max3_f32 v2, v2, v141, v140
	v_max3_f32 v139, v2, v143, v142
	v_add_f32_e32 v2, 0, v147
	v_add_f32_e32 v2, v228, v2
	v_add_f32_e32 v2, v229, v2
	v_sub_f32_e32 v138, v224, v1
	v_add_f32_e32 v2, v230, v2
	v_add_f32_e32 v2, v231, v2
	v_exp_f32_e32 v138, v138
	v_add_f32_e32 v2, v232, v2
	v_add_f32_e32 v2, v233, v2
	v_add_f32_e32 v2, v234, v2
	v_fmac_f32_e32 v2, v223, v138
	v_pk_mul_f32 v[98:99], v[98:99], v[138:139] op_sel_hi:[1,0]
	v_pk_mul_f32 v[96:97], v[96:97], v[138:139] op_sel_hi:[1,0]
	v_pk_mul_f32 v[106:107], v[106:107], v[138:139] op_sel_hi:[1,0]
	v_pk_mul_f32 v[104:105], v[104:105], v[138:139] op_sel_hi:[1,0]
	v_pk_mul_f32 v[110:111], v[110:111], v[138:139] op_sel_hi:[1,0]
	v_pk_mul_f32 v[108:109], v[108:109], v[138:139] op_sel_hi:[1,0]
	v_pk_mul_f32 v[114:115], v[114:115], v[138:139] op_sel_hi:[1,0]
	v_pk_mul_f32 v[112:113], v[112:113], v[138:139] op_sel_hi:[1,0]
	v_pk_mul_f32 v[118:119], v[118:119], v[138:139] op_sel_hi:[1,0]
	v_pk_mul_f32 v[116:117], v[116:117], v[138:139] op_sel_hi:[1,0]
	v_pk_mul_f32 v[122:123], v[122:123], v[138:139] op_sel_hi:[1,0]
	v_pk_mul_f32 v[120:121], v[120:121], v[138:139] op_sel_hi:[1,0]
	v_pk_mul_f32 v[126:127], v[126:127], v[138:139] op_sel_hi:[1,0]
	v_pk_mul_f32 v[124:125], v[124:125], v[138:139] op_sel_hi:[1,0]
	v_pk_mul_f32 v[130:131], v[130:131], v[138:139] op_sel_hi:[1,0]
	v_pk_mul_f32 v[128:129], v[128:129], v[138:139] op_sel_hi:[1,0]
	v_max3_f32 v138, v139, v137, v136
	ds_bpermute_b32 v139, v146, v138
	v_mov_b32_e32 v223, v2
	v_mov_b32_e32 v224, v1
	s_waitcnt lgkmcnt(0)
	v_max_f32_e32 v139, v139, v139
	v_max_f32_e32 v138, v138, v139
	ds_bpermute_b32 v3, v3, v138
	s_waitcnt lgkmcnt(0)
	v_max3_f32 v3, v222, v138, v3
	v_sub_f32_e32 v139, v145, v3
	v_exp_f32_e32 v139, v139
	v_sub_f32_e32 v144, v144, v3
	v_exp_f32_e32 v144, v144
	v_sub_f32_e32 v141, v141, v3
	v_exp_f32_e32 v141, v141
	v_sub_f32_e32 v140, v140, v3
	v_exp_f32_e32 v146, v140
	v_add_f32_e32 v145, 0, v139
	v_sub_f32_e32 v143, v143, v3
	v_add_f32_e32 v145, v144, v145
	v_exp_f32_e32 v143, v143
	v_sub_f32_e32 v142, v142, v3
	v_add_f32_e32 v145, v141, v145
	v_exp_f32_e32 v142, v142
	v_sub_f32_e32 v137, v137, v3
	v_add_f32_e32 v140, v146, v145
	v_exp_f32_e32 v145, v137
	v_sub_f32_e32 v136, v136, v3
	v_sub_f32_e32 v138, v222, v3
	v_exp_f32_e32 v147, v136
	v_add_f32_e32 v140, v143, v140
	v_exp_f32_e32 v136, v138
	v_add_f32_e32 v140, v142, v140
	v_add_f32_e32 v137, v145, v140
	v_add_f32_e32 v140, v147, v137
	v_fmac_f32_e32 v140, v221, v136
	v_pk_mul_f32 v[70:71], v[70:71], v[136:137] op_sel_hi:[1,0]
	v_pk_mul_f32 v[68:69], v[68:69], v[136:137] op_sel_hi:[1,0]
	v_pk_mul_f32 v[74:75], v[74:75], v[136:137] op_sel_hi:[1,0]
	v_pk_mul_f32 v[72:73], v[72:73], v[136:137] op_sel_hi:[1,0]
	v_pk_mul_f32 v[78:79], v[78:79], v[136:137] op_sel_hi:[1,0]
	v_pk_mul_f32 v[76:77], v[76:77], v[136:137] op_sel_hi:[1,0]
	v_pk_mul_f32 v[82:83], v[82:83], v[136:137] op_sel_hi:[1,0]
	v_pk_mul_f32 v[80:81], v[80:81], v[136:137] op_sel_hi:[1,0]
	v_pk_mul_f32 v[86:87], v[86:87], v[136:137] op_sel_hi:[1,0]
	v_pk_mul_f32 v[84:85], v[84:85], v[136:137] op_sel_hi:[1,0]
	v_pk_mul_f32 v[90:91], v[90:91], v[136:137] op_sel_hi:[1,0]
	v_pk_mul_f32 v[88:89], v[88:89], v[136:137] op_sel_hi:[1,0]
	v_pk_mul_f32 v[94:95], v[94:95], v[136:137] op_sel_hi:[1,0]
	v_pk_mul_f32 v[92:93], v[92:93], v[136:137] op_sel_hi:[1,0]
	v_pk_mul_f32 v[102:103], v[102:103], v[136:137] op_sel_hi:[1,0]
	v_pk_mul_f32 v[100:101], v[100:101], v[136:137] op_sel_hi:[1,0]
	v_cvt_pk_bf16_f32 v136, v139, v144
	v_cvt_pk_bf16_f32 v137, v141, v146
	v_add_u32_e32 v141, v197, v198
	v_cvt_pk_bf16_f32 v138, v143, v142
	v_add_u32_e32 v142, 0x8800, v141
	v_cvt_pk_bf16_f32 v139, v145, v147
	ds_read2_b64 v[236:239], v142 offset0:8 offset1:12
	v_mov_b32_e32 v221, v140
	v_add_u32_e32 v252, 0x9800, v141
	ds_read2_b64 v[240:243], v252 offset0:72 offset1:76
	ds_read2_b64 v[244:247], v215 offset0:8 offset1:12
	v_add_u32_e32 v252, 0xb800, v141
	ds_read2_b64 v[248:251], v252 offset0:200 offset1:204
	s_waitcnt lgkmcnt(3)
; #define LAS __attribute__((address_space(3)))
; __device__ __forceinline__ void attn_unit(LAS unsigned char* lds, bf16_t* proj, const float* biasG, const float* sink, int s, int qb, int kh, int hp, bf16_t* dummy = nullptr) {
;     ...
;             if (st < wq || st > wq + 8) continue;
;             f32x4 sa[2][2];
; #pragma unroll
;             for (int kt = 0; kt < 2; ++kt) { sa[kt][0] = (f32x4){0.f, 0.f, 0.f, 0.f}; sa[kt][1] = (f32x4){0.f, 0.f, 0.f, 0.f}; }
; #pragma unroll
;             for (int ks = 0; ks < 4; ++ks)
; #pragma unroll
;                 for (int kt = 0; kt < 2; ++kt) {
;                     const bf16x8 kf = *(const LAS bf16x8*)(Ks + (si * 32 + kt * 16 + l16) * 272 + ks * 64 + kg * 16);
;                     sa[kt][0] = __builtin_amdgcn_mfma_f32_16x16x32_bf16(kf, qf[0][ks], sa[kt][0], 0, 0, 0);
;                     sa[kt][1] = __builtin_amdgcn_mfma_f32_16x16x32_bf16(kf, qf[1][ks], sa[kt][1], 0, 0, 0);
;                 }
;             bf16x8 pf[2];
; #pragma unroll
;             for (int qt = 0; qt < 2; ++qt) {
;                 const int qp = wq * 32 + qt * 16 + l16;
;                 float sv[8]; float mx = -1e30f;
; #pragma unroll
;                 for (int kt = 0; kt < 2; ++kt)
; #pragma unroll
;                     for (int r = 0; r < 4; ++r) {
;                         const int kp = (kbi - 1) * 128 + si * 32 + kt * 16 + kg * 4 + r;
;                         const int rel = kp - qp; const bool valid = (rel >= -128) && (rel <= 128);
;                         const int idx = min(max(rel + 128, 0), 256);
;                         const float v = valid ? (sa[kt][qt][r] * SC + bL[hl * 260 + idx]) : -1e30f;
;     ...
; #pragma unroll
;             for (int dt = 0; dt < 8; ++dt) {
;                 const LAS unsigned char* vr = Vt + (dt * 16 + l16) * 288 + (si * 32 + kg * 4) * 2;
;                 const u32x2 lo = *(const LAS u32x2*)(vr), hi = *(const LAS u32x2*)(vr + 32);
;                 u32x4 vw; vw.x = lo.x; vw.y = lo.y; vw.z = hi.x; vw.w = hi.y;
;                 const bf16x8 vf = __builtin_bit_cast(bf16x8, vw);
;                 o[dt][0] = __builtin_amdgcn_mfma_f32_16x16x32_bf16(vf, pf[0], o[dt][0], 0, 0, 0);
;                 o[dt][1] = __builtin_amdgcn_mfma_f32_16x16x32_bf16(vf, pf[1], o[dt][1], 0, 0, 0);
;             }
	v_mfma_f32_16x16x32_bf16 v[96:99], v[236:239], v[132:135], v[96:99]
	v_mov_b32_e32 v222, v3
	v_mfma_f32_16x16x32_bf16 v[68:71], v[236:239], v[136:139], v[68:71]
	v_add_u32_e32 v252, 0xd000, v141
	ds_read2_b64 v[236:239], v252 offset0:8 offset1:12
	s_waitcnt lgkmcnt(3)
	v_mfma_f32_16x16x32_bf16 v[104:107], v[240:243], v[132:135], v[104:107]
	v_mfma_f32_16x16x32_bf16 v[72:75], v[240:243], v[136:139], v[72:75]
	v_add_u32_e32 v252, 0xe000, v141
	ds_read2_b64 v[240:243], v252 offset0:72 offset1:76
	v_add_u32_e32 v141, 0xf000, v141
	s_waitcnt lgkmcnt(3)
	v_mfma_f32_16x16x32_bf16 v[108:111], v[244:247], v[132:135], v[108:111]
	v_mfma_f32_16x16x32_bf16 v[76:79], v[244:247], v[136:139], v[76:79]
	ds_read2_b64 v[244:247], v141 offset0:136 offset1:140
	s_waitcnt lgkmcnt(3)
	v_mfma_f32_16x16x32_bf16 v[112:115], v[248:251], v[132:135], v[112:115]
	v_mfma_f32_16x16x32_bf16 v[80:83], v[248:251], v[136:139], v[80:83]
	ds_read2_b64 v[248:251], v216 offset0:192 offset1:196
	s_waitcnt lgkmcnt(3)
	v_mfma_f32_16x16x32_bf16 v[116:119], v[236:239], v[132:135], v[116:119]
	v_mfma_f32_16x16x32_bf16 v[84:87], v[236:239], v[136:139], v[84:87]
	s_waitcnt lgkmcnt(2)
	v_mfma_f32_16x16x32_bf16 v[120:123], v[240:243], v[132:135], v[120:123]
	v_mfma_f32_16x16x32_bf16 v[88:91], v[240:243], v[136:139], v[88:91]
	s_waitcnt lgkmcnt(1)
	v_mfma_f32_16x16x32_bf16 v[124:127], v[244:247], v[132:135], v[124:127]
	v_mfma_f32_16x16x32_bf16 v[92:95], v[244:247], v[136:139], v[92:95]
	s_waitcnt lgkmcnt(0)
	v_mfma_f32_16x16x32_bf16 v[128:131], v[248:251], v[132:135], v[128:131]
	v_mfma_f32_16x16x32_bf16 v[100:103], v[248:251], v[136:139], v[100:103]
.LBB0_733:
	s_or_b64 exec, exec, s[74:75]
	s_add_i32 s4, s30, -1
	v_cmp_ge_u32_e32 vcc, s4, v192
	v_cmp_le_u32_e64 s[4:5], s4, v195
	s_and_b64 s[4:5], vcc, s[4:5]
	s_and_saveexec_b64 s[74:75], s[4:5]
	s_cbranch_execz .LBB0_767
	v_add_u32_e32 v251, 0x11700, v201
	v_add_u32_e32 v251, v251, v196
	ds_read_b32 v235, v251 offset:512
	ds_read_b32 v236, v251 offset:516
	ds_read_b32 v237, v251 offset:520
	ds_read_b32 v238, v251 offset:524
	ds_read_b32 v239, v251 offset:576
	ds_read_b32 v240, v251 offset:580
	ds_read_b32 v241, v251 offset:584
	ds_read_b32 v242, v251 offset:588
	ds_read_b32 v243, v251 offset:448
	ds_read_b32 v244, v251 offset:452
	ds_read_b32 v245, v251 offset:456
	ds_read_b32 v246, v251 offset:460
	ds_read_b32 v247, v251 offset:512
	ds_read_b32 v248, v251 offset:516
	ds_read_b32 v249, v251 offset:520
	ds_read_b32 v250, v251 offset:524
	ds_read_b128 v[132:135], v211
	ds_read_b128 v[226:229], v211 offset:64
	ds_read_b128 v[140:143], v213 offset:21760
	v_subrev_u32_e32 v1, 51, v199
	v_cmp_gt_u32_e32 vcc, s53, v1
	v_add3_u32 v2, v201, v196, s14
	s_waitcnt lgkmcnt(0)
	v_mfma_f32_16x16x32_bf16 v[136:139], v[132:135], v[4:7], 0
	v_mfma_f32_16x16x32_bf16 v[132:135], v[132:135], v[20:23], 0
	v_mfma_f32_16x16x32_bf16 v[136:139], v[226:229], v[8:11], v[136:139]
	v_mfma_f32_16x16x32_bf16 v[132:135], v[226:229], v[24:27], v[132:135]
	ds_read_b128 v[226:229], v213 offset:21824
	v_mfma_f32_16x16x32_bf16 v[144:147], v[140:143], v[4:7], 0
	v_mfma_f32_16x16x32_bf16 v[140:143], v[140:143], v[20:23], 0
	s_waitcnt lgkmcnt(0)
	v_mfma_f32_16x16x32_bf16 v[144:147], v[226:229], v[8:11], v[144:147]
	v_mfma_f32_16x16x32_bf16 v[140:143], v[226:229], v[24:27], v[140:143]
	ds_read_b128 v[226:229], v211 offset:128
	s_waitcnt lgkmcnt(0)
	v_mfma_f32_16x16x32_bf16 v[136:139], v[226:229], v[12:15], v[136:139]
	v_mfma_f32_16x16x32_bf16 v[132:135], v[226:229], v[28:31], v[132:135]
	ds_read_b128 v[226:229], v213 offset:21888
	s_waitcnt lgkmcnt(0)
	v_mfma_f32_16x16x32_bf16 v[230:233], v[226:229], v[12:15], v[144:147]
	v_mfma_f32_16x16x32_bf16 v[226:229], v[226:229], v[28:31], v[140:143]
	s_nop 2
	ds_read_b128 v[140:143], v211 offset:192
	s_waitcnt lgkmcnt(0)
	v_mfma_f32_16x16x32_bf16 v[144:147], v[140:143], v[16:19], v[136:139]
	s_nop 2
	ds_read_b128 v[136:139], v213 offset:21952
	v_mfma_f32_16x16x32_bf16 v[140:143], v[140:143], v[32:35], v[132:135]
	s_waitcnt lgkmcnt(0)
	v_mfma_f32_16x16x32_bf16 v[132:135], v[136:139], v[16:19], v[230:233]
	v_mfma_f32_16x16x32_bf16 v[136:139], v[136:139], v[32:35], v[226:229]
	s_nop 2
	v_mov_b32_e32 v228, 0xf149f2ca
	v_mov_b32_e32 v229, 0xf149f2ca
	s_waitcnt lgkmcnt(0)
	v_fmac_f32_e32 v235, 0x3e0293ee, v144
	v_cndmask_b32_e32 v229, v229, v235, vcc
	v_subrev_u32_e32 v1, 50, v199
	v_cmp_gt_u32_e64 s[4:5], s53, v1
	v_add3_u32 v225, v201, v196, s54
	v_fmac_f32_e32 v236, 0x3e0293ee, v145
	v_cndmask_b32_e64 v228, v228, v236, s[4:5]
	v_subrev_u32_e32 v1, 49, v199
	v_cmp_gt_u32_e64 s[6:7], s53, v1
	v_mov_b32_e32 v145, 0xf149f2ca
	v_add3_u32 v226, v201, v196, s58
	v_mov_b32_e32 v230, 0xf149f2ca
	v_fmac_f32_e32 v237, 0x3e0293ee, v146
	v_cndmask_b32_e64 v230, v230, v237, s[6:7]
	v_subrev_u32_e32 v1, 48, v199
	v_cmp_gt_u32_e64 s[8:9], s53, v1
	v_add3_u32 v227, v201, v196, s97
	v_fmac_f32_e32 v238, 0x3e0293ee, v147
	v_cndmask_b32_e64 v145, v145, v238, s[8:9]
	v_subrev_u32_e32 v1, 35, v199
	v_cmp_gt_u32_e64 s[10:11], s53, v1
	v_mov_b32_e32 v232, 0xf149f2ca
	v_mov_b32_e32 v231, 0xf149f2ca
	v_fmac_f32_e32 v239, 0x3e0293ee, v132
	v_cndmask_b32_e64 v231, v231, v239, s[10:11]
	v_subrev_u32_e32 v1, 34, v199
	v_cmp_gt_u32_e64 s[10:11], s53, v1
	v_fmac_f32_e32 v240, 0x3e0293ee, v133
	s_nop 0
	v_cndmask_b32_e64 v232, v232, v240, s[10:11]
	v_subrev_u32_e32 v1, 33, v199
	v_cmp_gt_u32_e64 s[10:11], s53, v1
	v_mov_b32_e32 v132, 0xf149f2ca
	v_mov_b32_e32 v133, 0xf149f2ca
	v_fmac_f32_e32 v241, 0x3e0293ee, v134
	v_cndmask_b32_e64 v133, v133, v241, s[10:11]
	v_subrev_u32_e32 v1, 32, v199
	v_cmp_gt_u32_e64 s[10:11], s53, v1
	v_fmac_f32_e32 v242, 0x3e0293ee, v135
	s_nop 0
	v_cndmask_b32_e64 v132, v132, v242, s[10:11]
	v_mov_b32_e32 v144, 0xf149f2ca
	v_and_b32_e32 v134, 64, v182
	v_max3_f32 v1, v229, v144, v228
	v_xor_b32_e32 v3, 16, v182
	v_add_u32_e32 v134, 64, v134
	v_max3_f32 v1, v1, v230, v145
	v_cmp_lt_i32_e64 s[10:11], v3, v134
	v_max3_f32 v1, v1, v231, v232
	v_max3_f32 v1, v1, v133, v132
	v_cndmask_b32_e64 v3, v182, v3, s[10:11]
	v_lshlrev_b32_e32 v146, 2, v3
	ds_bpermute_b32 v135, v146, v1
	v_xor_b32_e32 v3, 32, v182
	v_cmp_lt_i32_e64 s[10:11], v3, v134
	s_waitcnt lgkmcnt(0)
; __device__ __forceinline__ unsigned cvt_pk_bf16(float lo, float hi) { unsigned r; asm volatile("v_cvt_pk_bf16_f32 %0, %1, %2" : "=v"(r) : "v"(lo), "v"(hi)); return r; }
; __device__ __forceinline__ void attn_unit(LAS unsigned char* lds, bf16_t* proj, const float* biasG, const float* sink, int s, int qb, int kh, int hp, bf16_t* dummy = nullptr) {
;     ...
;                         const float v = valid ? (sa[kt][qt][r] * SC + bL[hl * 260 + idx]) : -1e30f;
;                         sv[kt * 4 + r] = v; mx = fmaxf(mx, v);
;                     }
;                 mx = fmaxf(mx, __shfl_xor(mx, 16)); mx = fmaxf(mx, __shfl_xor(mx, 32));
;                 const float mnew = fmaxf(m2[qt], mx), alpha = __builtin_amdgcn_exp2f(m2[qt] - mnew); m2[qt] = mnew;
;                 float ps = 0.f; float pv[8];
; #pragma unroll
;                 for (int i = 0; i < 8; ++i) { pv[i] = __builtin_amdgcn_exp2f(sv[i] - mnew); ps += pv[i]; }
;                 lsum[qt] = lsum[qt] * alpha + ps;
; #pragma unroll
;                 for (int dt = 0; dt < 8; ++dt) o[dt][qt] = o[dt][qt] * alpha;
;                 u32x4 pw; pw.x = cvt_pk_bf16(pv[0], pv[1]); pw.y = cvt_pk_bf16(pv[2], pv[3]); pw.z = cvt_pk_bf16(pv[4], pv[5]); pw.w = cvt_pk_bf16(pv[6], pv[7]);
;                 pf[qt] = __builtin_bit_cast(bf16x8, pw);
	v_max_f32_e32 v134, v135, v135
	v_cndmask_b32_e64 v3, v182, v3, s[10:11]
	v_lshlrev_b32_e32 v3, 2, v3
	v_max_f32_e32 v1, v1, v134
	ds_bpermute_b32 v134, v3, v1
	s_waitcnt lgkmcnt(0)
	v_max3_f32 v1, v224, v1, v134
	v_sub_f32_e32 v134, v229, v1
	v_exp_f32_e32 v147, v134
	v_sub_f32_e32 v134, v228, v1
	v_exp_f32_e32 v228, v134
	v_sub_f32_e32 v134, v230, v1
	v_exp_f32_e32 v229, v134
	v_sub_f32_e32 v134, v145, v1
	v_exp_f32_e32 v230, v134
	v_sub_f32_e32 v134, v231, v1
	v_exp_f32_e32 v231, v134
	v_sub_f32_e32 v134, v232, v1
	v_sub_f32_e32 v133, v133, v1
	v_sub_f32_e32 v132, v132, v1
	v_exp_f32_e32 v232, v134
	v_exp_f32_e32 v233, v133
	v_exp_f32_e32 v234, v132
	v_add_u32_e32 v145, 0xffffffbd, v199
	v_cmp_gt_u32_e64 s[10:11], s53, v145
	v_mov_b32_e32 v145, 0xf149f2ca
	v_cvt_pk_bf16_f32 v132, v147, v228
	v_cvt_pk_bf16_f32 v133, v229, v230
	v_cvt_pk_bf16_f32 v134, v231, v232
	v_cvt_pk_bf16_f32 v135, v233, v234
	v_fmac_f32_e32 v243, 0x3e0293ee, v140
	v_cndmask_b32_e64 v145, v145, v243, s[10:11]
	v_add_u32_e32 v140, 0xffffffbe, v199
	v_cmp_gt_u32_e64 s[10:11], s53, v140
	v_fmac_f32_e32 v244, 0x3e0293ee, v141
	s_nop 0
	v_cndmask_b32_e64 v144, v144, v244, s[10:11]
	v_add_u32_e32 v140, 0xffffffbf, v199
	v_cmp_gt_u32_e64 s[10:11], s53, v140
	v_mov_b32_e32 v140, 0xf149f2ca
	v_mov_b32_e32 v141, 0xf149f2ca
	v_fmac_f32_e32 v245, 0x3e0293ee, v142
	v_cndmask_b32_e64 v141, v141, v245, s[10:11]
	v_subrev_u32_e32 v142, 64, v199
	v_cmp_gt_u32_e64 s[10:11], s53, v142
	v_fmac_f32_e32 v246, 0x3e0293ee, v143
	s_nop 0
	v_cndmask_b32_e64 v140, v140, v246, s[10:11]
	v_mov_b32_e32 v142, 0xf149f2ca
	v_mov_b32_e32 v143, 0xf149f2ca
	v_fmac_f32_e32 v247, 0x3e0293ee, v136
	v_cndmask_b32_e32 v143, v143, v247, vcc
	v_fmac_f32_e32 v248, 0x3e0293ee, v137
	v_cndmask_b32_e64 v142, v142, v248, s[4:5]
	v_mov_b32_e32 v136, 0xf149f2ca
	v_mov_b32_e32 v137, 0xf149f2ca
	v_fmac_f32_e32 v249, 0x3e0293ee, v138
	v_cndmask_b32_e64 v137, v137, v249, s[6:7]
	v_fmac_f32_e32 v250, 0x3e0293ee, v139
	v_cndmask_b32_e64 v136, v136, v250, s[8:9]
	v_max3_f32 v2, v145, s89, v144
	v_max3_f32 v2, v2, v141, v140
	v_max3_f32 v139, v2, v143, v142
	v_add_f32_e32 v2, 0, v147
	v_add_f32_e32 v2, v228, v2
	v_add_f32_e32 v2, v229, v2
	v_sub_f32_e32 v138, v224, v1
	v_add_f32_e32 v2, v230, v2
	v_add_f32_e32 v2, v231, v2
	v_exp_f32_e32 v138, v138
	v_add_f32_e32 v2, v232, v2
	v_add_f32_e32 v2, v233, v2
	v_add_f32_e32 v2, v234, v2
	v_fmac_f32_e32 v2, v223, v138
	v_pk_mul_f32 v[98:99], v[98:99], v[138:139] op_sel_hi:[1,0]
	v_pk_mul_f32 v[96:97], v[96:97], v[138:139] op_sel_hi:[1,0]
	v_pk_mul_f32 v[106:107], v[106:107], v[138:139] op_sel_hi:[1,0]
	v_pk_mul_f32 v[104:105], v[104:105], v[138:139] op_sel_hi:[1,0]
	v_pk_mul_f32 v[110:111], v[110:111], v[138:139] op_sel_hi:[1,0]
	v_pk_mul_f32 v[108:109], v[108:109], v[138:139] op_sel_hi:[1,0]
	v_pk_mul_f32 v[114:115], v[114:115], v[138:139] op_sel_hi:[1,0]
	v_pk_mul_f32 v[112:113], v[112:113], v[138:139] op_sel_hi:[1,0]
	v_pk_mul_f32 v[118:119], v[118:119], v[138:139] op_sel_hi:[1,0]
	v_pk_mul_f32 v[116:117], v[116:117], v[138:139] op_sel_hi:[1,0]
	v_pk_mul_f32 v[122:123], v[122:123], v[138:139] op_sel_hi:[1,0]
	v_pk_mul_f32 v[120:121], v[120:121], v[138:139] op_sel_hi:[1,0]
	v_pk_mul_f32 v[126:127], v[126:127], v[138:139] op_sel_hi:[1,0]
	v_pk_mul_f32 v[124:125], v[124:125], v[138:139] op_sel_hi:[1,0]
	v_pk_mul_f32 v[130:131], v[130:131], v[138:139] op_sel_hi:[1,0]
	v_pk_mul_f32 v[128:129], v[128:129], v[138:139] op_sel_hi:[1,0]
	v_max3_f32 v138, v139, v137, v136
	ds_bpermute_b32 v139, v146, v138
	v_mov_b32_e32 v223, v2
	v_mov_b32_e32 v224, v1
	s_waitcnt lgkmcnt(0)
	v_max_f32_e32 v139, v139, v139
	v_max_f32_e32 v138, v138, v139
	ds_bpermute_b32 v3, v3, v138
	s_waitcnt lgkmcnt(0)
	v_max3_f32 v3, v222, v138, v3
	v_sub_f32_e32 v139, v145, v3
	v_exp_f32_e32 v139, v139
	v_sub_f32_e32 v144, v144, v3
	v_exp_f32_e32 v144, v144
	v_sub_f32_e32 v141, v141, v3
	v_exp_f32_e32 v141, v141
	v_sub_f32_e32 v140, v140, v3
	v_exp_f32_e32 v146, v140
	v_add_f32_e32 v145, 0, v139
	v_sub_f32_e32 v143, v143, v3
	v_add_f32_e32 v145, v144, v145
	v_exp_f32_e32 v143, v143
	v_sub_f32_e32 v142, v142, v3
	v_add_f32_e32 v145, v141, v145
	v_exp_f32_e32 v142, v142
	v_sub_f32_e32 v137, v137, v3
	v_add_f32_e32 v140, v146, v145
	v_exp_f32_e32 v145, v137
	v_sub_f32_e32 v136, v136, v3
	v_sub_f32_e32 v138, v222, v3
	v_exp_f32_e32 v147, v136
	v_add_f32_e32 v140, v143, v140
	v_exp_f32_e32 v136, v138
	v_add_f32_e32 v140, v142, v140
	v_add_f32_e32 v137, v145, v140
	v_add_f32_e32 v140, v147, v137
	v_fmac_f32_e32 v140, v221, v136
	v_pk_mul_f32 v[70:71], v[70:71], v[136:137] op_sel_hi:[1,0]
	v_pk_mul_f32 v[68:69], v[68:69], v[136:137] op_sel_hi:[1,0]
	v_pk_mul_f32 v[74:75], v[74:75], v[136:137] op_sel_hi:[1,0]
	v_pk_mul_f32 v[72:73], v[72:73], v[136:137] op_sel_hi:[1,0]
	v_pk_mul_f32 v[78:79], v[78:79], v[136:137] op_sel_hi:[1,0]
	v_pk_mul_f32 v[76:77], v[76:77], v[136:137] op_sel_hi:[1,0]
	v_pk_mul_f32 v[82:83], v[82:83], v[136:137] op_sel_hi:[1,0]
	v_pk_mul_f32 v[80:81], v[80:81], v[136:137] op_sel_hi:[1,0]
	v_pk_mul_f32 v[86:87], v[86:87], v[136:137] op_sel_hi:[1,0]
	v_pk_mul_f32 v[84:85], v[84:85], v[136:137] op_sel_hi:[1,0]
	v_pk_mul_f32 v[90:91], v[90:91], v[136:137] op_sel_hi:[1,0]
	v_pk_mul_f32 v[88:89], v[88:89], v[136:137] op_sel_hi:[1,0]
	v_pk_mul_f32 v[94:95], v[94:95], v[136:137] op_sel_hi:[1,0]
	v_pk_mul_f32 v[92:93], v[92:93], v[136:137] op_sel_hi:[1,0]
	v_pk_mul_f32 v[102:103], v[102:103], v[136:137] op_sel_hi:[1,0]
	v_pk_mul_f32 v[100:101], v[100:101], v[136:137] op_sel_hi:[1,0]
	v_cvt_pk_bf16_f32 v136, v139, v144
	v_cvt_pk_bf16_f32 v137, v141, v146
	v_add_u32_e32 v141, v197, v198
	v_cvt_pk_bf16_f32 v138, v143, v142
	v_add_u32_e32 v142, 0x8800, v141
	v_cvt_pk_bf16_f32 v139, v145, v147
	ds_read2_b64 v[236:239], v142 offset0:16 offset1:20
	v_mov_b32_e32 v221, v140
	v_add_u32_e32 v252, 0x9800, v141
	ds_read2_b64 v[240:243], v252 offset0:80 offset1:84
	v_add_u32_e32 v252, 0xa800, v141
	ds_read2_b64 v[244:247], v252 offset0:144 offset1:148
	v_add_u32_e32 v252, 0xb800, v141
	ds_read2_b64 v[248:251], v252 offset0:208 offset1:212
	s_waitcnt lgkmcnt(3)
; #define LAS __attribute__((address_space(3)))
; __device__ __forceinline__ void attn_unit(LAS unsigned char* lds, bf16_t* proj, const float* biasG, const float* sink, int s, int qb, int kh, int hp, bf16_t* dummy = nullptr) {
;     ...
; #pragma unroll
;             for (int dt = 0; dt < 8; ++dt) {
;                 const LAS unsigned char* vr = Vt + (dt * 16 + l16) * 288 + (si * 32 + kg * 4) * 2;
;                 const u32x2 lo = *(const LAS u32x2*)(vr), hi = *(const LAS u32x2*)(vr + 32);
;                 u32x4 vw; vw.x = lo.x; vw.y = lo.y; vw.z = hi.x; vw.w = hi.y;
;                 const bf16x8 vf = __builtin_bit_cast(bf16x8, vw);
;                 o[dt][0] = __builtin_amdgcn_mfma_f32_16x16x32_bf16(vf, pf[0], o[dt][0], 0, 0, 0);
;                 o[dt][1] = __builtin_amdgcn_mfma_f32_16x16x32_bf16(vf, pf[1], o[dt][1], 0, 0, 0);
;             }
	v_mfma_f32_16x16x32_bf16 v[96:99], v[236:239], v[132:135], v[96:99]
	v_mov_b32_e32 v222, v3
	v_mfma_f32_16x16x32_bf16 v[68:71], v[236:239], v[136:139], v[68:71]
	ds_read2_b64 v[236:239], v217 offset0:16 offset1:20
	s_waitcnt lgkmcnt(3)
	v_mfma_f32_16x16x32_bf16 v[104:107], v[240:243], v[132:135], v[104:107]
	v_mfma_f32_16x16x32_bf16 v[72:75], v[240:243], v[136:139], v[72:75]
	v_add_u32_e32 v252, 0xe000, v141
	ds_read2_b64 v[240:243], v252 offset0:80 offset1:84
	v_add_u32_e32 v141, 0xf000, v141
	s_waitcnt lgkmcnt(3)
	v_mfma_f32_16x16x32_bf16 v[108:111], v[244:247], v[132:135], v[108:111]
	v_mfma_f32_16x16x32_bf16 v[76:79], v[244:247], v[136:139], v[76:79]
	ds_read2_b64 v[244:247], v141 offset0:144 offset1:148
	s_waitcnt lgkmcnt(3)
	v_mfma_f32_16x16x32_bf16 v[112:115], v[248:251], v[132:135], v[112:115]
	v_mfma_f32_16x16x32_bf16 v[80:83], v[248:251], v[136:139], v[80:83]
	ds_read2_b64 v[248:251], v218 offset0:192 offset1:196
	s_waitcnt lgkmcnt(3)
	v_mfma_f32_16x16x32_bf16 v[116:119], v[236:239], v[132:135], v[116:119]
	v_mfma_f32_16x16x32_bf16 v[84:87], v[236:239], v[136:139], v[84:87]
	s_waitcnt lgkmcnt(2)
	v_mfma_f32_16x16x32_bf16 v[120:123], v[240:243], v[132:135], v[120:123]
	v_mfma_f32_16x16x32_bf16 v[88:91], v[240:243], v[136:139], v[88:91]
	s_waitcnt lgkmcnt(1)
	v_mfma_f32_16x16x32_bf16 v[124:127], v[244:247], v[132:135], v[124:127]
	v_mfma_f32_16x16x32_bf16 v[92:95], v[244:247], v[136:139], v[92:95]
	s_waitcnt lgkmcnt(0)
	v_mfma_f32_16x16x32_bf16 v[128:131], v[248:251], v[132:135], v[128:131]
	v_mfma_f32_16x16x32_bf16 v[100:103], v[248:251], v[136:139], v[100:103]
; #define LAS __attribute__((address_space(3)))
; __device__ __forceinline__ void attn_unit(LAS unsigned char* lds, bf16_t* proj, const float* biasG, const float* sink, int s, int qb, int kh, int hp, bf16_t* dummy = nullptr) {
;     ...
;         for (int si = 0; si < 4; ++si) {
;             const int st = kbi * 4 + si;
;             if (st < wq || st > wq + 8) continue;
;             f32x4 sa[2][2];
; #pragma unroll
;             for (int kt = 0; kt < 2; ++kt) { sa[kt][0] = (f32x4){0.f, 0.f, 0.f, 0.f}; sa[kt][1] = (f32x4){0.f, 0.f, 0.f, 0.f}; }
; #pragma unroll
;             for (int ks = 0; ks < 4; ++ks)
; #pragma unroll
;                 for (int kt = 0; kt < 2; ++kt) {
;                     const bf16x8 kf = *(const LAS bf16x8*)(Ks + (si * 32 + kt * 16 + l16) * 272 + ks * 64 + kg * 16);
;                     sa[kt][0] = __builtin_amdgcn_mfma_f32_16x16x32_bf16(kf, qf[0][ks], sa[kt][0], 0, 0, 0);
;                     sa[kt][1] = __builtin_amdgcn_mfma_f32_16x16x32_bf16(kf, qf[1][ks], sa[kt][1], 0, 0, 0);
;                 }
;             bf16x8 pf[2];
; #pragma unroll
;             for (int qt = 0; qt < 2; ++qt) {
;                 const int qp = wq * 32 + qt * 16 + l16;
;                 float sv[8]; float mx = -1e30f;
; #pragma unroll
;                 for (int kt = 0; kt < 2; ++kt)
; #pragma unroll
;                     for (int r = 0; r < 4; ++r) {
;                         const int kp = (kbi - 1) * 128 + si * 32 + kt * 16 + kg * 4 + r;
;                         const int rel = kp - qp; const bool valid = (rel >= -128) && (rel <= 128);
;                         const int idx = min(max(rel + 128, 0), 256);
;                         const float v = valid ? (sa[kt][qt][r] * SC + bL[hl * 260 + idx]) : -1e30f;
;                         sv[kt * 4 + r] = v; mx = fmaxf(mx, v);
;                     }
;                 mx = fmaxf(mx, __shfl_xor(mx, 16)); mx = fmaxf(mx, __shfl_xor(mx, 32));
;                 const float mnew = fmaxf(m2[qt], mx), alpha = __builtin_amdgcn_exp2f(m2[qt] - mnew); m2[qt] = mnew;
;                 float ps = 0.f; float pv[8];
; #pragma unroll
;                 for (int i = 0; i < 8; ++i) { pv[i] = __builtin_amdgcn_exp2f(sv[i] - mnew); ps += pv[i]; }
;                 lsum[qt] = lsum[qt] * alpha + ps;
; #pragma unroll
;                 for (int dt = 0; dt < 8; ++dt) o[dt][qt] = o[dt][qt] * alpha;
.LBB0_767:
	s_or_b64 exec, exec, s[74:75]
	v_cmp_le_u32_e32 vcc, s30, v195
	s_and_saveexec_b64 s[74:75], vcc
	s_cbranch_execz .LBB0_662
	v_add_u32_e32 v251, 0x11700, v201
	v_add_u32_e32 v251, v251, v196
	ds_read_b32 v235, v251 offset:640
	ds_read_b32 v236, v251 offset:644
	ds_read_b32 v237, v251 offset:648
	ds_read_b32 v238, v251 offset:652
	ds_read_b32 v239, v251 offset:704
	ds_read_b32 v240, v251 offset:708
	ds_read_b32 v241, v251 offset:712
	ds_read_b32 v242, v251 offset:716
	ds_read_b32 v243, v251 offset:576
	ds_read_b32 v244, v251 offset:580
	ds_read_b32 v245, v251 offset:584
	ds_read_b32 v246, v251 offset:588
	ds_read_b32 v247, v251 offset:640
	ds_read_b32 v248, v251 offset:644
	ds_read_b32 v249, v251 offset:648
	ds_read_b32 v250, v251 offset:652
	ds_read_b128 v[132:135], v212
	ds_read_b128 v[226:229], v212 offset:64
	ds_read_b128 v[140:143], v213 offset:30464
	v_subrev_u32_e32 v1, 19, v199
	v_cmp_gt_u32_e32 vcc, s53, v1
	v_add3_u32 v2, v201, v196, s49
	s_waitcnt lgkmcnt(0)
	v_mfma_f32_16x16x32_bf16 v[136:139], v[132:135], v[4:7], 0
	v_mfma_f32_16x16x32_bf16 v[132:135], v[132:135], v[20:23], 0
	v_mfma_f32_16x16x32_bf16 v[136:139], v[226:229], v[8:11], v[136:139]
	v_mfma_f32_16x16x32_bf16 v[132:135], v[226:229], v[24:27], v[132:135]
	ds_read_b128 v[226:229], v213 offset:30528
	v_mfma_f32_16x16x32_bf16 v[144:147], v[140:143], v[4:7], 0
	v_mfma_f32_16x16x32_bf16 v[140:143], v[140:143], v[20:23], 0
	s_waitcnt lgkmcnt(0)
	v_mfma_f32_16x16x32_bf16 v[144:147], v[226:229], v[8:11], v[144:147]
	v_mfma_f32_16x16x32_bf16 v[140:143], v[226:229], v[24:27], v[140:143]
	ds_read_b128 v[226:229], v212 offset:128
	s_waitcnt lgkmcnt(0)
	v_mfma_f32_16x16x32_bf16 v[136:139], v[226:229], v[12:15], v[136:139]
	v_mfma_f32_16x16x32_bf16 v[132:135], v[226:229], v[28:31], v[132:135]
	ds_read_b128 v[226:229], v213 offset:30592
	s_waitcnt lgkmcnt(0)
	v_mfma_f32_16x16x32_bf16 v[230:233], v[226:229], v[12:15], v[144:147]
	v_mfma_f32_16x16x32_bf16 v[226:229], v[226:229], v[28:31], v[140:143]
	s_nop 2
	ds_read_b128 v[140:143], v212 offset:192
	s_waitcnt lgkmcnt(0)
	v_mfma_f32_16x16x32_bf16 v[144:147], v[140:143], v[16:19], v[136:139]
	s_nop 2
	ds_read_b128 v[136:139], v213 offset:30656
	v_mfma_f32_16x16x32_bf16 v[140:143], v[140:143], v[32:35], v[132:135]
	s_waitcnt lgkmcnt(0)
	v_mfma_f32_16x16x32_bf16 v[132:135], v[136:139], v[16:19], v[230:233]
	v_mfma_f32_16x16x32_bf16 v[136:139], v[136:139], v[32:35], v[226:229]
	s_nop 2
	v_mov_b32_e32 v228, 0xf149f2ca
	v_mov_b32_e32 v229, 0xf149f2ca
	s_waitcnt lgkmcnt(0)
	v_fmac_f32_e32 v235, 0x3e0293ee, v144
	v_cndmask_b32_e32 v229, v229, v235, vcc
	v_subrev_u32_e32 v1, 18, v199
	v_cmp_gt_u32_e64 s[4:5], s53, v1
	v_add3_u32 v225, v201, v196, s0
	v_fmac_f32_e32 v236, 0x3e0293ee, v145
	v_cndmask_b32_e64 v228, v228, v236, s[4:5]
	v_subrev_u32_e32 v1, 17, v199
	v_cmp_gt_u32_e64 s[6:7], s53, v1
	v_mov_b32_e32 v145, 0xf149f2ca
	v_add3_u32 v226, v201, v196, s1
	v_mov_b32_e32 v230, 0xf149f2ca
	v_fmac_f32_e32 v237, 0x3e0293ee, v146
	v_cndmask_b32_e64 v230, v230, v237, s[6:7]
	v_add_u32_e32 v1, -16, v199
	v_cmp_gt_u32_e64 s[8:9], s53, v1
	v_add3_u32 v227, v201, v196, s15
	v_fmac_f32_e32 v238, 0x3e0293ee, v147
	v_cndmask_b32_e64 v145, v145, v238, s[8:9]
	v_add_u32_e32 v1, -3, v199
	v_cmp_gt_u32_e64 s[10:11], s53, v1
	v_mov_b32_e32 v232, 0xf149f2ca
	v_mov_b32_e32 v231, 0xf149f2ca
	v_fmac_f32_e32 v239, 0x3e0293ee, v132
	v_cndmask_b32_e64 v231, v231, v239, s[10:11]
	v_add_u32_e32 v1, -2, v199
	v_cmp_gt_u32_e64 s[10:11], s53, v1
	v_fmac_f32_e32 v240, 0x3e0293ee, v133
	s_nop 0
	v_cndmask_b32_e64 v232, v232, v240, s[10:11]
	v_add_u32_e32 v1, -1, v199
	v_cmp_gt_u32_e64 s[10:11], s53, v1
	v_mov_b32_e32 v132, 0xf149f2ca
	v_mov_b32_e32 v133, 0xf149f2ca
	v_fmac_f32_e32 v241, 0x3e0293ee, v134
	v_cndmask_b32_e64 v133, v133, v241, s[10:11]
	v_cmp_gt_u32_e64 s[10:11], s53, v199
	v_fmac_f32_e32 v242, 0x3e0293ee, v135
	s_nop 0
	v_cndmask_b32_e64 v132, v132, v242, s[10:11]
	v_mov_b32_e32 v144, 0xf149f2ca
	v_and_b32_e32 v134, 64, v182
	v_max3_f32 v1, v229, v144, v228
	v_xor_b32_e32 v3, 16, v182
	v_add_u32_e32 v134, 64, v134
	v_max3_f32 v1, v1, v230, v145
	v_cmp_lt_i32_e64 s[10:11], v3, v134
	v_max3_f32 v1, v1, v231, v232
	v_max3_f32 v1, v1, v133, v132
	v_cndmask_b32_e64 v3, v182, v3, s[10:11]
	v_lshlrev_b32_e32 v146, 2, v3
	ds_bpermute_b32 v135, v146, v1
	v_xor_b32_e32 v3, 32, v182
	v_cmp_lt_i32_e64 s[10:11], v3, v134
	s_waitcnt lgkmcnt(0)
	v_max_f32_e32 v134, v135, v135
	v_cndmask_b32_e64 v3, v182, v3, s[10:11]
	v_lshlrev_b32_e32 v3, 2, v3
	v_max_f32_e32 v1, v1, v134
	ds_bpermute_b32 v134, v3, v1
	s_waitcnt lgkmcnt(0)
	v_max3_f32 v1, v224, v1, v134
	v_sub_f32_e32 v134, v229, v1
	v_exp_f32_e32 v147, v134
	v_sub_f32_e32 v134, v228, v1
	v_exp_f32_e32 v228, v134
	v_sub_f32_e32 v134, v230, v1
	v_exp_f32_e32 v229, v134
	v_sub_f32_e32 v134, v145, v1
	v_exp_f32_e32 v230, v134
	v_sub_f32_e32 v134, v231, v1
	v_exp_f32_e32 v231, v134
	v_sub_f32_e32 v134, v232, v1
	v_sub_f32_e32 v133, v133, v1
	v_sub_f32_e32 v132, v132, v1
	v_exp_f32_e32 v232, v134
	v_exp_f32_e32 v233, v133
	v_exp_f32_e32 v234, v132
	v_subrev_u32_e32 v145, 35, v199
	v_cmp_gt_u32_e64 s[10:11], s53, v145
	v_mov_b32_e32 v145, 0xf149f2ca
	v_cvt_pk_bf16_f32 v132, v147, v228
	v_cvt_pk_bf16_f32 v133, v229, v230
	v_cvt_pk_bf16_f32 v134, v231, v232
	v_cvt_pk_bf16_f32 v135, v233, v234
	v_fmac_f32_e32 v243, 0x3e0293ee, v140
	v_cndmask_b32_e64 v145, v145, v243, s[10:11]
	v_subrev_u32_e32 v140, 34, v199
	v_cmp_gt_u32_e64 s[10:11], s53, v140
	v_fmac_f32_e32 v244, 0x3e0293ee, v141
	s_nop 0
	v_cndmask_b32_e64 v144, v144, v244, s[10:11]
	v_subrev_u32_e32 v140, 33, v199
	v_cmp_gt_u32_e64 s[10:11], s53, v140
	v_mov_b32_e32 v140, 0xf149f2ca
	v_mov_b32_e32 v141, 0xf149f2ca
	v_fmac_f32_e32 v245, 0x3e0293ee, v142
	v_cndmask_b32_e64 v141, v141, v245, s[10:11]
	v_subrev_u32_e32 v142, 32, v199
	v_cmp_gt_u32_e64 s[10:11], s53, v142
	v_fmac_f32_e32 v246, 0x3e0293ee, v143
	s_nop 0
	v_cndmask_b32_e64 v140, v140, v246, s[10:11]
	v_mov_b32_e32 v142, 0xf149f2ca
	v_mov_b32_e32 v143, 0xf149f2ca
	v_fmac_f32_e32 v247, 0x3e0293ee, v136
	v_cndmask_b32_e32 v143, v143, v247, vcc
	v_fmac_f32_e32 v248, 0x3e0293ee, v137
	v_cndmask_b32_e64 v142, v142, v248, s[4:5]
	v_mov_b32_e32 v136, 0xf149f2ca
	v_mov_b32_e32 v137, 0xf149f2ca
	v_fmac_f32_e32 v249, 0x3e0293ee, v138
	v_cndmask_b32_e64 v137, v137, v249, s[6:7]
	s_and_saveexec_b64 s[4:5], s[8:9]
	s_cbranch_execz .LBB0_661
	v_mov_b32_e32 v136, v250
	v_fmac_f32_e32 v136, 0x3e0293ee, v139
	s_branch .LBB0_661
